# K-loop MFMA blocks: priority yield (s_setprio 0/2) after every 8 MFMAs instead of every 16, on v58
# baseline (speedup 1.0000x reference)
; #define PG8_STAGE(bufoff, gbase, voff) do { _Pragma("unroll") for (int _i = 0; _i < 2; ++_i) \
;         __builtin_amdgcn_global_load_lds((const unsigned*)((const char*)(gbase) + (voff)[_i]), (PG8_LAS unsigned*)(lds + (bufoff) + ldsw + _i * 8192), 16, 0, 0); } while (0)
; #define PG8_LDA(dst, b, h) do { _Pragma("unroll") for (int m = 0; m < 4; ++m) _Pragma("unroll") for (int k = 0; k < 2; ++k) dst[m][k] = *(const PG8_LAS bf16x8*)(lds + PG8_SA(b, h) + aoff + m * 2048 + k * 1024); } while (0)
; #define PG8_LDB(dst, b, h) do { _Pragma("unroll") for (int n = 0; n < 2; ++n) _Pragma("unroll") for (int k = 0; k < 2; ++k) dst[n][k] = *(const PG8_LAS bf16x8*)(lds + PG8_SB(b, h) + boff + n * 2048 + k * 1024); } while (0)
; #define PG8_MMA(ai, bj, At, Bt) do { __builtin_amdgcn_s_setprio(1); _Pragma("unroll") for (int m = 0; m < 4; ++m) _Pragma("unroll") for (int n = 0; n < 2; ++n) _Pragma("unroll") for (int k = 0; k < 2; ++k) \
;         acc[ai][bj][m][n] = __builtin_amdgcn_mfma_f32_16x16x32_bf16(Bt[n][k], At[m][k], acc[ai][bj][m][n], 0, 0, 0); __builtin_amdgcn_s_setprio(0); } while (0)
; #define PG8_WAIT_V(n) asm volatile("s_waitcnt vmcnt(" #n ")" ::: "memory")
; #define PG8_BAR __builtin_amdgcn_s_barrier()
; template <class Epi, class Sched, bool ALIGN_EPI = false, bool SP2 = false>
; __device__ __forceinline__ void gemm_phase(PG8_LAS unsigned char* lds, const Gemm g, const Sched& S, const Epi& E, const int wv  ) {
;     ...
;         for (int t = 0; t < nt; t += 2) {
;             const bool last = (t == nt - 2);
;             const char* a1 = cA + (size_t)(t + 1) * kstep;
;             const char* a2 = last ? nA : cA + (size_t)(t + 2) * kstep; const char* b2 = last ? nB : cB + (size_t)(t + 2) * kstep;
;             const char* a3 = a2 + kstep; const char* b3 = b2 + kstep;
;             if (last && has_next) S.a_ready(nxt);
;             if constexpr (SP2) {
;             PG8_LDB(B0, 0, 0); PG8_LDB(B1, 0, 1); PG8_SCHED; PG8_LDA(At, 0, 0); PG8_STAGE(PG8_SA(1, 1), a1 + hstepA, voffA);
;             PG8_WAIT_V(8); PG8_WAIT_L(0); PG8_BAR; PG8_MMA(0, 0, At, B0); PG8_MMA(0, 1, At, B1); PG8_BAR; PG8_SCHED;
;             PG8_LDA(At, 0, 1); PG8_STAGE(PG8_SB(0, 0), b2, voffB); PG8_STAGE(PG8_SB(0, 1), b2 + hstepB, voffB); PG8_STAGE(PG8_SA(0, 0), a2, voffA);
;             PG8_WAIT_V(8); PG8_WAIT_L(0); PG8_BAR; PG8_MMA(1, 0, At, B0); PG8_MMA(1, 1, At, B1); PG8_BAR; PG8_SCHED;
.LBB0_121:
	ds_read_b128 v[146:149], v152
	ds_read_b128 v[156:159], v152 offset:1024
	ds_read_b128 v[160:163], v152 offset:2048
	ds_read_b128 v[164:167], v152 offset:3072
	ds_read_b128 v[168:171], v153
	ds_read_b128 v[172:175], v153 offset:1024
	ds_read_b128 v[176:179], v153 offset:2048
	ds_read_b128 v[180:183], v153 offset:3072
	s_add_u32 s66, s64, 0xfff00080
	s_addc_u32 s67, s65, -1
	s_cmp_eq_u32 s96, 60
	s_cselect_b32 s69, s57, s67
	s_cselect_b32 s68, s92, s66
	s_cselect_b32 s67, s55, s95
	s_cselect_b32 s66, s93, s94
	v_lshl_add_u64 v[216:217], s[64:65], 0, v[138:139]
	s_add_i32 m0, s75, 0xc000
	ds_read_b128 v[184:187], v154
	ds_read_b128 v[188:191], v154 offset:1024
	ds_read_b128 v[192:195], v154 offset:2048
	ds_read_b128 v[196:199], v154 offset:3072
	ds_read_b128 v[200:203], v154 offset:4096
	ds_read_b128 v[204:207], v154 offset:5120
	ds_read_b128 v[208:211], v154 offset:6144
	ds_read_b128 v[212:215], v154 offset:7168
	global_load_lds_dwordx4 v[216:217], off
	v_lshl_add_u64 v[216:217], s[64:65], 0, v[140:141]
	s_add_i32 m0, s75, 0xe000
	s_nop 0
	global_load_lds_dwordx4 v[216:217], off
	s_waitcnt vmcnt(8)
	s_waitcnt lgkmcnt(0)
	s_barrier
	s_setprio 2
	s_waitcnt lgkmcnt(0)
	v_mfma_f32_16x16x32_bf16 v[76:79], v[146:149], v[184:187], v[76:79]
	v_mfma_f32_16x16x32_bf16 v[72:75], v[160:163], v[184:187], v[72:75]
	v_mfma_f32_16x16x32_bf16 v[68:71], v[146:149], v[192:195], v[68:71]
	v_mfma_f32_16x16x32_bf16 v[64:67], v[160:163], v[192:195], v[64:67]
	v_mfma_f32_16x16x32_bf16 v[56:59], v[146:149], v[200:203], v[56:59]
	v_mfma_f32_16x16x32_bf16 v[52:55], v[160:163], v[200:203], v[52:55]
	v_mfma_f32_16x16x32_bf16 v[44:47], v[146:149], v[208:211], v[44:47]
	v_mfma_f32_16x16x32_bf16 v[40:43], v[160:163], v[208:211], v[40:43]
	s_setprio 0
	s_setprio 2
	v_mfma_f32_16x16x32_bf16 v[76:79], v[156:159], v[188:191], v[76:79]
	v_mfma_f32_16x16x32_bf16 v[72:75], v[164:167], v[188:191], v[72:75]
	v_mfma_f32_16x16x32_bf16 v[68:71], v[156:159], v[196:199], v[68:71]
	v_mfma_f32_16x16x32_bf16 v[64:67], v[164:167], v[196:199], v[64:67]
	v_mfma_f32_16x16x32_bf16 v[56:59], v[156:159], v[204:207], v[56:59]
	v_mfma_f32_16x16x32_bf16 v[52:55], v[164:167], v[204:207], v[52:55]
	v_mfma_f32_16x16x32_bf16 v[44:47], v[156:159], v[212:215], v[44:47]
	v_mfma_f32_16x16x32_bf16 v[40:43], v[164:167], v[212:215], v[40:43]
	s_setprio 0
	s_setprio 2
	v_mfma_f32_16x16x32_bf16 v[124:127], v[168:171], v[184:187], v[124:127]
	v_mfma_f32_16x16x32_bf16 v[120:123], v[176:179], v[184:187], v[120:123]
	v_mfma_f32_16x16x32_bf16 v[116:119], v[168:171], v[192:195], v[116:119]
	v_mfma_f32_16x16x32_bf16 v[112:115], v[176:179], v[192:195], v[112:115]
	v_mfma_f32_16x16x32_bf16 v[108:111], v[168:171], v[200:203], v[108:111]
	v_mfma_f32_16x16x32_bf16 v[104:107], v[176:179], v[200:203], v[104:107]
	v_mfma_f32_16x16x32_bf16 v[100:103], v[168:171], v[208:211], v[100:103]
	v_mfma_f32_16x16x32_bf16 v[96:99], v[176:179], v[208:211], v[96:99]
	s_setprio 0
	s_setprio 2
	v_mfma_f32_16x16x32_bf16 v[124:127], v[172:175], v[188:191], v[124:127]
	v_mfma_f32_16x16x32_bf16 v[120:123], v[180:183], v[188:191], v[120:123]
	v_mfma_f32_16x16x32_bf16 v[116:119], v[172:175], v[196:199], v[116:119]
	v_mfma_f32_16x16x32_bf16 v[112:115], v[180:183], v[196:199], v[112:115]
	v_mfma_f32_16x16x32_bf16 v[108:111], v[172:175], v[204:207], v[108:111]
	v_mfma_f32_16x16x32_bf16 v[104:107], v[180:183], v[204:207], v[104:107]
	v_mfma_f32_16x16x32_bf16 v[100:103], v[172:175], v[212:215], v[100:103]
	s_setprio 3
	s_barrier
	v_mfma_f32_16x16x32_bf16 v[96:99], v[180:183], v[212:215], v[96:99]
	s_setprio 0
	s_add_i32 s97, s84, s74
	v_lshl_add_u64 v[216:217], s[66:67], 0, v[130:131]
	s_mov_b32 m0, s97
	ds_read_b128 v[184:187], v154 offset:16384
	ds_read_b128 v[188:191], v154 offset:17408
	ds_read_b128 v[192:195], v154 offset:18432
	ds_read_b128 v[196:199], v154 offset:19456
	ds_read_b128 v[200:203], v154 offset:20480
	ds_read_b128 v[204:207], v154 offset:21504
	ds_read_b128 v[208:211], v154 offset:22528
	ds_read_b128 v[212:215], v154 offset:23552
	global_load_lds_dwordx4 v[216:217], off
	s_add_i32 m0, s97, 0x2000
	s_add_u32 vcc_lo, s66, 0x100000
	v_lshl_add_u64 v[218:219], s[66:67], 0, v[134:135]
	s_addc_u32 vcc_hi, s67, 0
	s_add_i32 s97, s85, s74
	global_load_lds_dwordx4 v[218:219], off
	v_lshl_add_u64 v[220:221], vcc, 0, v[130:131]
	s_mov_b32 m0, s97
	v_lshl_add_u64 v[222:223], s[68:69], 0, v[132:133]
	global_load_lds_dwordx4 v[220:221], off
	v_lshl_add_u64 v[220:221], vcc, 0, v[134:135]
	s_add_i32 m0, s97, 0x2000
	s_nop 0
	global_load_lds_dwordx4 v[220:221], off
	v_lshl_add_u64 v[220:221], s[68:69], 0, v[128:129]
	s_mov_b32 m0, s75
	s_nop 0
	global_load_lds_dwordx4 v[220:221], off
	s_mov_b32 m0, s76
	s_nop 0
	global_load_lds_dwordx4 v[222:223], off
	s_waitcnt vmcnt(8)
	s_waitcnt lgkmcnt(0)
	s_barrier
; #define PG8_STAGE(bufoff, gbase, voff) do { _Pragma("unroll") for (int _i = 0; _i < 2; ++_i) \
;         __builtin_amdgcn_global_load_lds((const unsigned*)((const char*)(gbase) + (voff)[_i]), (PG8_LAS unsigned*)(lds + (bufoff) + ldsw + _i * 8192), 16, 0, 0); } while (0)
; #define PG8_LDA(dst, b, h) do { _Pragma("unroll") for (int m = 0; m < 4; ++m) _Pragma("unroll") for (int k = 0; k < 2; ++k) dst[m][k] = *(const PG8_LAS bf16x8*)(lds + PG8_SA(b, h) + aoff + m * 2048 + k * 1024); } while (0)
; #define PG8_LDB(dst, b, h) do { _Pragma("unroll") for (int n = 0; n < 2; ++n) _Pragma("unroll") for (int k = 0; k < 2; ++k) dst[n][k] = *(const PG8_LAS bf16x8*)(lds + PG8_SB(b, h) + boff + n * 2048 + k * 1024); } while (0)
; #define PG8_MMA(ai, bj, At, Bt) do { __builtin_amdgcn_s_setprio(1); _Pragma("unroll") for (int m = 0; m < 4; ++m) _Pragma("unroll") for (int n = 0; n < 2; ++n) _Pragma("unroll") for (int k = 0; k < 2; ++k) \
;         acc[ai][bj][m][n] = __builtin_amdgcn_mfma_f32_16x16x32_bf16(Bt[n][k], At[m][k], acc[ai][bj][m][n], 0, 0, 0); __builtin_amdgcn_s_setprio(0); } while (0)
; #define PG8_WAIT_V(n) asm volatile("s_waitcnt vmcnt(" #n ")" ::: "memory")
; #define PG8_WAIT_L(n) asm volatile("s_waitcnt lgkmcnt(" #n ")" ::: "memory")
; #define PG8_BAR __builtin_amdgcn_s_barrier()
; #define PG8_SCHED __builtin_amdgcn_sched_barrier(0)
; template <class Epi, class Sched, bool ALIGN_EPI = false, bool SP2 = false>
; __device__ __forceinline__ void gemm_phase(PG8_LAS unsigned char* lds, const Gemm g, const Sched& S, const Epi& E, const int wv  ) {
;     ...
;             PG8_WAIT_V(8); PG8_WAIT_L(0); PG8_BAR; PG8_MMA(1, 0, At, B0); PG8_MMA(1, 1, At, B1); PG8_BAR; PG8_SCHED;
;             PG8_LDB(B0, 1, 0); PG8_LDB(B1, 1, 1); PG8_SCHED; PG8_LDA(At, 1, 0); PG8_STAGE(PG8_SA(0, 1), a2 + hstepA, voffA);
;             PG8_WAIT_V(8); PG8_WAIT_L(0); PG8_BAR; PG8_MMA(0, 0, At, B0); PG8_MMA(0, 1, At, B1); PG8_BAR; PG8_SCHED;
	s_setprio 2
	s_waitcnt lgkmcnt(0)
	v_mfma_f32_16x16x32_bf16 v[28:31], v[146:149], v[184:187], v[28:31]
	v_mfma_f32_16x16x32_bf16 v[24:27], v[160:163], v[184:187], v[24:27]
	v_mfma_f32_16x16x32_bf16 v[20:23], v[146:149], v[192:195], v[20:23]
	v_mfma_f32_16x16x32_bf16 v[16:19], v[160:163], v[192:195], v[16:19]
	v_mfma_f32_16x16x32_bf16 v[12:15], v[146:149], v[200:203], v[12:15]
	v_mfma_f32_16x16x32_bf16 v[8:11], v[160:163], v[200:203], v[8:11]
	v_mfma_f32_16x16x32_bf16 v[4:7], v[146:149], v[208:211], v[4:7]
	v_mfma_f32_16x16x32_bf16 v[0:3], v[160:163], v[208:211], v[0:3]
	s_setprio 0
	s_setprio 2
	v_mfma_f32_16x16x32_bf16 v[28:31], v[156:159], v[188:191], v[28:31]
	v_mfma_f32_16x16x32_bf16 v[24:27], v[164:167], v[188:191], v[24:27]
	v_mfma_f32_16x16x32_bf16 v[20:23], v[156:159], v[196:199], v[20:23]
	v_mfma_f32_16x16x32_bf16 v[16:19], v[164:167], v[196:199], v[16:19]
	v_mfma_f32_16x16x32_bf16 v[12:15], v[156:159], v[204:207], v[12:15]
	v_mfma_f32_16x16x32_bf16 v[8:11], v[164:167], v[204:207], v[8:11]
	v_mfma_f32_16x16x32_bf16 v[4:7], v[156:159], v[212:215], v[4:7]
	v_mfma_f32_16x16x32_bf16 v[0:3], v[164:167], v[212:215], v[0:3]
	s_setprio 0
	s_setprio 2
	v_mfma_f32_16x16x32_bf16 v[92:95], v[168:171], v[184:187], v[92:95]
	v_mfma_f32_16x16x32_bf16 v[88:91], v[176:179], v[184:187], v[88:91]
	v_mfma_f32_16x16x32_bf16 v[84:87], v[168:171], v[192:195], v[84:87]
	v_mfma_f32_16x16x32_bf16 v[80:83], v[176:179], v[192:195], v[80:83]
	v_mfma_f32_16x16x32_bf16 v[60:63], v[168:171], v[200:203], v[60:63]
	v_mfma_f32_16x16x32_bf16 v[48:51], v[176:179], v[200:203], v[48:51]
	v_mfma_f32_16x16x32_bf16 v[36:39], v[168:171], v[208:211], v[36:39]
	v_mfma_f32_16x16x32_bf16 v[32:35], v[176:179], v[208:211], v[32:35]
	s_setprio 0
	s_setprio 2
	v_mfma_f32_16x16x32_bf16 v[92:95], v[172:175], v[188:191], v[92:95]
	v_mfma_f32_16x16x32_bf16 v[88:91], v[180:183], v[188:191], v[88:91]
	v_mfma_f32_16x16x32_bf16 v[84:87], v[172:175], v[196:199], v[84:87]
	v_mfma_f32_16x16x32_bf16 v[80:83], v[180:183], v[196:199], v[80:83]
	v_mfma_f32_16x16x32_bf16 v[60:63], v[172:175], v[204:207], v[60:63]
	v_mfma_f32_16x16x32_bf16 v[48:51], v[180:183], v[204:207], v[48:51]
	v_mfma_f32_16x16x32_bf16 v[36:39], v[172:175], v[212:215], v[36:39]
	s_setprio 3
	s_barrier
	v_mfma_f32_16x16x32_bf16 v[32:35], v[180:183], v[212:215], v[32:35]
	s_setprio 0
	s_add_i32 s97, 0, 0x18000
	v_add_u32_e32 v155, s97, v150
	s_add_i32 vcc_lo, 0, 0x1c000
	ds_read_b128 v[146:149], v155
	ds_read_b128 v[156:159], v155 offset:1024
	ds_read_b128 v[160:163], v155 offset:2048
	ds_read_b128 v[164:167], v155 offset:3072
	v_add_u32_e32 v155, vcc_lo, v150
	ds_read_b128 v[168:171], v155
	ds_read_b128 v[172:175], v155 offset:1024
	ds_read_b128 v[176:179], v155 offset:2048
	ds_read_b128 v[180:183], v155 offset:3072
	s_add_u32 s68, s68, 0x100000
	s_addc_u32 s69, s69, 0
	s_mov_b32 m0, s77
	v_lshl_add_u64 v[224:225], s[68:69], 0, v[128:129]
	ds_read_b128 v[184:187], v154 offset:32768
	ds_read_b128 v[188:191], v154 offset:33792
	ds_read_b128 v[192:195], v154 offset:34816
	ds_read_b128 v[196:199], v154 offset:35840
	ds_read_b128 v[200:203], v154 offset:36864
	ds_read_b128 v[204:207], v154 offset:37888
	ds_read_b128 v[208:211], v154 offset:38912
	ds_read_b128 v[212:215], v154 offset:39936
	global_load_lds_dwordx4 v[224:225], off
	v_lshl_add_u64 v[224:225], s[68:69], 0, v[132:133]
	s_mov_b32 m0, s78
	s_nop 0
	global_load_lds_dwordx4 v[224:225], off
	s_waitcnt vmcnt(8)
	s_waitcnt lgkmcnt(0)
	s_barrier
	s_setprio 2
	s_waitcnt lgkmcnt(0)
	v_mfma_f32_16x16x32_bf16 v[76:79], v[146:149], v[184:187], v[76:79]
	v_mfma_f32_16x16x32_bf16 v[72:75], v[160:163], v[184:187], v[72:75]
	v_mfma_f32_16x16x32_bf16 v[68:71], v[146:149], v[192:195], v[68:71]
	v_mfma_f32_16x16x32_bf16 v[64:67], v[160:163], v[192:195], v[64:67]
	v_mfma_f32_16x16x32_bf16 v[56:59], v[146:149], v[200:203], v[56:59]
	v_mfma_f32_16x16x32_bf16 v[52:55], v[160:163], v[200:203], v[52:55]
	v_mfma_f32_16x16x32_bf16 v[44:47], v[146:149], v[208:211], v[44:47]
	v_mfma_f32_16x16x32_bf16 v[40:43], v[160:163], v[208:211], v[40:43]
	s_setprio 0
	s_setprio 2
	v_mfma_f32_16x16x32_bf16 v[76:79], v[156:159], v[188:191], v[76:79]
	v_mfma_f32_16x16x32_bf16 v[72:75], v[164:167], v[188:191], v[72:75]
	v_mfma_f32_16x16x32_bf16 v[68:71], v[156:159], v[196:199], v[68:71]
	v_mfma_f32_16x16x32_bf16 v[64:67], v[164:167], v[196:199], v[64:67]
	v_mfma_f32_16x16x32_bf16 v[56:59], v[156:159], v[204:207], v[56:59]
	v_mfma_f32_16x16x32_bf16 v[52:55], v[164:167], v[204:207], v[52:55]
	v_mfma_f32_16x16x32_bf16 v[44:47], v[156:159], v[212:215], v[44:47]
	v_mfma_f32_16x16x32_bf16 v[40:43], v[164:167], v[212:215], v[40:43]
	s_setprio 0
	s_setprio 2
	v_mfma_f32_16x16x32_bf16 v[124:127], v[168:171], v[184:187], v[124:127]
	v_mfma_f32_16x16x32_bf16 v[120:123], v[176:179], v[184:187], v[120:123]
	v_mfma_f32_16x16x32_bf16 v[116:119], v[168:171], v[192:195], v[116:119]
	v_mfma_f32_16x16x32_bf16 v[112:115], v[176:179], v[192:195], v[112:115]
	v_mfma_f32_16x16x32_bf16 v[108:111], v[168:171], v[200:203], v[108:111]
	v_mfma_f32_16x16x32_bf16 v[104:107], v[176:179], v[200:203], v[104:107]
	v_mfma_f32_16x16x32_bf16 v[100:103], v[168:171], v[208:211], v[100:103]
	v_mfma_f32_16x16x32_bf16 v[96:99], v[176:179], v[208:211], v[96:99]
	s_setprio 0
	s_setprio 2
	v_mfma_f32_16x16x32_bf16 v[124:127], v[172:175], v[188:191], v[124:127]
	v_mfma_f32_16x16x32_bf16 v[120:123], v[180:183], v[188:191], v[120:123]
	v_mfma_f32_16x16x32_bf16 v[116:119], v[172:175], v[196:199], v[116:119]
	v_mfma_f32_16x16x32_bf16 v[112:115], v[180:183], v[196:199], v[112:115]
	v_mfma_f32_16x16x32_bf16 v[108:111], v[172:175], v[204:207], v[108:111]
	v_mfma_f32_16x16x32_bf16 v[104:107], v[180:183], v[204:207], v[104:107]
	v_mfma_f32_16x16x32_bf16 v[100:103], v[172:175], v[212:215], v[100:103]
	s_setprio 3
	s_barrier
; #define PG8_STAGE(bufoff, gbase, voff) do { _Pragma("unroll") for (int _i = 0; _i < 2; ++_i) \
;         __builtin_amdgcn_global_load_lds((const unsigned*)((const char*)(gbase) + (voff)[_i]), (PG8_LAS unsigned*)(lds + (bufoff) + ldsw + _i * 8192), 16, 0, 0); } while (0)
; #define PG8_LDA(dst, b, h) do { _Pragma("unroll") for (int m = 0; m < 4; ++m) _Pragma("unroll") for (int k = 0; k < 2; ++k) dst[m][k] = *(const PG8_LAS bf16x8*)(lds + PG8_SA(b, h) + aoff + m * 2048 + k * 1024); } while (0)
; #define PG8_MMA(ai, bj, At, Bt) do { __builtin_amdgcn_s_setprio(1); _Pragma("unroll") for (int m = 0; m < 4; ++m) _Pragma("unroll") for (int n = 0; n < 2; ++n) _Pragma("unroll") for (int k = 0; k < 2; ++k) \
;         acc[ai][bj][m][n] = __builtin_amdgcn_mfma_f32_16x16x32_bf16(Bt[n][k], At[m][k], acc[ai][bj][m][n], 0, 0, 0); __builtin_amdgcn_s_setprio(0); } while (0)
; #define PG8_WAIT_V(n) asm volatile("s_waitcnt vmcnt(" #n ")" ::: "memory")
; #define PG8_WAIT_L(n) asm volatile("s_waitcnt lgkmcnt(" #n ")" ::: "memory")
; #define PG8_BAR __builtin_amdgcn_s_barrier()
; #define PG8_SCHED __builtin_amdgcn_sched_barrier(0)
; template <class Epi, class Sched, bool ALIGN_EPI = false, bool SP2 = false>
; __device__ __forceinline__ void gemm_phase(PG8_LAS unsigned char* lds, const Gemm g, const Sched& S, const Epi& E, const int wv  ) {
;     ...
;             PG8_WAIT_V(8); PG8_WAIT_L(0); PG8_BAR; PG8_MMA(0, 0, At, B0); PG8_MMA(0, 1, At, B1); PG8_BAR; PG8_SCHED;
;             PG8_LDA(At, 1, 1); PG8_STAGE(PG8_SB(1, 0), b3, voffB); PG8_STAGE(PG8_SB(1, 1), b3 + hstepB, voffB); PG8_STAGE(PG8_SA(1, 0), a3, voffA);
;             PG8_WAIT_V(8); PG8_WAIT_L(0); PG8_BAR; PG8_MMA(1, 0, At, B0); PG8_MMA(1, 1, At, B1); PG8_BAR; PG8_SCHED;
	v_mfma_f32_16x16x32_bf16 v[96:99], v[180:183], v[212:215], v[96:99]
	s_setprio 0
	s_add_i32 s68, s97, s74
	v_lshl_add_u64 v[216:217], v[216:217], 0, s[18:19]
	s_mov_b32 m0, s68
	ds_read_b128 v[184:187], v154 offset:49152
	ds_read_b128 v[188:191], v154 offset:50176
	ds_read_b128 v[192:195], v154 offset:51200
	ds_read_b128 v[196:199], v154 offset:52224
	ds_read_b128 v[200:203], v154 offset:53248
	ds_read_b128 v[204:207], v154 offset:54272
	ds_read_b128 v[208:211], v154 offset:55296
	ds_read_b128 v[212:215], v154 offset:56320
	global_load_lds_dwordx4 v[216:217], off
	s_add_i32 m0, s68, 0x2000
	s_add_u32 s66, s66, 0x100080
	v_lshl_add_u64 v[216:217], v[218:219], 0, s[18:19]
	s_addc_u32 s67, s67, 0
	s_add_i32 s68, vcc_lo, s74
	global_load_lds_dwordx4 v[216:217], off
	v_lshl_add_u64 v[216:217], s[66:67], 0, v[130:131]
	s_mov_b32 m0, s68
	s_nop 0
	global_load_lds_dwordx4 v[216:217], off
	v_lshl_add_u64 v[216:217], s[66:67], 0, v[134:135]
	s_add_i32 m0, s68, 0x2000
	s_nop 0
	global_load_lds_dwordx4 v[216:217], off
	v_lshl_add_u64 v[216:217], v[220:221], 0, s[18:19]
	s_mov_b32 m0, s81
	s_nop 0
	global_load_lds_dwordx4 v[216:217], off
	v_lshl_add_u64 v[216:217], v[222:223], 0, s[18:19]
	s_mov_b32 m0, s82
	s_nop 0
	global_load_lds_dwordx4 v[216:217], off
	s_waitcnt vmcnt(8)
	s_waitcnt lgkmcnt(0)
	s_barrier
	s_setprio 2
	s_waitcnt lgkmcnt(0)
	v_mfma_f32_16x16x32_bf16 v[28:31], v[146:149], v[184:187], v[28:31]
	v_mfma_f32_16x16x32_bf16 v[24:27], v[160:163], v[184:187], v[24:27]
	v_mfma_f32_16x16x32_bf16 v[20:23], v[146:149], v[192:195], v[20:23]
	v_mfma_f32_16x16x32_bf16 v[16:19], v[160:163], v[192:195], v[16:19]
	v_mfma_f32_16x16x32_bf16 v[12:15], v[146:149], v[200:203], v[12:15]
	v_mfma_f32_16x16x32_bf16 v[8:11], v[160:163], v[200:203], v[8:11]
	v_mfma_f32_16x16x32_bf16 v[4:7], v[146:149], v[208:211], v[4:7]
	v_mfma_f32_16x16x32_bf16 v[0:3], v[160:163], v[208:211], v[0:3]
	s_setprio 0
	s_setprio 2
	v_mfma_f32_16x16x32_bf16 v[28:31], v[156:159], v[188:191], v[28:31]
	v_mfma_f32_16x16x32_bf16 v[24:27], v[164:167], v[188:191], v[24:27]
	v_mfma_f32_16x16x32_bf16 v[20:23], v[156:159], v[196:199], v[20:23]
	v_mfma_f32_16x16x32_bf16 v[16:19], v[164:167], v[196:199], v[16:19]
	v_mfma_f32_16x16x32_bf16 v[12:15], v[156:159], v[204:207], v[12:15]
	v_mfma_f32_16x16x32_bf16 v[8:11], v[164:167], v[204:207], v[8:11]
	v_mfma_f32_16x16x32_bf16 v[4:7], v[156:159], v[212:215], v[4:7]
	v_mfma_f32_16x16x32_bf16 v[0:3], v[164:167], v[212:215], v[0:3]
	s_setprio 0
	s_setprio 2
	v_mfma_f32_16x16x32_bf16 v[92:95], v[168:171], v[184:187], v[92:95]
	v_mfma_f32_16x16x32_bf16 v[88:91], v[176:179], v[184:187], v[88:91]
	v_mfma_f32_16x16x32_bf16 v[84:87], v[168:171], v[192:195], v[84:87]
	v_mfma_f32_16x16x32_bf16 v[80:83], v[176:179], v[192:195], v[80:83]
	v_mfma_f32_16x16x32_bf16 v[60:63], v[168:171], v[200:203], v[60:63]
	v_mfma_f32_16x16x32_bf16 v[48:51], v[176:179], v[200:203], v[48:51]
	v_mfma_f32_16x16x32_bf16 v[36:39], v[168:171], v[208:211], v[36:39]
	v_mfma_f32_16x16x32_bf16 v[32:35], v[176:179], v[208:211], v[32:35]
	s_setprio 0
	s_setprio 2
	v_mfma_f32_16x16x32_bf16 v[92:95], v[172:175], v[188:191], v[92:95]
	v_mfma_f32_16x16x32_bf16 v[88:91], v[180:183], v[188:191], v[88:91]
	v_mfma_f32_16x16x32_bf16 v[84:87], v[172:175], v[196:199], v[84:87]
	v_mfma_f32_16x16x32_bf16 v[80:83], v[180:183], v[196:199], v[80:83]
	v_mfma_f32_16x16x32_bf16 v[60:63], v[172:175], v[204:207], v[60:63]
	v_mfma_f32_16x16x32_bf16 v[48:51], v[180:183], v[204:207], v[48:51]
	v_mfma_f32_16x16x32_bf16 v[36:39], v[172:175], v[212:215], v[36:39]
	s_setprio 3
	s_barrier
	v_mfma_f32_16x16x32_bf16 v[32:35], v[180:183], v[212:215], v[32:35]
	s_setprio 0
	s_add_i32 s96, s96, 2
	s_add_u32 s64, s64, 0x100
	s_addc_u32 s65, s65, 0
	s_add_u32 s94, s94, 0x100
	s_addc_u32 s95, s95, 0
	s_cmp_gt_u32 s96, 61
	s_cbranch_scc0 .LBB0_121
	s_and_b64 vcc, exec, s[20:21]
	s_cbranch_vccz .LBB0_124
	s_barrier

; #define PG8_STAGE(bufoff, gbase, voff) do { _Pragma("unroll") for (int _i = 0; _i < 2; ++_i) \
;         __builtin_amdgcn_global_load_lds((const unsigned*)((const char*)(gbase) + (voff)[_i]), (PG8_LAS unsigned*)(lds + (bufoff) + ldsw + _i * 8192), 16, 0, 0); } while (0)
; #define PG8_LDA(dst, b, h) do { _Pragma("unroll") for (int m = 0; m < 4; ++m) _Pragma("unroll") for (int k = 0; k < 2; ++k) dst[m][k] = *(const PG8_LAS bf16x8*)(lds + PG8_SA(b, h) + aoff + m * 2048 + k * 1024); } while (0)
; #define PG8_LDB(dst, b, h) do { _Pragma("unroll") for (int n = 0; n < 2; ++n) _Pragma("unroll") for (int k = 0; k < 2; ++k) dst[n][k] = *(const PG8_LAS bf16x8*)(lds + PG8_SB(b, h) + boff + n * 2048 + k * 1024); } while (0)
; #define PG8_MMA(ai, bj, At, Bt) do { __builtin_amdgcn_s_setprio(1); _Pragma("unroll") for (int m = 0; m < 4; ++m) _Pragma("unroll") for (int n = 0; n < 2; ++n) _Pragma("unroll") for (int k = 0; k < 2; ++k) \
;         acc[ai][bj][m][n] = __builtin_amdgcn_mfma_f32_16x16x32_bf16(Bt[n][k], At[m][k], acc[ai][bj][m][n], 0, 0, 0); __builtin_amdgcn_s_setprio(0); } while (0)
; #define PG8_WAIT_V(n) asm volatile("s_waitcnt vmcnt(" #n ")" ::: "memory")
; #define PG8_BAR __builtin_amdgcn_s_barrier()
; template <class Epi, class Sched, bool ALIGN_EPI = false, bool SP2 = false>
; __device__ __forceinline__ void gemm_phase(PG8_LAS unsigned char* lds, const Gemm g, const Sched& S, const Epi& E, const int wv  ) {
;     ...
;         for (int t = 0; t < nt; t += 2) {
;             const bool last = (t == nt - 2);
;             const char* a1 = cA + (size_t)(t + 1) * kstep;
;             const char* a2 = last ? nA : cA + (size_t)(t + 2) * kstep; const char* b2 = last ? nB : cB + (size_t)(t + 2) * kstep;
;             const char* a3 = a2 + kstep; const char* b3 = b2 + kstep;
;             if (last && has_next) S.a_ready(nxt);
;             if constexpr (SP2) {
;             PG8_LDB(B0, 0, 0); PG8_LDB(B1, 0, 1); PG8_SCHED; PG8_LDA(At, 0, 0); PG8_STAGE(PG8_SA(1, 1), a1 + hstepA, voffA);
;             PG8_WAIT_V(8); PG8_WAIT_L(0); PG8_BAR; PG8_MMA(0, 0, At, B0); PG8_MMA(0, 1, At, B1); PG8_BAR; PG8_SCHED;
;             PG8_LDA(At, 0, 1); PG8_STAGE(PG8_SB(0, 0), b2, voffB); PG8_STAGE(PG8_SB(0, 1), b2 + hstepB, voffB); PG8_STAGE(PG8_SA(0, 0), a2, voffA);
;             PG8_WAIT_V(8); PG8_WAIT_L(0); PG8_BAR; PG8_MMA(1, 0, At, B0); PG8_MMA(1, 1, At, B1); PG8_BAR; PG8_SCHED;
.LBB0_706:
	ds_read_b128 v[146:149], v152
	ds_read_b128 v[156:159], v152 offset:1024
	ds_read_b128 v[160:163], v152 offset:2048
	ds_read_b128 v[164:167], v152 offset:3072
	ds_read_b128 v[168:171], v153
	ds_read_b128 v[172:175], v153 offset:1024
	ds_read_b128 v[176:179], v153 offset:2048
	ds_read_b128 v[180:183], v153 offset:3072
	s_add_u32 s60, s58, 0xfff00080
	s_addc_u32 s61, s59, -1
	s_cmp_eq_u32 s87, 60
	s_cselect_b32 s63, s51, s61
	s_cselect_b32 s62, s83, s60
	s_cselect_b32 s61, s49, s86
	s_cselect_b32 s60, s84, s85
	v_lshl_add_u64 v[216:217], s[58:59], 0, v[138:139]
	s_add_i32 m0, s68, 0xc000
	ds_read_b128 v[184:187], v154
	ds_read_b128 v[188:191], v154 offset:1024
	ds_read_b128 v[192:195], v154 offset:2048
	ds_read_b128 v[196:199], v154 offset:3072
	ds_read_b128 v[200:203], v154 offset:4096
	ds_read_b128 v[204:207], v154 offset:5120
	ds_read_b128 v[208:211], v154 offset:6144
	ds_read_b128 v[212:215], v154 offset:7168
	global_load_lds_dwordx4 v[216:217], off
	v_lshl_add_u64 v[216:217], s[58:59], 0, v[140:141]
	s_add_i32 m0, s68, 0xe000
	s_nop 0
	global_load_lds_dwordx4 v[216:217], off
	s_waitcnt vmcnt(8)
	s_waitcnt lgkmcnt(0)
	s_barrier
	s_setprio 2
	s_waitcnt lgkmcnt(0)
	v_mfma_f32_16x16x32_bf16 v[76:79], v[146:149], v[184:187], v[76:79]
	v_mfma_f32_16x16x32_bf16 v[72:75], v[160:163], v[184:187], v[72:75]
	v_mfma_f32_16x16x32_bf16 v[68:71], v[146:149], v[192:195], v[68:71]
	v_mfma_f32_16x16x32_bf16 v[64:67], v[160:163], v[192:195], v[64:67]
	v_mfma_f32_16x16x32_bf16 v[56:59], v[146:149], v[200:203], v[56:59]
	v_mfma_f32_16x16x32_bf16 v[52:55], v[160:163], v[200:203], v[52:55]
	v_mfma_f32_16x16x32_bf16 v[44:47], v[146:149], v[208:211], v[44:47]
	v_mfma_f32_16x16x32_bf16 v[40:43], v[160:163], v[208:211], v[40:43]
	s_setprio 0
	s_setprio 2
	v_mfma_f32_16x16x32_bf16 v[76:79], v[156:159], v[188:191], v[76:79]
	v_mfma_f32_16x16x32_bf16 v[72:75], v[164:167], v[188:191], v[72:75]
	v_mfma_f32_16x16x32_bf16 v[68:71], v[156:159], v[196:199], v[68:71]
	v_mfma_f32_16x16x32_bf16 v[64:67], v[164:167], v[196:199], v[64:67]
	v_mfma_f32_16x16x32_bf16 v[56:59], v[156:159], v[204:207], v[56:59]
	v_mfma_f32_16x16x32_bf16 v[52:55], v[164:167], v[204:207], v[52:55]
	v_mfma_f32_16x16x32_bf16 v[44:47], v[156:159], v[212:215], v[44:47]
	v_mfma_f32_16x16x32_bf16 v[40:43], v[164:167], v[212:215], v[40:43]
	s_setprio 0
	s_setprio 2
	v_mfma_f32_16x16x32_bf16 v[124:127], v[168:171], v[184:187], v[124:127]
	v_mfma_f32_16x16x32_bf16 v[120:123], v[176:179], v[184:187], v[120:123]
	v_mfma_f32_16x16x32_bf16 v[116:119], v[168:171], v[192:195], v[116:119]
	v_mfma_f32_16x16x32_bf16 v[112:115], v[176:179], v[192:195], v[112:115]
	v_mfma_f32_16x16x32_bf16 v[108:111], v[168:171], v[200:203], v[108:111]
	v_mfma_f32_16x16x32_bf16 v[104:107], v[176:179], v[200:203], v[104:107]
	v_mfma_f32_16x16x32_bf16 v[100:103], v[168:171], v[208:211], v[100:103]
	v_mfma_f32_16x16x32_bf16 v[96:99], v[176:179], v[208:211], v[96:99]
	s_setprio 0
	s_setprio 2
	v_mfma_f32_16x16x32_bf16 v[124:127], v[172:175], v[188:191], v[124:127]
	v_mfma_f32_16x16x32_bf16 v[120:123], v[180:183], v[188:191], v[120:123]
	v_mfma_f32_16x16x32_bf16 v[116:119], v[172:175], v[196:199], v[116:119]
	v_mfma_f32_16x16x32_bf16 v[112:115], v[180:183], v[196:199], v[112:115]
	v_mfma_f32_16x16x32_bf16 v[108:111], v[172:175], v[204:207], v[108:111]
	v_mfma_f32_16x16x32_bf16 v[104:107], v[180:183], v[204:207], v[104:107]
	v_mfma_f32_16x16x32_bf16 v[100:103], v[172:175], v[212:215], v[100:103]
	s_setprio 3
	s_barrier
	v_mfma_f32_16x16x32_bf16 v[96:99], v[180:183], v[212:215], v[96:99]
	s_setprio 0
	s_add_i32 s90, s77, s67
	v_lshl_add_u64 v[216:217], s[60:61], 0, v[130:131]
	s_mov_b32 m0, s90
	ds_read_b128 v[184:187], v154 offset:16384
	ds_read_b128 v[188:191], v154 offset:17408
	ds_read_b128 v[192:195], v154 offset:18432
	ds_read_b128 v[196:199], v154 offset:19456
	ds_read_b128 v[200:203], v154 offset:20480
	ds_read_b128 v[204:207], v154 offset:21504
	ds_read_b128 v[208:211], v154 offset:22528
	ds_read_b128 v[212:215], v154 offset:23552
	global_load_lds_dwordx4 v[216:217], off
	s_add_i32 m0, s90, 0x2000
	s_add_u32 s90, s60, 0x100000
	v_lshl_add_u64 v[218:219], s[60:61], 0, v[134:135]
	s_addc_u32 s91, s61, 0
	s_add_i32 s92, s78, s67
	global_load_lds_dwordx4 v[218:219], off
	v_lshl_add_u64 v[220:221], s[90:91], 0, v[130:131]
	s_mov_b32 m0, s92
	v_lshl_add_u64 v[222:223], s[62:63], 0, v[132:133]
	global_load_lds_dwordx4 v[220:221], off
	v_lshl_add_u64 v[220:221], s[90:91], 0, v[134:135]
	s_add_i32 m0, s92, 0x2000
	s_nop 0
	global_load_lds_dwordx4 v[220:221], off
	v_lshl_add_u64 v[220:221], s[62:63], 0, v[128:129]
	s_mov_b32 m0, s68
	s_nop 0
	global_load_lds_dwordx4 v[220:221], off
	s_mov_b32 m0, s69
	s_nop 0
	global_load_lds_dwordx4 v[222:223], off
	s_waitcnt vmcnt(8)
	s_waitcnt lgkmcnt(0)
	s_barrier
; #define PG8_STAGE(bufoff, gbase, voff) do { _Pragma("unroll") for (int _i = 0; _i < 2; ++_i) \
;         __builtin_amdgcn_global_load_lds((const unsigned*)((const char*)(gbase) + (voff)[_i]), (PG8_LAS unsigned*)(lds + (bufoff) + ldsw + _i * 8192), 16, 0, 0); } while (0)
; #define PG8_LDA(dst, b, h) do { _Pragma("unroll") for (int m = 0; m < 4; ++m) _Pragma("unroll") for (int k = 0; k < 2; ++k) dst[m][k] = *(const PG8_LAS bf16x8*)(lds + PG8_SA(b, h) + aoff + m * 2048 + k * 1024); } while (0)
; #define PG8_LDB(dst, b, h) do { _Pragma("unroll") for (int n = 0; n < 2; ++n) _Pragma("unroll") for (int k = 0; k < 2; ++k) dst[n][k] = *(const PG8_LAS bf16x8*)(lds + PG8_SB(b, h) + boff + n * 2048 + k * 1024); } while (0)
; #define PG8_MMA(ai, bj, At, Bt) do { __builtin_amdgcn_s_setprio(1); _Pragma("unroll") for (int m = 0; m < 4; ++m) _Pragma("unroll") for (int n = 0; n < 2; ++n) _Pragma("unroll") for (int k = 0; k < 2; ++k) \
;         acc[ai][bj][m][n] = __builtin_amdgcn_mfma_f32_16x16x32_bf16(Bt[n][k], At[m][k], acc[ai][bj][m][n], 0, 0, 0); __builtin_amdgcn_s_setprio(0); } while (0)
; #define PG8_WAIT_V(n) asm volatile("s_waitcnt vmcnt(" #n ")" ::: "memory")
; #define PG8_WAIT_L(n) asm volatile("s_waitcnt lgkmcnt(" #n ")" ::: "memory")
; #define PG8_BAR __builtin_amdgcn_s_barrier()
; #define PG8_SCHED __builtin_amdgcn_sched_barrier(0)
; template <class Epi, class Sched, bool ALIGN_EPI = false, bool SP2 = false>
; __device__ __forceinline__ void gemm_phase(PG8_LAS unsigned char* lds, const Gemm g, const Sched& S, const Epi& E, const int wv  ) {
;     ...
;             PG8_WAIT_V(8); PG8_WAIT_L(0); PG8_BAR; PG8_MMA(1, 0, At, B0); PG8_MMA(1, 1, At, B1); PG8_BAR; PG8_SCHED;
;             PG8_LDB(B0, 1, 0); PG8_LDB(B1, 1, 1); PG8_SCHED; PG8_LDA(At, 1, 0); PG8_STAGE(PG8_SA(0, 1), a2 + hstepA, voffA);
;             PG8_WAIT_V(8); PG8_WAIT_L(0); PG8_BAR; PG8_MMA(0, 0, At, B0); PG8_MMA(0, 1, At, B1); PG8_BAR; PG8_SCHED;
	s_setprio 2
	s_waitcnt lgkmcnt(0)
	v_mfma_f32_16x16x32_bf16 v[28:31], v[146:149], v[184:187], v[28:31]
	v_mfma_f32_16x16x32_bf16 v[24:27], v[160:163], v[184:187], v[24:27]
	v_mfma_f32_16x16x32_bf16 v[20:23], v[146:149], v[192:195], v[20:23]
	v_mfma_f32_16x16x32_bf16 v[16:19], v[160:163], v[192:195], v[16:19]
	v_mfma_f32_16x16x32_bf16 v[12:15], v[146:149], v[200:203], v[12:15]
	v_mfma_f32_16x16x32_bf16 v[8:11], v[160:163], v[200:203], v[8:11]
	v_mfma_f32_16x16x32_bf16 v[4:7], v[146:149], v[208:211], v[4:7]
	v_mfma_f32_16x16x32_bf16 v[0:3], v[160:163], v[208:211], v[0:3]
	s_setprio 0
	s_setprio 2
	v_mfma_f32_16x16x32_bf16 v[28:31], v[156:159], v[188:191], v[28:31]
	v_mfma_f32_16x16x32_bf16 v[24:27], v[164:167], v[188:191], v[24:27]
	v_mfma_f32_16x16x32_bf16 v[20:23], v[156:159], v[196:199], v[20:23]
	v_mfma_f32_16x16x32_bf16 v[16:19], v[164:167], v[196:199], v[16:19]
	v_mfma_f32_16x16x32_bf16 v[12:15], v[156:159], v[204:207], v[12:15]
	v_mfma_f32_16x16x32_bf16 v[8:11], v[164:167], v[204:207], v[8:11]
	v_mfma_f32_16x16x32_bf16 v[4:7], v[156:159], v[212:215], v[4:7]
	v_mfma_f32_16x16x32_bf16 v[0:3], v[164:167], v[212:215], v[0:3]
	s_setprio 0
	s_setprio 2
	v_mfma_f32_16x16x32_bf16 v[92:95], v[168:171], v[184:187], v[92:95]
	v_mfma_f32_16x16x32_bf16 v[88:91], v[176:179], v[184:187], v[88:91]
	v_mfma_f32_16x16x32_bf16 v[84:87], v[168:171], v[192:195], v[84:87]
	v_mfma_f32_16x16x32_bf16 v[80:83], v[176:179], v[192:195], v[80:83]
	v_mfma_f32_16x16x32_bf16 v[60:63], v[168:171], v[200:203], v[60:63]
	v_mfma_f32_16x16x32_bf16 v[48:51], v[176:179], v[200:203], v[48:51]
	v_mfma_f32_16x16x32_bf16 v[36:39], v[168:171], v[208:211], v[36:39]
	v_mfma_f32_16x16x32_bf16 v[32:35], v[176:179], v[208:211], v[32:35]
	s_setprio 0
	s_setprio 2
	v_mfma_f32_16x16x32_bf16 v[92:95], v[172:175], v[188:191], v[92:95]
	v_mfma_f32_16x16x32_bf16 v[88:91], v[180:183], v[188:191], v[88:91]
	v_mfma_f32_16x16x32_bf16 v[84:87], v[172:175], v[196:199], v[84:87]
	v_mfma_f32_16x16x32_bf16 v[80:83], v[180:183], v[196:199], v[80:83]
	v_mfma_f32_16x16x32_bf16 v[60:63], v[172:175], v[204:207], v[60:63]
	v_mfma_f32_16x16x32_bf16 v[48:51], v[180:183], v[204:207], v[48:51]
	v_mfma_f32_16x16x32_bf16 v[36:39], v[172:175], v[212:215], v[36:39]
	s_setprio 3
	s_barrier
	v_mfma_f32_16x16x32_bf16 v[32:35], v[180:183], v[212:215], v[32:35]
	s_setprio 0
	s_add_i32 s90, 0, 0x18000
	v_add_u32_e32 v155, s90, v150
	s_add_i32 s91, 0, 0x1c000
	ds_read_b128 v[146:149], v155
	ds_read_b128 v[156:159], v155 offset:1024
	ds_read_b128 v[160:163], v155 offset:2048
	ds_read_b128 v[164:167], v155 offset:3072
	v_add_u32_e32 v155, s91, v150
	ds_read_b128 v[168:171], v155
	ds_read_b128 v[172:175], v155 offset:1024
	ds_read_b128 v[176:179], v155 offset:2048
	ds_read_b128 v[180:183], v155 offset:3072
	s_add_u32 s62, s62, 0x100000
	s_addc_u32 s63, s63, 0
	s_mov_b32 m0, s70
	v_lshl_add_u64 v[224:225], s[62:63], 0, v[128:129]
	ds_read_b128 v[184:187], v154 offset:32768
	ds_read_b128 v[188:191], v154 offset:33792
	ds_read_b128 v[192:195], v154 offset:34816
	ds_read_b128 v[196:199], v154 offset:35840
	ds_read_b128 v[200:203], v154 offset:36864
	ds_read_b128 v[204:207], v154 offset:37888
	ds_read_b128 v[208:211], v154 offset:38912
	ds_read_b128 v[212:215], v154 offset:39936
	global_load_lds_dwordx4 v[224:225], off
	v_lshl_add_u64 v[224:225], s[62:63], 0, v[132:133]
	s_mov_b32 m0, s71
	s_nop 0
	global_load_lds_dwordx4 v[224:225], off
	s_waitcnt vmcnt(8)
	s_waitcnt lgkmcnt(0)
	s_barrier
	s_setprio 2
	s_waitcnt lgkmcnt(0)
	v_mfma_f32_16x16x32_bf16 v[76:79], v[146:149], v[184:187], v[76:79]
	v_mfma_f32_16x16x32_bf16 v[72:75], v[160:163], v[184:187], v[72:75]
	v_mfma_f32_16x16x32_bf16 v[68:71], v[146:149], v[192:195], v[68:71]
	v_mfma_f32_16x16x32_bf16 v[64:67], v[160:163], v[192:195], v[64:67]
	v_mfma_f32_16x16x32_bf16 v[56:59], v[146:149], v[200:203], v[56:59]
	v_mfma_f32_16x16x32_bf16 v[52:55], v[160:163], v[200:203], v[52:55]
	v_mfma_f32_16x16x32_bf16 v[44:47], v[146:149], v[208:211], v[44:47]
	v_mfma_f32_16x16x32_bf16 v[40:43], v[160:163], v[208:211], v[40:43]
	s_setprio 0
	s_setprio 2
	v_mfma_f32_16x16x32_bf16 v[76:79], v[156:159], v[188:191], v[76:79]
	v_mfma_f32_16x16x32_bf16 v[72:75], v[164:167], v[188:191], v[72:75]
	v_mfma_f32_16x16x32_bf16 v[68:71], v[156:159], v[196:199], v[68:71]
	v_mfma_f32_16x16x32_bf16 v[64:67], v[164:167], v[196:199], v[64:67]
	v_mfma_f32_16x16x32_bf16 v[56:59], v[156:159], v[204:207], v[56:59]
	v_mfma_f32_16x16x32_bf16 v[52:55], v[164:167], v[204:207], v[52:55]
	v_mfma_f32_16x16x32_bf16 v[44:47], v[156:159], v[212:215], v[44:47]
	v_mfma_f32_16x16x32_bf16 v[40:43], v[164:167], v[212:215], v[40:43]
	s_setprio 0
	s_setprio 2
	v_mfma_f32_16x16x32_bf16 v[124:127], v[168:171], v[184:187], v[124:127]
	v_mfma_f32_16x16x32_bf16 v[120:123], v[176:179], v[184:187], v[120:123]
	v_mfma_f32_16x16x32_bf16 v[116:119], v[168:171], v[192:195], v[116:119]
	v_mfma_f32_16x16x32_bf16 v[112:115], v[176:179], v[192:195], v[112:115]
	v_mfma_f32_16x16x32_bf16 v[108:111], v[168:171], v[200:203], v[108:111]
	v_mfma_f32_16x16x32_bf16 v[104:107], v[176:179], v[200:203], v[104:107]
	v_mfma_f32_16x16x32_bf16 v[100:103], v[168:171], v[208:211], v[100:103]
	v_mfma_f32_16x16x32_bf16 v[96:99], v[176:179], v[208:211], v[96:99]
	s_setprio 0
	s_setprio 2
	v_mfma_f32_16x16x32_bf16 v[124:127], v[172:175], v[188:191], v[124:127]
	v_mfma_f32_16x16x32_bf16 v[120:123], v[180:183], v[188:191], v[120:123]
	v_mfma_f32_16x16x32_bf16 v[116:119], v[172:175], v[196:199], v[116:119]
	v_mfma_f32_16x16x32_bf16 v[112:115], v[180:183], v[196:199], v[112:115]
	v_mfma_f32_16x16x32_bf16 v[108:111], v[172:175], v[204:207], v[108:111]
	v_mfma_f32_16x16x32_bf16 v[104:107], v[180:183], v[204:207], v[104:107]
	v_mfma_f32_16x16x32_bf16 v[100:103], v[172:175], v[212:215], v[100:103]
	s_setprio 3
	s_barrier
; #define PG8_STAGE(bufoff, gbase, voff) do { _Pragma("unroll") for (int _i = 0; _i < 2; ++_i) \
;         __builtin_amdgcn_global_load_lds((const unsigned*)((const char*)(gbase) + (voff)[_i]), (PG8_LAS unsigned*)(lds + (bufoff) + ldsw + _i * 8192), 16, 0, 0); } while (0)
; #define PG8_LDA(dst, b, h) do { _Pragma("unroll") for (int m = 0; m < 4; ++m) _Pragma("unroll") for (int k = 0; k < 2; ++k) dst[m][k] = *(const PG8_LAS bf16x8*)(lds + PG8_SA(b, h) + aoff + m * 2048 + k * 1024); } while (0)
; #define PG8_MMA(ai, bj, At, Bt) do { __builtin_amdgcn_s_setprio(1); _Pragma("unroll") for (int m = 0; m < 4; ++m) _Pragma("unroll") for (int n = 0; n < 2; ++n) _Pragma("unroll") for (int k = 0; k < 2; ++k) \
;         acc[ai][bj][m][n] = __builtin_amdgcn_mfma_f32_16x16x32_bf16(Bt[n][k], At[m][k], acc[ai][bj][m][n], 0, 0, 0); __builtin_amdgcn_s_setprio(0); } while (0)
; #define PG8_WAIT_V(n) asm volatile("s_waitcnt vmcnt(" #n ")" ::: "memory")
; #define PG8_WAIT_L(n) asm volatile("s_waitcnt lgkmcnt(" #n ")" ::: "memory")
; #define PG8_BAR __builtin_amdgcn_s_barrier()
; #define PG8_SCHED __builtin_amdgcn_sched_barrier(0)
; template <class Epi, class Sched, bool ALIGN_EPI = false, bool SP2 = false>
; __device__ __forceinline__ void gemm_phase(PG8_LAS unsigned char* lds, const Gemm g, const Sched& S, const Epi& E, const int wv  ) {
;     ...
;             PG8_WAIT_V(8); PG8_WAIT_L(0); PG8_BAR; PG8_MMA(0, 0, At, B0); PG8_MMA(0, 1, At, B1); PG8_BAR; PG8_SCHED;
;             PG8_LDA(At, 1, 1); PG8_STAGE(PG8_SB(1, 0), b3, voffB); PG8_STAGE(PG8_SB(1, 1), b3 + hstepB, voffB); PG8_STAGE(PG8_SA(1, 0), a3, voffA);
;             PG8_WAIT_V(8); PG8_WAIT_L(0); PG8_BAR; PG8_MMA(1, 0, At, B0); PG8_MMA(1, 1, At, B1); PG8_BAR; PG8_SCHED;
	v_mfma_f32_16x16x32_bf16 v[96:99], v[180:183], v[212:215], v[96:99]
	s_setprio 0
	s_add_i32 s62, s90, s67
	v_lshl_add_u64 v[216:217], v[216:217], 0, s[12:13]
	s_mov_b32 m0, s62
	ds_read_b128 v[184:187], v154 offset:49152
	ds_read_b128 v[188:191], v154 offset:50176
	ds_read_b128 v[192:195], v154 offset:51200
	ds_read_b128 v[196:199], v154 offset:52224
	ds_read_b128 v[200:203], v154 offset:53248
	ds_read_b128 v[204:207], v154 offset:54272
	ds_read_b128 v[208:211], v154 offset:55296
	ds_read_b128 v[212:215], v154 offset:56320
	global_load_lds_dwordx4 v[216:217], off
	s_add_i32 m0, s62, 0x2000
	s_add_u32 s60, s60, 0x100080
	v_lshl_add_u64 v[216:217], v[218:219], 0, s[12:13]
	s_addc_u32 s61, s61, 0
	s_add_i32 s62, s91, s67
	global_load_lds_dwordx4 v[216:217], off
	v_lshl_add_u64 v[216:217], s[60:61], 0, v[130:131]
	s_mov_b32 m0, s62
	s_nop 0
	global_load_lds_dwordx4 v[216:217], off
	v_lshl_add_u64 v[216:217], s[60:61], 0, v[134:135]
	s_add_i32 m0, s62, 0x2000
	s_nop 0
	global_load_lds_dwordx4 v[216:217], off
	v_lshl_add_u64 v[216:217], v[220:221], 0, s[12:13]
	s_mov_b32 m0, s74
	s_nop 0
	global_load_lds_dwordx4 v[216:217], off
	v_lshl_add_u64 v[216:217], v[222:223], 0, s[12:13]
	s_mov_b32 m0, s75
	s_nop 0
	global_load_lds_dwordx4 v[216:217], off
	s_waitcnt vmcnt(8)
	s_waitcnt lgkmcnt(0)
	s_barrier
	s_setprio 2
	s_waitcnt lgkmcnt(0)
	v_mfma_f32_16x16x32_bf16 v[28:31], v[146:149], v[184:187], v[28:31]
	v_mfma_f32_16x16x32_bf16 v[24:27], v[160:163], v[184:187], v[24:27]
	v_mfma_f32_16x16x32_bf16 v[20:23], v[146:149], v[192:195], v[20:23]
	v_mfma_f32_16x16x32_bf16 v[16:19], v[160:163], v[192:195], v[16:19]
	v_mfma_f32_16x16x32_bf16 v[12:15], v[146:149], v[200:203], v[12:15]
	v_mfma_f32_16x16x32_bf16 v[8:11], v[160:163], v[200:203], v[8:11]
	v_mfma_f32_16x16x32_bf16 v[4:7], v[146:149], v[208:211], v[4:7]
	v_mfma_f32_16x16x32_bf16 v[0:3], v[160:163], v[208:211], v[0:3]
	s_setprio 0
	s_setprio 2
	v_mfma_f32_16x16x32_bf16 v[28:31], v[156:159], v[188:191], v[28:31]
	v_mfma_f32_16x16x32_bf16 v[24:27], v[164:167], v[188:191], v[24:27]
	v_mfma_f32_16x16x32_bf16 v[20:23], v[156:159], v[196:199], v[20:23]
	v_mfma_f32_16x16x32_bf16 v[16:19], v[164:167], v[196:199], v[16:19]
	v_mfma_f32_16x16x32_bf16 v[12:15], v[156:159], v[204:207], v[12:15]
	v_mfma_f32_16x16x32_bf16 v[8:11], v[164:167], v[204:207], v[8:11]
	v_mfma_f32_16x16x32_bf16 v[4:7], v[156:159], v[212:215], v[4:7]
	v_mfma_f32_16x16x32_bf16 v[0:3], v[164:167], v[212:215], v[0:3]
	s_setprio 0
	s_setprio 2
	v_mfma_f32_16x16x32_bf16 v[92:95], v[168:171], v[184:187], v[92:95]
	v_mfma_f32_16x16x32_bf16 v[88:91], v[176:179], v[184:187], v[88:91]
	v_mfma_f32_16x16x32_bf16 v[84:87], v[168:171], v[192:195], v[84:87]
	v_mfma_f32_16x16x32_bf16 v[80:83], v[176:179], v[192:195], v[80:83]
	v_mfma_f32_16x16x32_bf16 v[60:63], v[168:171], v[200:203], v[60:63]
	v_mfma_f32_16x16x32_bf16 v[48:51], v[176:179], v[200:203], v[48:51]
	v_mfma_f32_16x16x32_bf16 v[36:39], v[168:171], v[208:211], v[36:39]
	v_mfma_f32_16x16x32_bf16 v[32:35], v[176:179], v[208:211], v[32:35]
	s_setprio 0
	s_setprio 2
	v_mfma_f32_16x16x32_bf16 v[92:95], v[172:175], v[188:191], v[92:95]
	v_mfma_f32_16x16x32_bf16 v[88:91], v[180:183], v[188:191], v[88:91]
	v_mfma_f32_16x16x32_bf16 v[84:87], v[172:175], v[196:199], v[84:87]
	v_mfma_f32_16x16x32_bf16 v[80:83], v[180:183], v[196:199], v[80:83]
	v_mfma_f32_16x16x32_bf16 v[60:63], v[172:175], v[204:207], v[60:63]
	v_mfma_f32_16x16x32_bf16 v[48:51], v[180:183], v[204:207], v[48:51]
	v_mfma_f32_16x16x32_bf16 v[36:39], v[172:175], v[212:215], v[36:39]
	s_setprio 3
	s_barrier
	v_mfma_f32_16x16x32_bf16 v[32:35], v[180:183], v[212:215], v[32:35]
	s_setprio 0
	s_add_i32 s87, s87, 2
	s_add_u32 s58, s58, 0x100
	s_addc_u32 s59, s59, 0
	s_add_u32 s85, s85, 0x100
	s_addc_u32 s86, s86, 0
	s_cmp_gt_u32 s87, 61
	s_cbranch_scc0 .LBB0_706
	s_and_b64 vcc, exec, s[14:15]
	s_cbranch_vccz .LBB0_709
	s_barrier

; #define PG8_STAGE(bufoff, gbase, voff) do { _Pragma("unroll") for (int _i = 0; _i < 2; ++_i) \
;         __builtin_amdgcn_global_load_lds((const unsigned*)((const char*)(gbase) + (voff)[_i]), (PG8_LAS unsigned*)(lds + (bufoff) + ldsw + _i * 8192), 16, 0, 0); } while (0)
; #define PG8_LDA(dst, b, h) do { _Pragma("unroll") for (int m = 0; m < 4; ++m) _Pragma("unroll") for (int k = 0; k < 2; ++k) dst[m][k] = *(const PG8_LAS bf16x8*)(lds + PG8_SA(b, h) + aoff + m * 2048 + k * 1024); } while (0)
; #define PG8_LDB(dst, b, h) do { _Pragma("unroll") for (int n = 0; n < 2; ++n) _Pragma("unroll") for (int k = 0; k < 2; ++k) dst[n][k] = *(const PG8_LAS bf16x8*)(lds + PG8_SB(b, h) + boff + n * 2048 + k * 1024); } while (0)
; #define PG8_MMA(ai, bj, At, Bt) do { __builtin_amdgcn_s_setprio(1); _Pragma("unroll") for (int m = 0; m < 4; ++m) _Pragma("unroll") for (int n = 0; n < 2; ++n) _Pragma("unroll") for (int k = 0; k < 2; ++k) \
;         acc[ai][bj][m][n] = __builtin_amdgcn_mfma_f32_16x16x32_bf16(Bt[n][k], At[m][k], acc[ai][bj][m][n], 0, 0, 0); __builtin_amdgcn_s_setprio(0); } while (0)
; #define PG8_WAIT_V(n) asm volatile("s_waitcnt vmcnt(" #n ")" ::: "memory")
; #define PG8_BAR __builtin_amdgcn_s_barrier()
; template <class Epi, class Sched, bool ALIGN_EPI = false, bool SP2 = false>
; __device__ __forceinline__ void gemm_phase(PG8_LAS unsigned char* lds, const Gemm g, const Sched& S, const Epi& E, const int wv  ) {
;     ...
;         for (int t = 0; t < nt; t += 2) {
;             const bool last = (t == nt - 2);
;             const char* a1 = cA + (size_t)(t + 1) * kstep;
;             const char* a2 = last ? nA : cA + (size_t)(t + 2) * kstep; const char* b2 = last ? nB : cB + (size_t)(t + 2) * kstep;
;             const char* a3 = a2 + kstep; const char* b3 = b2 + kstep;
;             if (last && has_next) S.a_ready(nxt);
;             if constexpr (SP2) {
;             PG8_LDB(B0, 0, 0); PG8_LDB(B1, 0, 1); PG8_SCHED; PG8_LDA(At, 0, 0); PG8_STAGE(PG8_SA(1, 1), a1 + hstepA, voffA);
;             PG8_WAIT_V(8); PG8_WAIT_L(0); PG8_BAR; PG8_MMA(0, 0, At, B0); PG8_MMA(0, 1, At, B1); PG8_BAR; PG8_SCHED;
;             PG8_LDA(At, 0, 1); PG8_STAGE(PG8_SB(0, 0), b2, voffB); PG8_STAGE(PG8_SB(0, 1), b2 + hstepB, voffB); PG8_STAGE(PG8_SA(0, 0), a2, voffA);
;             PG8_WAIT_V(8); PG8_WAIT_L(0); PG8_BAR; PG8_MMA(1, 0, At, B0); PG8_MMA(1, 1, At, B1); PG8_BAR; PG8_SCHED;
.LBB0_850:
	ds_read_b128 v[146:149], v152
	ds_read_b128 v[156:159], v152 offset:1024
	ds_read_b128 v[160:163], v152 offset:2048
	ds_read_b128 v[164:167], v152 offset:3072
	ds_read_b128 v[168:171], v153
	ds_read_b128 v[172:175], v153 offset:1024
	ds_read_b128 v[176:179], v153 offset:2048
	ds_read_b128 v[180:183], v153 offset:3072
	s_add_u32 s60, s58, 0xfff00080
	s_addc_u32 s61, s59, -1
	s_cmp_eq_u32 s92, 60
	s_cselect_b32 s63, s51, s61
	s_cselect_b32 s62, s86, s60
	s_cselect_b32 s61, s49, s91
	s_cselect_b32 s60, s87, s90
	v_lshl_add_u64 v[216:217], s[58:59], 0, v[138:139]
	s_add_i32 m0, s71, 0xc000
	ds_read_b128 v[184:187], v154
	ds_read_b128 v[188:191], v154 offset:1024
	ds_read_b128 v[192:195], v154 offset:2048
	ds_read_b128 v[196:199], v154 offset:3072
	ds_read_b128 v[200:203], v154 offset:4096
	ds_read_b128 v[204:207], v154 offset:5120
	ds_read_b128 v[208:211], v154 offset:6144
	ds_read_b128 v[212:215], v154 offset:7168
	global_load_lds_dwordx4 v[216:217], off
	v_lshl_add_u64 v[216:217], s[58:59], 0, v[140:141]
	s_add_i32 m0, s71, 0xe000
	s_nop 0
	global_load_lds_dwordx4 v[216:217], off
	s_waitcnt vmcnt(8)
	s_waitcnt lgkmcnt(0)
	s_barrier
	s_setprio 2
	s_waitcnt lgkmcnt(0)
	v_mfma_f32_16x16x32_bf16 v[76:79], v[146:149], v[184:187], v[76:79]
	v_mfma_f32_16x16x32_bf16 v[72:75], v[160:163], v[184:187], v[72:75]
	v_mfma_f32_16x16x32_bf16 v[68:71], v[146:149], v[192:195], v[68:71]
	v_mfma_f32_16x16x32_bf16 v[64:67], v[160:163], v[192:195], v[64:67]
	v_mfma_f32_16x16x32_bf16 v[56:59], v[146:149], v[200:203], v[56:59]
	v_mfma_f32_16x16x32_bf16 v[52:55], v[160:163], v[200:203], v[52:55]
	v_mfma_f32_16x16x32_bf16 v[44:47], v[146:149], v[208:211], v[44:47]
	v_mfma_f32_16x16x32_bf16 v[40:43], v[160:163], v[208:211], v[40:43]
	s_setprio 0
	s_setprio 2
	v_mfma_f32_16x16x32_bf16 v[76:79], v[156:159], v[188:191], v[76:79]
	v_mfma_f32_16x16x32_bf16 v[72:75], v[164:167], v[188:191], v[72:75]
	v_mfma_f32_16x16x32_bf16 v[68:71], v[156:159], v[196:199], v[68:71]
	v_mfma_f32_16x16x32_bf16 v[64:67], v[164:167], v[196:199], v[64:67]
	v_mfma_f32_16x16x32_bf16 v[56:59], v[156:159], v[204:207], v[56:59]
	v_mfma_f32_16x16x32_bf16 v[52:55], v[164:167], v[204:207], v[52:55]
	v_mfma_f32_16x16x32_bf16 v[44:47], v[156:159], v[212:215], v[44:47]
	v_mfma_f32_16x16x32_bf16 v[40:43], v[164:167], v[212:215], v[40:43]
	s_setprio 0
	s_setprio 2
	v_mfma_f32_16x16x32_bf16 v[124:127], v[168:171], v[184:187], v[124:127]
	v_mfma_f32_16x16x32_bf16 v[120:123], v[176:179], v[184:187], v[120:123]
	v_mfma_f32_16x16x32_bf16 v[116:119], v[168:171], v[192:195], v[116:119]
	v_mfma_f32_16x16x32_bf16 v[112:115], v[176:179], v[192:195], v[112:115]
	v_mfma_f32_16x16x32_bf16 v[108:111], v[168:171], v[200:203], v[108:111]
	v_mfma_f32_16x16x32_bf16 v[104:107], v[176:179], v[200:203], v[104:107]
	v_mfma_f32_16x16x32_bf16 v[100:103], v[168:171], v[208:211], v[100:103]
	v_mfma_f32_16x16x32_bf16 v[96:99], v[176:179], v[208:211], v[96:99]
	s_setprio 0
	s_setprio 2
	v_mfma_f32_16x16x32_bf16 v[124:127], v[172:175], v[188:191], v[124:127]
	v_mfma_f32_16x16x32_bf16 v[120:123], v[180:183], v[188:191], v[120:123]
	v_mfma_f32_16x16x32_bf16 v[116:119], v[172:175], v[196:199], v[116:119]
	v_mfma_f32_16x16x32_bf16 v[112:115], v[180:183], v[196:199], v[112:115]
	v_mfma_f32_16x16x32_bf16 v[108:111], v[172:175], v[204:207], v[108:111]
	v_mfma_f32_16x16x32_bf16 v[104:107], v[180:183], v[204:207], v[104:107]
	v_mfma_f32_16x16x32_bf16 v[100:103], v[172:175], v[212:215], v[100:103]
	s_setprio 3
	s_barrier
	v_mfma_f32_16x16x32_bf16 v[96:99], v[180:183], v[212:215], v[96:99]
	s_setprio 0
	s_add_i32 s93, s80, s70
	v_lshl_add_u64 v[216:217], s[60:61], 0, v[130:131]
	s_mov_b32 m0, s93
	ds_read_b128 v[184:187], v154 offset:16384
	ds_read_b128 v[188:191], v154 offset:17408
	ds_read_b128 v[192:195], v154 offset:18432
	ds_read_b128 v[196:199], v154 offset:19456
	ds_read_b128 v[200:203], v154 offset:20480
	ds_read_b128 v[204:207], v154 offset:21504
	ds_read_b128 v[208:211], v154 offset:22528
	ds_read_b128 v[212:215], v154 offset:23552
	global_load_lds_dwordx4 v[216:217], off
	s_add_i32 m0, s93, 0x2000
	s_add_u32 s94, s60, 0x100000
	v_lshl_add_u64 v[218:219], s[60:61], 0, v[134:135]
	s_addc_u32 s95, s61, 0
	s_add_i32 s93, s81, s70
	global_load_lds_dwordx4 v[218:219], off
	v_lshl_add_u64 v[220:221], s[94:95], 0, v[130:131]
	s_mov_b32 m0, s93
	v_lshl_add_u64 v[222:223], s[62:63], 0, v[132:133]
	global_load_lds_dwordx4 v[220:221], off
	v_lshl_add_u64 v[220:221], s[94:95], 0, v[134:135]
	s_add_i32 m0, s93, 0x2000
	s_nop 0
	global_load_lds_dwordx4 v[220:221], off
	v_lshl_add_u64 v[220:221], s[62:63], 0, v[128:129]
	s_mov_b32 m0, s71
	s_nop 0
	global_load_lds_dwordx4 v[220:221], off
	s_mov_b32 m0, s72
	s_nop 0
	global_load_lds_dwordx4 v[222:223], off
	s_waitcnt vmcnt(8)
	s_waitcnt lgkmcnt(0)
	s_barrier
; #define PG8_STAGE(bufoff, gbase, voff) do { _Pragma("unroll") for (int _i = 0; _i < 2; ++_i) \
;         __builtin_amdgcn_global_load_lds((const unsigned*)((const char*)(gbase) + (voff)[_i]), (PG8_LAS unsigned*)(lds + (bufoff) + ldsw + _i * 8192), 16, 0, 0); } while (0)
; #define PG8_LDA(dst, b, h) do { _Pragma("unroll") for (int m = 0; m < 4; ++m) _Pragma("unroll") for (int k = 0; k < 2; ++k) dst[m][k] = *(const PG8_LAS bf16x8*)(lds + PG8_SA(b, h) + aoff + m * 2048 + k * 1024); } while (0)
; #define PG8_LDB(dst, b, h) do { _Pragma("unroll") for (int n = 0; n < 2; ++n) _Pragma("unroll") for (int k = 0; k < 2; ++k) dst[n][k] = *(const PG8_LAS bf16x8*)(lds + PG8_SB(b, h) + boff + n * 2048 + k * 1024); } while (0)
; #define PG8_MMA(ai, bj, At, Bt) do { __builtin_amdgcn_s_setprio(1); _Pragma("unroll") for (int m = 0; m < 4; ++m) _Pragma("unroll") for (int n = 0; n < 2; ++n) _Pragma("unroll") for (int k = 0; k < 2; ++k) \
;         acc[ai][bj][m][n] = __builtin_amdgcn_mfma_f32_16x16x32_bf16(Bt[n][k], At[m][k], acc[ai][bj][m][n], 0, 0, 0); __builtin_amdgcn_s_setprio(0); } while (0)
; #define PG8_WAIT_V(n) asm volatile("s_waitcnt vmcnt(" #n ")" ::: "memory")
; #define PG8_WAIT_L(n) asm volatile("s_waitcnt lgkmcnt(" #n ")" ::: "memory")
; #define PG8_BAR __builtin_amdgcn_s_barrier()
; #define PG8_SCHED __builtin_amdgcn_sched_barrier(0)
; template <class Epi, class Sched, bool ALIGN_EPI = false, bool SP2 = false>
; __device__ __forceinline__ void gemm_phase(PG8_LAS unsigned char* lds, const Gemm g, const Sched& S, const Epi& E, const int wv  ) {
;     ...
;             PG8_WAIT_V(8); PG8_WAIT_L(0); PG8_BAR; PG8_MMA(1, 0, At, B0); PG8_MMA(1, 1, At, B1); PG8_BAR; PG8_SCHED;
;             PG8_LDB(B0, 1, 0); PG8_LDB(B1, 1, 1); PG8_SCHED; PG8_LDA(At, 1, 0); PG8_STAGE(PG8_SA(0, 1), a2 + hstepA, voffA);
;             PG8_WAIT_V(8); PG8_WAIT_L(0); PG8_BAR; PG8_MMA(0, 0, At, B0); PG8_MMA(0, 1, At, B1); PG8_BAR; PG8_SCHED;
	s_setprio 2
	s_waitcnt lgkmcnt(0)
	v_mfma_f32_16x16x32_bf16 v[28:31], v[146:149], v[184:187], v[28:31]
	v_mfma_f32_16x16x32_bf16 v[24:27], v[160:163], v[184:187], v[24:27]
	v_mfma_f32_16x16x32_bf16 v[20:23], v[146:149], v[192:195], v[20:23]
	v_mfma_f32_16x16x32_bf16 v[16:19], v[160:163], v[192:195], v[16:19]
	v_mfma_f32_16x16x32_bf16 v[12:15], v[146:149], v[200:203], v[12:15]
	v_mfma_f32_16x16x32_bf16 v[8:11], v[160:163], v[200:203], v[8:11]
	v_mfma_f32_16x16x32_bf16 v[4:7], v[146:149], v[208:211], v[4:7]
	v_mfma_f32_16x16x32_bf16 v[0:3], v[160:163], v[208:211], v[0:3]
	s_setprio 0
	s_setprio 2
	v_mfma_f32_16x16x32_bf16 v[28:31], v[156:159], v[188:191], v[28:31]
	v_mfma_f32_16x16x32_bf16 v[24:27], v[164:167], v[188:191], v[24:27]
	v_mfma_f32_16x16x32_bf16 v[20:23], v[156:159], v[196:199], v[20:23]
	v_mfma_f32_16x16x32_bf16 v[16:19], v[164:167], v[196:199], v[16:19]
	v_mfma_f32_16x16x32_bf16 v[12:15], v[156:159], v[204:207], v[12:15]
	v_mfma_f32_16x16x32_bf16 v[8:11], v[164:167], v[204:207], v[8:11]
	v_mfma_f32_16x16x32_bf16 v[4:7], v[156:159], v[212:215], v[4:7]
	v_mfma_f32_16x16x32_bf16 v[0:3], v[164:167], v[212:215], v[0:3]
	s_setprio 0
	s_setprio 2
	v_mfma_f32_16x16x32_bf16 v[92:95], v[168:171], v[184:187], v[92:95]
	v_mfma_f32_16x16x32_bf16 v[88:91], v[176:179], v[184:187], v[88:91]
	v_mfma_f32_16x16x32_bf16 v[84:87], v[168:171], v[192:195], v[84:87]
	v_mfma_f32_16x16x32_bf16 v[80:83], v[176:179], v[192:195], v[80:83]
	v_mfma_f32_16x16x32_bf16 v[60:63], v[168:171], v[200:203], v[60:63]
	v_mfma_f32_16x16x32_bf16 v[48:51], v[176:179], v[200:203], v[48:51]
	v_mfma_f32_16x16x32_bf16 v[36:39], v[168:171], v[208:211], v[36:39]
	v_mfma_f32_16x16x32_bf16 v[32:35], v[176:179], v[208:211], v[32:35]
	s_setprio 0
	s_setprio 2
	v_mfma_f32_16x16x32_bf16 v[92:95], v[172:175], v[188:191], v[92:95]
	v_mfma_f32_16x16x32_bf16 v[88:91], v[180:183], v[188:191], v[88:91]
	v_mfma_f32_16x16x32_bf16 v[84:87], v[172:175], v[196:199], v[84:87]
	v_mfma_f32_16x16x32_bf16 v[80:83], v[180:183], v[196:199], v[80:83]
	v_mfma_f32_16x16x32_bf16 v[60:63], v[172:175], v[204:207], v[60:63]
	v_mfma_f32_16x16x32_bf16 v[48:51], v[180:183], v[204:207], v[48:51]
	v_mfma_f32_16x16x32_bf16 v[36:39], v[172:175], v[212:215], v[36:39]
	s_setprio 3
	s_barrier
	v_mfma_f32_16x16x32_bf16 v[32:35], v[180:183], v[212:215], v[32:35]
	s_setprio 0
	s_add_i32 s93, 0, 0x18000
	v_add_u32_e32 v155, s93, v150
	s_add_i32 s94, 0, 0x1c000
	ds_read_b128 v[146:149], v155
	ds_read_b128 v[156:159], v155 offset:1024
	ds_read_b128 v[160:163], v155 offset:2048
	ds_read_b128 v[164:167], v155 offset:3072
	v_add_u32_e32 v155, s94, v150
	ds_read_b128 v[168:171], v155
	ds_read_b128 v[172:175], v155 offset:1024
	ds_read_b128 v[176:179], v155 offset:2048
	ds_read_b128 v[180:183], v155 offset:3072
	s_add_u32 s62, s62, 0x100000
	s_addc_u32 s63, s63, 0
	s_mov_b32 m0, s73
	v_lshl_add_u64 v[224:225], s[62:63], 0, v[128:129]
	ds_read_b128 v[184:187], v154 offset:32768
	ds_read_b128 v[188:191], v154 offset:33792
	ds_read_b128 v[192:195], v154 offset:34816
	ds_read_b128 v[196:199], v154 offset:35840
	ds_read_b128 v[200:203], v154 offset:36864
	ds_read_b128 v[204:207], v154 offset:37888
	ds_read_b128 v[208:211], v154 offset:38912
	ds_read_b128 v[212:215], v154 offset:39936
	global_load_lds_dwordx4 v[224:225], off
	v_lshl_add_u64 v[224:225], s[62:63], 0, v[132:133]
	s_mov_b32 m0, s74
	s_nop 0
	global_load_lds_dwordx4 v[224:225], off
	s_waitcnt vmcnt(8)
	s_waitcnt lgkmcnt(0)
	s_barrier
	s_setprio 2
	s_waitcnt lgkmcnt(0)
	v_mfma_f32_16x16x32_bf16 v[76:79], v[146:149], v[184:187], v[76:79]
	v_mfma_f32_16x16x32_bf16 v[72:75], v[160:163], v[184:187], v[72:75]
	v_mfma_f32_16x16x32_bf16 v[68:71], v[146:149], v[192:195], v[68:71]
	v_mfma_f32_16x16x32_bf16 v[64:67], v[160:163], v[192:195], v[64:67]
	v_mfma_f32_16x16x32_bf16 v[56:59], v[146:149], v[200:203], v[56:59]
	v_mfma_f32_16x16x32_bf16 v[52:55], v[160:163], v[200:203], v[52:55]
	v_mfma_f32_16x16x32_bf16 v[44:47], v[146:149], v[208:211], v[44:47]
	v_mfma_f32_16x16x32_bf16 v[40:43], v[160:163], v[208:211], v[40:43]
	s_setprio 0
	s_setprio 2
	v_mfma_f32_16x16x32_bf16 v[76:79], v[156:159], v[188:191], v[76:79]
	v_mfma_f32_16x16x32_bf16 v[72:75], v[164:167], v[188:191], v[72:75]
	v_mfma_f32_16x16x32_bf16 v[68:71], v[156:159], v[196:199], v[68:71]
	v_mfma_f32_16x16x32_bf16 v[64:67], v[164:167], v[196:199], v[64:67]
	v_mfma_f32_16x16x32_bf16 v[56:59], v[156:159], v[204:207], v[56:59]
	v_mfma_f32_16x16x32_bf16 v[52:55], v[164:167], v[204:207], v[52:55]
	v_mfma_f32_16x16x32_bf16 v[44:47], v[156:159], v[212:215], v[44:47]
	v_mfma_f32_16x16x32_bf16 v[40:43], v[164:167], v[212:215], v[40:43]
	s_setprio 0
	s_setprio 2
	v_mfma_f32_16x16x32_bf16 v[124:127], v[168:171], v[184:187], v[124:127]
	v_mfma_f32_16x16x32_bf16 v[120:123], v[176:179], v[184:187], v[120:123]
	v_mfma_f32_16x16x32_bf16 v[116:119], v[168:171], v[192:195], v[116:119]
	v_mfma_f32_16x16x32_bf16 v[112:115], v[176:179], v[192:195], v[112:115]
	v_mfma_f32_16x16x32_bf16 v[108:111], v[168:171], v[200:203], v[108:111]
	v_mfma_f32_16x16x32_bf16 v[104:107], v[176:179], v[200:203], v[104:107]
	v_mfma_f32_16x16x32_bf16 v[100:103], v[168:171], v[208:211], v[100:103]
	v_mfma_f32_16x16x32_bf16 v[96:99], v[176:179], v[208:211], v[96:99]
	s_setprio 0
	s_setprio 2
	v_mfma_f32_16x16x32_bf16 v[124:127], v[172:175], v[188:191], v[124:127]
	v_mfma_f32_16x16x32_bf16 v[120:123], v[180:183], v[188:191], v[120:123]
	v_mfma_f32_16x16x32_bf16 v[116:119], v[172:175], v[196:199], v[116:119]
	v_mfma_f32_16x16x32_bf16 v[112:115], v[180:183], v[196:199], v[112:115]
	v_mfma_f32_16x16x32_bf16 v[108:111], v[172:175], v[204:207], v[108:111]
	v_mfma_f32_16x16x32_bf16 v[104:107], v[180:183], v[204:207], v[104:107]
	v_mfma_f32_16x16x32_bf16 v[100:103], v[172:175], v[212:215], v[100:103]
	s_setprio 3
	s_barrier
; #define PG8_STAGE(bufoff, gbase, voff) do { _Pragma("unroll") for (int _i = 0; _i < 2; ++_i) \
;         __builtin_amdgcn_global_load_lds((const unsigned*)((const char*)(gbase) + (voff)[_i]), (PG8_LAS unsigned*)(lds + (bufoff) + ldsw + _i * 8192), 16, 0, 0); } while (0)
; #define PG8_LDA(dst, b, h) do { _Pragma("unroll") for (int m = 0; m < 4; ++m) _Pragma("unroll") for (int k = 0; k < 2; ++k) dst[m][k] = *(const PG8_LAS bf16x8*)(lds + PG8_SA(b, h) + aoff + m * 2048 + k * 1024); } while (0)
; #define PG8_MMA(ai, bj, At, Bt) do { __builtin_amdgcn_s_setprio(1); _Pragma("unroll") for (int m = 0; m < 4; ++m) _Pragma("unroll") for (int n = 0; n < 2; ++n) _Pragma("unroll") for (int k = 0; k < 2; ++k) \
;         acc[ai][bj][m][n] = __builtin_amdgcn_mfma_f32_16x16x32_bf16(Bt[n][k], At[m][k], acc[ai][bj][m][n], 0, 0, 0); __builtin_amdgcn_s_setprio(0); } while (0)
; #define PG8_WAIT_V(n) asm volatile("s_waitcnt vmcnt(" #n ")" ::: "memory")
; #define PG8_WAIT_L(n) asm volatile("s_waitcnt lgkmcnt(" #n ")" ::: "memory")
; #define PG8_BAR __builtin_amdgcn_s_barrier()
; #define PG8_SCHED __builtin_amdgcn_sched_barrier(0)
; template <class Epi, class Sched, bool ALIGN_EPI = false, bool SP2 = false>
; __device__ __forceinline__ void gemm_phase(PG8_LAS unsigned char* lds, const Gemm g, const Sched& S, const Epi& E, const int wv  ) {
;     ...
;             PG8_WAIT_V(8); PG8_WAIT_L(0); PG8_BAR; PG8_MMA(0, 0, At, B0); PG8_MMA(0, 1, At, B1); PG8_BAR; PG8_SCHED;
;             PG8_LDA(At, 1, 1); PG8_STAGE(PG8_SB(1, 0), b3, voffB); PG8_STAGE(PG8_SB(1, 1), b3 + hstepB, voffB); PG8_STAGE(PG8_SA(1, 0), a3, voffA);
;             PG8_WAIT_V(8); PG8_WAIT_L(0); PG8_BAR; PG8_MMA(1, 0, At, B0); PG8_MMA(1, 1, At, B1); PG8_BAR; PG8_SCHED;
	v_mfma_f32_16x16x32_bf16 v[96:99], v[180:183], v[212:215], v[96:99]
	s_setprio 0
	s_add_i32 s62, s93, s70
	v_lshl_add_u64 v[216:217], v[216:217], 0, s[10:11]
	s_mov_b32 m0, s62
	ds_read_b128 v[184:187], v154 offset:49152
	ds_read_b128 v[188:191], v154 offset:50176
	ds_read_b128 v[192:195], v154 offset:51200
	ds_read_b128 v[196:199], v154 offset:52224
	ds_read_b128 v[200:203], v154 offset:53248
	ds_read_b128 v[204:207], v154 offset:54272
	ds_read_b128 v[208:211], v154 offset:55296
	ds_read_b128 v[212:215], v154 offset:56320
	global_load_lds_dwordx4 v[216:217], off
	s_add_i32 m0, s62, 0x2000
	s_add_u32 s60, s60, 0x100080
	v_lshl_add_u64 v[216:217], v[218:219], 0, s[10:11]
	s_addc_u32 s61, s61, 0
	s_add_i32 s62, s94, s70
	global_load_lds_dwordx4 v[216:217], off
	v_lshl_add_u64 v[216:217], s[60:61], 0, v[130:131]
	s_mov_b32 m0, s62
	s_nop 0
	global_load_lds_dwordx4 v[216:217], off
	v_lshl_add_u64 v[216:217], s[60:61], 0, v[134:135]
	s_add_i32 m0, s62, 0x2000
	s_nop 0
	global_load_lds_dwordx4 v[216:217], off
	v_lshl_add_u64 v[216:217], v[220:221], 0, s[10:11]
	s_mov_b32 m0, s77
	s_nop 0
	global_load_lds_dwordx4 v[216:217], off
	v_lshl_add_u64 v[216:217], v[222:223], 0, s[10:11]
	s_mov_b32 m0, s78
	s_nop 0
	global_load_lds_dwordx4 v[216:217], off
	s_waitcnt vmcnt(8)
	s_waitcnt lgkmcnt(0)
	s_barrier
	s_setprio 2
	s_waitcnt lgkmcnt(0)
	v_mfma_f32_16x16x32_bf16 v[28:31], v[146:149], v[184:187], v[28:31]
	v_mfma_f32_16x16x32_bf16 v[24:27], v[160:163], v[184:187], v[24:27]
	v_mfma_f32_16x16x32_bf16 v[20:23], v[146:149], v[192:195], v[20:23]
	v_mfma_f32_16x16x32_bf16 v[16:19], v[160:163], v[192:195], v[16:19]
	v_mfma_f32_16x16x32_bf16 v[12:15], v[146:149], v[200:203], v[12:15]
	v_mfma_f32_16x16x32_bf16 v[8:11], v[160:163], v[200:203], v[8:11]
	v_mfma_f32_16x16x32_bf16 v[4:7], v[146:149], v[208:211], v[4:7]
	v_mfma_f32_16x16x32_bf16 v[0:3], v[160:163], v[208:211], v[0:3]
	s_setprio 0
	s_setprio 2
	v_mfma_f32_16x16x32_bf16 v[28:31], v[156:159], v[188:191], v[28:31]
	v_mfma_f32_16x16x32_bf16 v[24:27], v[164:167], v[188:191], v[24:27]
	v_mfma_f32_16x16x32_bf16 v[20:23], v[156:159], v[196:199], v[20:23]
	v_mfma_f32_16x16x32_bf16 v[16:19], v[164:167], v[196:199], v[16:19]
	v_mfma_f32_16x16x32_bf16 v[12:15], v[156:159], v[204:207], v[12:15]
	v_mfma_f32_16x16x32_bf16 v[8:11], v[164:167], v[204:207], v[8:11]
	v_mfma_f32_16x16x32_bf16 v[4:7], v[156:159], v[212:215], v[4:7]
	v_mfma_f32_16x16x32_bf16 v[0:3], v[164:167], v[212:215], v[0:3]
	s_setprio 0
	s_setprio 2
	v_mfma_f32_16x16x32_bf16 v[92:95], v[168:171], v[184:187], v[92:95]
	v_mfma_f32_16x16x32_bf16 v[88:91], v[176:179], v[184:187], v[88:91]
	v_mfma_f32_16x16x32_bf16 v[84:87], v[168:171], v[192:195], v[84:87]
	v_mfma_f32_16x16x32_bf16 v[80:83], v[176:179], v[192:195], v[80:83]
	v_mfma_f32_16x16x32_bf16 v[60:63], v[168:171], v[200:203], v[60:63]
	v_mfma_f32_16x16x32_bf16 v[48:51], v[176:179], v[200:203], v[48:51]
	v_mfma_f32_16x16x32_bf16 v[36:39], v[168:171], v[208:211], v[36:39]
	v_mfma_f32_16x16x32_bf16 v[32:35], v[176:179], v[208:211], v[32:35]
	s_setprio 0
	s_setprio 2
	v_mfma_f32_16x16x32_bf16 v[92:95], v[172:175], v[188:191], v[92:95]
	v_mfma_f32_16x16x32_bf16 v[88:91], v[180:183], v[188:191], v[88:91]
	v_mfma_f32_16x16x32_bf16 v[84:87], v[172:175], v[196:199], v[84:87]
	v_mfma_f32_16x16x32_bf16 v[80:83], v[180:183], v[196:199], v[80:83]
	v_mfma_f32_16x16x32_bf16 v[60:63], v[172:175], v[204:207], v[60:63]
	v_mfma_f32_16x16x32_bf16 v[48:51], v[180:183], v[204:207], v[48:51]
	v_mfma_f32_16x16x32_bf16 v[36:39], v[172:175], v[212:215], v[36:39]
	s_setprio 3
	s_barrier
	v_mfma_f32_16x16x32_bf16 v[32:35], v[180:183], v[212:215], v[32:35]
	s_setprio 0
	s_add_i32 s92, s92, 2
	s_add_u32 s58, s58, 0x100
	s_addc_u32 s59, s59, 0
	s_add_u32 s90, s90, 0x100
	s_addc_u32 s91, s91, 0
	s_cmp_gt_u32 s92, 61
	s_cbranch_scc0 .LBB0_850
	s_and_b64 vcc, exec, s[12:13]
	s_cbranch_vccz .LBB0_853
	s_barrier

; #define PG8_STAGE(bufoff, gbase, voff) do { _Pragma("unroll") for (int _i = 0; _i < 2; ++_i) \
;         __builtin_amdgcn_global_load_lds((const unsigned*)((const char*)(gbase) + (voff)[_i]), (PG8_LAS unsigned*)(lds + (bufoff) + ldsw + _i * 8192), 16, 0, 0); } while (0)
; #define PG8_LDA(dst, b, h) do { _Pragma("unroll") for (int m = 0; m < 4; ++m) _Pragma("unroll") for (int k = 0; k < 2; ++k) dst[m][k] = *(const PG8_LAS bf16x8*)(lds + PG8_SA(b, h) + aoff + m * 2048 + k * 1024); } while (0)
; #define PG8_LDB(dst, b, h) do { _Pragma("unroll") for (int n = 0; n < 2; ++n) _Pragma("unroll") for (int k = 0; k < 2; ++k) dst[n][k] = *(const PG8_LAS bf16x8*)(lds + PG8_SB(b, h) + boff + n * 2048 + k * 1024); } while (0)
; #define PG8_MMA(ai, bj, At, Bt) do { __builtin_amdgcn_s_setprio(1); _Pragma("unroll") for (int m = 0; m < 4; ++m) _Pragma("unroll") for (int n = 0; n < 2; ++n) _Pragma("unroll") for (int k = 0; k < 2; ++k) \
;         acc[ai][bj][m][n] = __builtin_amdgcn_mfma_f32_16x16x32_bf16(Bt[n][k], At[m][k], acc[ai][bj][m][n], 0, 0, 0); __builtin_amdgcn_s_setprio(0); } while (0)
; #define PG8_WAIT_V(n) asm volatile("s_waitcnt vmcnt(" #n ")" ::: "memory")
; #define PG8_BAR __builtin_amdgcn_s_barrier()
; template <class Epi, class Sched, bool ALIGN_EPI = false, bool SP2 = false>
; __device__ __forceinline__ void gemm_phase(PG8_LAS unsigned char* lds, const Gemm g, const Sched& S, const Epi& E, const int wv  ) {
;     ...
;         for (int t = 0; t < nt; t += 2) {
;             const bool last = (t == nt - 2);
;             const char* a1 = cA + (size_t)(t + 1) * kstep;
;             const char* a2 = last ? nA : cA + (size_t)(t + 2) * kstep; const char* b2 = last ? nB : cB + (size_t)(t + 2) * kstep;
;             const char* a3 = a2 + kstep; const char* b3 = b2 + kstep;
;             if (last && has_next) S.a_ready(nxt);
;             if constexpr (SP2) {
;             PG8_LDB(B0, 0, 0); PG8_LDB(B1, 0, 1); PG8_SCHED; PG8_LDA(At, 0, 0); PG8_STAGE(PG8_SA(1, 1), a1 + hstepA, voffA);
;             PG8_WAIT_V(8); PG8_WAIT_L(0); PG8_BAR; PG8_MMA(0, 0, At, B0); PG8_MMA(0, 1, At, B1); PG8_BAR; PG8_SCHED;
;             PG8_LDA(At, 0, 1); PG8_STAGE(PG8_SB(0, 0), b2, voffB); PG8_STAGE(PG8_SB(0, 1), b2 + hstepB, voffB); PG8_STAGE(PG8_SA(0, 0), a2, voffA);
;             PG8_WAIT_V(8); PG8_WAIT_L(0); PG8_BAR; PG8_MMA(1, 0, At, B0); PG8_MMA(1, 1, At, B1); PG8_BAR; PG8_SCHED;
.LBB0_871:
	ds_read_b128 v[142:145], v148
	ds_read_b128 v[152:155], v148 offset:1024
	ds_read_b128 v[156:159], v148 offset:2048
	ds_read_b128 v[160:163], v148 offset:3072
	ds_read_b128 v[164:167], v149
	ds_read_b128 v[168:171], v149 offset:1024
	ds_read_b128 v[172:175], v149 offset:2048
	ds_read_b128 v[176:179], v149 offset:3072
	s_add_u32 s60, s58, 0xfff00080
	s_addc_u32 s61, s59, -1
	s_cmp_eq_u32 s96, 60
	s_cselect_b32 s63, s49, s61
	s_cselect_b32 s62, s92, s60
	s_cselect_b32 s61, s47, s95
	s_cselect_b32 s60, s93, s94
	v_lshl_add_u64 v[212:213], s[58:59], 0, v[138:139]
	s_add_i32 m0, s75, 0xc000
	ds_read_b128 v[180:183], v150
	ds_read_b128 v[184:187], v150 offset:1024
	ds_read_b128 v[188:191], v150 offset:2048
	ds_read_b128 v[192:195], v150 offset:3072
	ds_read_b128 v[196:199], v150 offset:4096
	ds_read_b128 v[200:203], v150 offset:5120
	ds_read_b128 v[204:207], v150 offset:6144
	ds_read_b128 v[208:211], v150 offset:7168
	global_load_lds_dwordx4 v[212:213], off
	v_lshl_add_u64 v[212:213], s[58:59], 0, v[140:141]
	s_add_i32 m0, s75, 0xe000
	s_nop 0
	global_load_lds_dwordx4 v[212:213], off
	s_waitcnt vmcnt(8)
	s_waitcnt lgkmcnt(0)
	s_barrier
	s_setprio 2
	s_waitcnt lgkmcnt(0)
	v_mfma_f32_16x16x32_bf16 v[76:79], v[142:145], v[180:183], v[76:79]
	v_mfma_f32_16x16x32_bf16 v[72:75], v[156:159], v[180:183], v[72:75]
	v_mfma_f32_16x16x32_bf16 v[68:71], v[142:145], v[188:191], v[68:71]
	v_mfma_f32_16x16x32_bf16 v[64:67], v[156:159], v[188:191], v[64:67]
	v_mfma_f32_16x16x32_bf16 v[56:59], v[142:145], v[196:199], v[56:59]
	v_mfma_f32_16x16x32_bf16 v[52:55], v[156:159], v[196:199], v[52:55]
	v_mfma_f32_16x16x32_bf16 v[44:47], v[142:145], v[204:207], v[44:47]
	v_mfma_f32_16x16x32_bf16 v[40:43], v[156:159], v[204:207], v[40:43]
	s_setprio 0
	s_setprio 2
	v_mfma_f32_16x16x32_bf16 v[76:79], v[152:155], v[184:187], v[76:79]
	v_mfma_f32_16x16x32_bf16 v[72:75], v[160:163], v[184:187], v[72:75]
	v_mfma_f32_16x16x32_bf16 v[68:71], v[152:155], v[192:195], v[68:71]
	v_mfma_f32_16x16x32_bf16 v[64:67], v[160:163], v[192:195], v[64:67]
	v_mfma_f32_16x16x32_bf16 v[56:59], v[152:155], v[200:203], v[56:59]
	v_mfma_f32_16x16x32_bf16 v[52:55], v[160:163], v[200:203], v[52:55]
	v_mfma_f32_16x16x32_bf16 v[44:47], v[152:155], v[208:211], v[44:47]
	v_mfma_f32_16x16x32_bf16 v[40:43], v[160:163], v[208:211], v[40:43]
	s_setprio 0
	s_setprio 2
	v_mfma_f32_16x16x32_bf16 v[124:127], v[164:167], v[180:183], v[124:127]
	v_mfma_f32_16x16x32_bf16 v[120:123], v[172:175], v[180:183], v[120:123]
	v_mfma_f32_16x16x32_bf16 v[116:119], v[164:167], v[188:191], v[116:119]
	v_mfma_f32_16x16x32_bf16 v[112:115], v[172:175], v[188:191], v[112:115]
	v_mfma_f32_16x16x32_bf16 v[108:111], v[164:167], v[196:199], v[108:111]
	v_mfma_f32_16x16x32_bf16 v[104:107], v[172:175], v[196:199], v[104:107]
	v_mfma_f32_16x16x32_bf16 v[100:103], v[164:167], v[204:207], v[100:103]
	v_mfma_f32_16x16x32_bf16 v[96:99], v[172:175], v[204:207], v[96:99]
	s_setprio 0
	s_setprio 2
	v_mfma_f32_16x16x32_bf16 v[124:127], v[168:171], v[184:187], v[124:127]
	v_mfma_f32_16x16x32_bf16 v[120:123], v[176:179], v[184:187], v[120:123]
	v_mfma_f32_16x16x32_bf16 v[116:119], v[168:171], v[192:195], v[116:119]
	v_mfma_f32_16x16x32_bf16 v[112:115], v[176:179], v[192:195], v[112:115]
	v_mfma_f32_16x16x32_bf16 v[108:111], v[168:171], v[200:203], v[108:111]
	v_mfma_f32_16x16x32_bf16 v[104:107], v[176:179], v[200:203], v[104:107]
	v_mfma_f32_16x16x32_bf16 v[100:103], v[168:171], v[208:211], v[100:103]
	s_setprio 3
	s_barrier
	v_mfma_f32_16x16x32_bf16 v[96:99], v[176:179], v[208:211], v[96:99]
	s_setprio 0
	s_add_i32 s97, s84, s73
	v_lshl_add_u64 v[212:213], s[60:61], 0, v[132:133]
	s_mov_b32 m0, s97
	ds_read_b128 v[180:183], v150 offset:16384
	ds_read_b128 v[184:187], v150 offset:17408
	ds_read_b128 v[188:191], v150 offset:18432
	ds_read_b128 v[192:195], v150 offset:19456
	ds_read_b128 v[196:199], v150 offset:20480
	ds_read_b128 v[200:203], v150 offset:21504
	ds_read_b128 v[204:207], v150 offset:22528
	ds_read_b128 v[208:211], v150 offset:23552
	global_load_lds_dwordx4 v[212:213], off
	s_add_i32 m0, s97, 0x2000
	s_add_u32 vcc_lo, s60, 0x100000
	v_lshl_add_u64 v[214:215], s[60:61], 0, v[128:129]
	s_addc_u32 vcc_hi, s61, 0
	s_add_i32 s97, s85, s73
	global_load_lds_dwordx4 v[214:215], off
	v_lshl_add_u64 v[216:217], vcc, 0, v[132:133]
	s_mov_b32 m0, s97
	v_lshl_add_u64 v[218:219], s[62:63], 0, v[130:131]
	global_load_lds_dwordx4 v[216:217], off
	v_lshl_add_u64 v[216:217], vcc, 0, v[128:129]
	s_add_i32 m0, s97, 0x2000
	s_nop 0
	global_load_lds_dwordx4 v[216:217], off
	v_lshl_add_u64 v[216:217], s[62:63], 0, v[134:135]
	s_mov_b32 m0, s75
	s_nop 0
	global_load_lds_dwordx4 v[216:217], off
	s_mov_b32 m0, s76
	s_nop 0
	global_load_lds_dwordx4 v[218:219], off
	s_waitcnt vmcnt(8)
	s_waitcnt lgkmcnt(0)
	s_barrier
; #define PG8_STAGE(bufoff, gbase, voff) do { _Pragma("unroll") for (int _i = 0; _i < 2; ++_i) \
;         __builtin_amdgcn_global_load_lds((const unsigned*)((const char*)(gbase) + (voff)[_i]), (PG8_LAS unsigned*)(lds + (bufoff) + ldsw + _i * 8192), 16, 0, 0); } while (0)
; #define PG8_LDA(dst, b, h) do { _Pragma("unroll") for (int m = 0; m < 4; ++m) _Pragma("unroll") for (int k = 0; k < 2; ++k) dst[m][k] = *(const PG8_LAS bf16x8*)(lds + PG8_SA(b, h) + aoff + m * 2048 + k * 1024); } while (0)
; #define PG8_LDB(dst, b, h) do { _Pragma("unroll") for (int n = 0; n < 2; ++n) _Pragma("unroll") for (int k = 0; k < 2; ++k) dst[n][k] = *(const PG8_LAS bf16x8*)(lds + PG8_SB(b, h) + boff + n * 2048 + k * 1024); } while (0)
; #define PG8_MMA(ai, bj, At, Bt) do { __builtin_amdgcn_s_setprio(1); _Pragma("unroll") for (int m = 0; m < 4; ++m) _Pragma("unroll") for (int n = 0; n < 2; ++n) _Pragma("unroll") for (int k = 0; k < 2; ++k) \
;         acc[ai][bj][m][n] = __builtin_amdgcn_mfma_f32_16x16x32_bf16(Bt[n][k], At[m][k], acc[ai][bj][m][n], 0, 0, 0); __builtin_amdgcn_s_setprio(0); } while (0)
; #define PG8_WAIT_V(n) asm volatile("s_waitcnt vmcnt(" #n ")" ::: "memory")
; #define PG8_WAIT_L(n) asm volatile("s_waitcnt lgkmcnt(" #n ")" ::: "memory")
; #define PG8_BAR __builtin_amdgcn_s_barrier()
; #define PG8_SCHED __builtin_amdgcn_sched_barrier(0)
; template <class Epi, class Sched, bool ALIGN_EPI = false, bool SP2 = false>
; __device__ __forceinline__ void gemm_phase(PG8_LAS unsigned char* lds, const Gemm g, const Sched& S, const Epi& E, const int wv  ) {
;     ...
;             PG8_WAIT_V(8); PG8_WAIT_L(0); PG8_BAR; PG8_MMA(1, 0, At, B0); PG8_MMA(1, 1, At, B1); PG8_BAR; PG8_SCHED;
;             PG8_LDB(B0, 1, 0); PG8_LDB(B1, 1, 1); PG8_SCHED; PG8_LDA(At, 1, 0); PG8_STAGE(PG8_SA(0, 1), a2 + hstepA, voffA);
;             PG8_WAIT_V(8); PG8_WAIT_L(0); PG8_BAR; PG8_MMA(0, 0, At, B0); PG8_MMA(0, 1, At, B1); PG8_BAR; PG8_SCHED;
	s_setprio 2
	s_waitcnt lgkmcnt(0)
	v_mfma_f32_16x16x32_bf16 v[28:31], v[142:145], v[180:183], v[28:31]
	v_mfma_f32_16x16x32_bf16 v[24:27], v[156:159], v[180:183], v[24:27]
	v_mfma_f32_16x16x32_bf16 v[20:23], v[142:145], v[188:191], v[20:23]
	v_mfma_f32_16x16x32_bf16 v[16:19], v[156:159], v[188:191], v[16:19]
	v_mfma_f32_16x16x32_bf16 v[12:15], v[142:145], v[196:199], v[12:15]
	v_mfma_f32_16x16x32_bf16 v[8:11], v[156:159], v[196:199], v[8:11]
	v_mfma_f32_16x16x32_bf16 v[4:7], v[142:145], v[204:207], v[4:7]
	v_mfma_f32_16x16x32_bf16 v[0:3], v[156:159], v[204:207], v[0:3]
	s_setprio 0
	s_setprio 2
	v_mfma_f32_16x16x32_bf16 v[28:31], v[152:155], v[184:187], v[28:31]
	v_mfma_f32_16x16x32_bf16 v[24:27], v[160:163], v[184:187], v[24:27]
	v_mfma_f32_16x16x32_bf16 v[20:23], v[152:155], v[192:195], v[20:23]
	v_mfma_f32_16x16x32_bf16 v[16:19], v[160:163], v[192:195], v[16:19]
	v_mfma_f32_16x16x32_bf16 v[12:15], v[152:155], v[200:203], v[12:15]
	v_mfma_f32_16x16x32_bf16 v[8:11], v[160:163], v[200:203], v[8:11]
	v_mfma_f32_16x16x32_bf16 v[4:7], v[152:155], v[208:211], v[4:7]
	v_mfma_f32_16x16x32_bf16 v[0:3], v[160:163], v[208:211], v[0:3]
	s_setprio 0
	s_setprio 2
	v_mfma_f32_16x16x32_bf16 v[92:95], v[164:167], v[180:183], v[92:95]
	v_mfma_f32_16x16x32_bf16 v[88:91], v[172:175], v[180:183], v[88:91]
	v_mfma_f32_16x16x32_bf16 v[84:87], v[164:167], v[188:191], v[84:87]
	v_mfma_f32_16x16x32_bf16 v[80:83], v[172:175], v[188:191], v[80:83]
	v_mfma_f32_16x16x32_bf16 v[60:63], v[164:167], v[196:199], v[60:63]
	v_mfma_f32_16x16x32_bf16 v[48:51], v[172:175], v[196:199], v[48:51]
	v_mfma_f32_16x16x32_bf16 v[36:39], v[164:167], v[204:207], v[36:39]
	v_mfma_f32_16x16x32_bf16 v[32:35], v[172:175], v[204:207], v[32:35]
	s_setprio 0
	s_setprio 2
	v_mfma_f32_16x16x32_bf16 v[92:95], v[168:171], v[184:187], v[92:95]
	v_mfma_f32_16x16x32_bf16 v[88:91], v[176:179], v[184:187], v[88:91]
	v_mfma_f32_16x16x32_bf16 v[84:87], v[168:171], v[192:195], v[84:87]
	v_mfma_f32_16x16x32_bf16 v[80:83], v[176:179], v[192:195], v[80:83]
	v_mfma_f32_16x16x32_bf16 v[60:63], v[168:171], v[200:203], v[60:63]
	v_mfma_f32_16x16x32_bf16 v[48:51], v[176:179], v[200:203], v[48:51]
	v_mfma_f32_16x16x32_bf16 v[36:39], v[168:171], v[208:211], v[36:39]
	s_setprio 3
	s_barrier
	v_mfma_f32_16x16x32_bf16 v[32:35], v[176:179], v[208:211], v[32:35]
	s_setprio 0
	s_add_i32 s97, 0, 0x18000
	v_add_u32_e32 v151, s97, v146
	s_add_i32 vcc_lo, 0, 0x1c000
	ds_read_b128 v[142:145], v151
	ds_read_b128 v[152:155], v151 offset:1024
	ds_read_b128 v[156:159], v151 offset:2048
	ds_read_b128 v[160:163], v151 offset:3072
	v_add_u32_e32 v151, vcc_lo, v146
	ds_read_b128 v[164:167], v151
	ds_read_b128 v[168:171], v151 offset:1024
	ds_read_b128 v[172:175], v151 offset:2048
	ds_read_b128 v[176:179], v151 offset:3072
	s_add_u32 s62, s62, 0x100000
	s_addc_u32 s63, s63, 0
	s_mov_b32 m0, s77
	v_lshl_add_u64 v[220:221], s[62:63], 0, v[134:135]
	ds_read_b128 v[180:183], v150 offset:32768
	ds_read_b128 v[184:187], v150 offset:33792
	ds_read_b128 v[188:191], v150 offset:34816
	ds_read_b128 v[192:195], v150 offset:35840
	ds_read_b128 v[196:199], v150 offset:36864
	ds_read_b128 v[200:203], v150 offset:37888
	ds_read_b128 v[204:207], v150 offset:38912
	ds_read_b128 v[208:211], v150 offset:39936
	global_load_lds_dwordx4 v[220:221], off
	v_lshl_add_u64 v[220:221], s[62:63], 0, v[130:131]
	s_mov_b32 m0, s78
	s_nop 0
	global_load_lds_dwordx4 v[220:221], off
	s_waitcnt vmcnt(8)
	s_waitcnt lgkmcnt(0)
	s_barrier
	s_setprio 2
	s_waitcnt lgkmcnt(0)
	v_mfma_f32_16x16x32_bf16 v[76:79], v[142:145], v[180:183], v[76:79]
	v_mfma_f32_16x16x32_bf16 v[72:75], v[156:159], v[180:183], v[72:75]
	v_mfma_f32_16x16x32_bf16 v[68:71], v[142:145], v[188:191], v[68:71]
	v_mfma_f32_16x16x32_bf16 v[64:67], v[156:159], v[188:191], v[64:67]
	v_mfma_f32_16x16x32_bf16 v[56:59], v[142:145], v[196:199], v[56:59]
	v_mfma_f32_16x16x32_bf16 v[52:55], v[156:159], v[196:199], v[52:55]
	v_mfma_f32_16x16x32_bf16 v[44:47], v[142:145], v[204:207], v[44:47]
	v_mfma_f32_16x16x32_bf16 v[40:43], v[156:159], v[204:207], v[40:43]
	s_setprio 0
	s_setprio 2
	v_mfma_f32_16x16x32_bf16 v[76:79], v[152:155], v[184:187], v[76:79]
	v_mfma_f32_16x16x32_bf16 v[72:75], v[160:163], v[184:187], v[72:75]
	v_mfma_f32_16x16x32_bf16 v[68:71], v[152:155], v[192:195], v[68:71]
	v_mfma_f32_16x16x32_bf16 v[64:67], v[160:163], v[192:195], v[64:67]
	v_mfma_f32_16x16x32_bf16 v[56:59], v[152:155], v[200:203], v[56:59]
	v_mfma_f32_16x16x32_bf16 v[52:55], v[160:163], v[200:203], v[52:55]
	v_mfma_f32_16x16x32_bf16 v[44:47], v[152:155], v[208:211], v[44:47]
	v_mfma_f32_16x16x32_bf16 v[40:43], v[160:163], v[208:211], v[40:43]
	s_setprio 0
	s_setprio 2
	v_mfma_f32_16x16x32_bf16 v[124:127], v[164:167], v[180:183], v[124:127]
	v_mfma_f32_16x16x32_bf16 v[120:123], v[172:175], v[180:183], v[120:123]
	v_mfma_f32_16x16x32_bf16 v[116:119], v[164:167], v[188:191], v[116:119]
	v_mfma_f32_16x16x32_bf16 v[112:115], v[172:175], v[188:191], v[112:115]
	v_mfma_f32_16x16x32_bf16 v[108:111], v[164:167], v[196:199], v[108:111]
	v_mfma_f32_16x16x32_bf16 v[104:107], v[172:175], v[196:199], v[104:107]
	v_mfma_f32_16x16x32_bf16 v[100:103], v[164:167], v[204:207], v[100:103]
	v_mfma_f32_16x16x32_bf16 v[96:99], v[172:175], v[204:207], v[96:99]
	s_setprio 0
	s_setprio 2
	v_mfma_f32_16x16x32_bf16 v[124:127], v[168:171], v[184:187], v[124:127]
	v_mfma_f32_16x16x32_bf16 v[120:123], v[176:179], v[184:187], v[120:123]
	v_mfma_f32_16x16x32_bf16 v[116:119], v[168:171], v[192:195], v[116:119]
	v_mfma_f32_16x16x32_bf16 v[112:115], v[176:179], v[192:195], v[112:115]
	v_mfma_f32_16x16x32_bf16 v[108:111], v[168:171], v[200:203], v[108:111]
	v_mfma_f32_16x16x32_bf16 v[104:107], v[176:179], v[200:203], v[104:107]
	v_mfma_f32_16x16x32_bf16 v[100:103], v[168:171], v[208:211], v[100:103]
	s_setprio 3
	s_barrier
; #define PG8_STAGE(bufoff, gbase, voff) do { _Pragma("unroll") for (int _i = 0; _i < 2; ++_i) \
;         __builtin_amdgcn_global_load_lds((const unsigned*)((const char*)(gbase) + (voff)[_i]), (PG8_LAS unsigned*)(lds + (bufoff) + ldsw + _i * 8192), 16, 0, 0); } while (0)
; #define PG8_LDA(dst, b, h) do { _Pragma("unroll") for (int m = 0; m < 4; ++m) _Pragma("unroll") for (int k = 0; k < 2; ++k) dst[m][k] = *(const PG8_LAS bf16x8*)(lds + PG8_SA(b, h) + aoff + m * 2048 + k * 1024); } while (0)
; #define PG8_MMA(ai, bj, At, Bt) do { __builtin_amdgcn_s_setprio(1); _Pragma("unroll") for (int m = 0; m < 4; ++m) _Pragma("unroll") for (int n = 0; n < 2; ++n) _Pragma("unroll") for (int k = 0; k < 2; ++k) \
;         acc[ai][bj][m][n] = __builtin_amdgcn_mfma_f32_16x16x32_bf16(Bt[n][k], At[m][k], acc[ai][bj][m][n], 0, 0, 0); __builtin_amdgcn_s_setprio(0); } while (0)
; #define PG8_WAIT_V(n) asm volatile("s_waitcnt vmcnt(" #n ")" ::: "memory")
; #define PG8_WAIT_L(n) asm volatile("s_waitcnt lgkmcnt(" #n ")" ::: "memory")
; #define PG8_BAR __builtin_amdgcn_s_barrier()
; #define PG8_SCHED __builtin_amdgcn_sched_barrier(0)
; template <class Epi, class Sched, bool ALIGN_EPI = false, bool SP2 = false>
; __device__ __forceinline__ void gemm_phase(PG8_LAS unsigned char* lds, const Gemm g, const Sched& S, const Epi& E, const int wv  ) {
;     ...
;             PG8_LDA(At, 1, 1); PG8_STAGE(PG8_SB(1, 0), b3, voffB); PG8_STAGE(PG8_SB(1, 1), b3 + hstepB, voffB); PG8_STAGE(PG8_SA(1, 0), a3, voffA);
;             PG8_WAIT_V(8); PG8_WAIT_L(0); PG8_BAR; PG8_MMA(1, 0, At, B0); PG8_MMA(1, 1, At, B1); PG8_BAR; PG8_SCHED;
;     ...
;         if constexpr (ALIGN_EPI) { if (wr == 0) PG8_BAR; }
;         if constexpr (!Epi::AFTER_DRAIN) { E(acc, cur, wr, wc, fr, fq); S.done(cur); }
;         if (!has_next) break;
	v_mfma_f32_16x16x32_bf16 v[96:99], v[176:179], v[208:211], v[96:99]
	s_setprio 0
	s_add_i32 s62, s97, s73
	v_lshl_add_u64 v[212:213], v[212:213], 0, s[8:9]
	s_mov_b32 m0, s62
	ds_read_b128 v[180:183], v150 offset:49152
	ds_read_b128 v[184:187], v150 offset:50176
	ds_read_b128 v[188:191], v150 offset:51200
	ds_read_b128 v[192:195], v150 offset:52224
	ds_read_b128 v[196:199], v150 offset:53248
	ds_read_b128 v[200:203], v150 offset:54272
	ds_read_b128 v[204:207], v150 offset:55296
	ds_read_b128 v[208:211], v150 offset:56320
	global_load_lds_dwordx4 v[212:213], off
	s_add_i32 m0, s62, 0x2000
	s_add_u32 s60, s60, 0x100080
	v_lshl_add_u64 v[212:213], v[214:215], 0, s[8:9]
	s_addc_u32 s61, s61, 0
	s_add_i32 s62, vcc_lo, s73
	global_load_lds_dwordx4 v[212:213], off
	v_lshl_add_u64 v[212:213], s[60:61], 0, v[132:133]
	s_mov_b32 m0, s62
	s_nop 0
	global_load_lds_dwordx4 v[212:213], off
	v_lshl_add_u64 v[212:213], s[60:61], 0, v[128:129]
	s_add_i32 m0, s62, 0x2000
	s_nop 0
	global_load_lds_dwordx4 v[212:213], off
	v_lshl_add_u64 v[212:213], v[216:217], 0, s[8:9]
	s_mov_b32 m0, s80
	s_nop 0
	global_load_lds_dwordx4 v[212:213], off
	v_lshl_add_u64 v[212:213], v[218:219], 0, s[8:9]
	s_mov_b32 m0, s81
	s_nop 0
	global_load_lds_dwordx4 v[212:213], off
	s_waitcnt vmcnt(8)
	s_waitcnt lgkmcnt(0)
	s_barrier
	s_setprio 2
	s_waitcnt lgkmcnt(0)
	v_mfma_f32_16x16x32_bf16 v[28:31], v[142:145], v[180:183], v[28:31]
	v_mfma_f32_16x16x32_bf16 v[24:27], v[156:159], v[180:183], v[24:27]
	v_mfma_f32_16x16x32_bf16 v[20:23], v[142:145], v[188:191], v[20:23]
	v_mfma_f32_16x16x32_bf16 v[16:19], v[156:159], v[188:191], v[16:19]
	v_mfma_f32_16x16x32_bf16 v[12:15], v[142:145], v[196:199], v[12:15]
	v_mfma_f32_16x16x32_bf16 v[8:11], v[156:159], v[196:199], v[8:11]
	v_mfma_f32_16x16x32_bf16 v[4:7], v[142:145], v[204:207], v[4:7]
	v_mfma_f32_16x16x32_bf16 v[0:3], v[156:159], v[204:207], v[0:3]
	s_setprio 0
	s_setprio 2
	v_mfma_f32_16x16x32_bf16 v[28:31], v[152:155], v[184:187], v[28:31]
	v_mfma_f32_16x16x32_bf16 v[24:27], v[160:163], v[184:187], v[24:27]
	v_mfma_f32_16x16x32_bf16 v[20:23], v[152:155], v[192:195], v[20:23]
	v_mfma_f32_16x16x32_bf16 v[16:19], v[160:163], v[192:195], v[16:19]
	v_mfma_f32_16x16x32_bf16 v[12:15], v[152:155], v[200:203], v[12:15]
	v_mfma_f32_16x16x32_bf16 v[8:11], v[160:163], v[200:203], v[8:11]
	v_mfma_f32_16x16x32_bf16 v[4:7], v[152:155], v[208:211], v[4:7]
	v_mfma_f32_16x16x32_bf16 v[0:3], v[160:163], v[208:211], v[0:3]
	s_setprio 0
	s_setprio 2
	v_mfma_f32_16x16x32_bf16 v[92:95], v[164:167], v[180:183], v[92:95]
	v_mfma_f32_16x16x32_bf16 v[88:91], v[172:175], v[180:183], v[88:91]
	v_mfma_f32_16x16x32_bf16 v[84:87], v[164:167], v[188:191], v[84:87]
	v_mfma_f32_16x16x32_bf16 v[80:83], v[172:175], v[188:191], v[80:83]
	v_mfma_f32_16x16x32_bf16 v[60:63], v[164:167], v[196:199], v[60:63]
	v_mfma_f32_16x16x32_bf16 v[48:51], v[172:175], v[196:199], v[48:51]
	v_mfma_f32_16x16x32_bf16 v[36:39], v[164:167], v[204:207], v[36:39]
	v_mfma_f32_16x16x32_bf16 v[32:35], v[172:175], v[204:207], v[32:35]
	s_setprio 0
	s_setprio 2
	v_mfma_f32_16x16x32_bf16 v[92:95], v[168:171], v[184:187], v[92:95]
	v_mfma_f32_16x16x32_bf16 v[88:91], v[176:179], v[184:187], v[88:91]
	v_mfma_f32_16x16x32_bf16 v[84:87], v[168:171], v[192:195], v[84:87]
	v_mfma_f32_16x16x32_bf16 v[80:83], v[176:179], v[192:195], v[80:83]
	v_mfma_f32_16x16x32_bf16 v[60:63], v[168:171], v[200:203], v[60:63]
	v_mfma_f32_16x16x32_bf16 v[48:51], v[176:179], v[200:203], v[48:51]
	v_mfma_f32_16x16x32_bf16 v[36:39], v[168:171], v[208:211], v[36:39]
	s_setprio 3
	s_barrier
	v_mfma_f32_16x16x32_bf16 v[32:35], v[176:179], v[208:211], v[32:35]
	s_setprio 0
	s_add_i32 s96, s96, 2
	s_add_u32 s58, s58, 0x100
	s_addc_u32 s59, s59, 0
	s_add_u32 s94, s94, 0x100
	s_addc_u32 s95, s95, 0
	s_cmp_gt_u32 s96, 61
	s_cbranch_scc0 .LBB0_871
	s_and_b64 vcc, exec, s[10:11]
	s_cbranch_vccz .LBB0_874
	s_barrier

; #define PG8_STAGE(bufoff, gbase, voff) do { _Pragma("unroll") for (int _i = 0; _i < 2; ++_i) \
;         __builtin_amdgcn_global_load_lds((const unsigned*)((const char*)(gbase) + (voff)[_i]), (PG8_LAS unsigned*)(lds + (bufoff) + ldsw + _i * 8192), 16, 0, 0); } while (0)
; #define PG8_LDA(dst, b, h) do { _Pragma("unroll") for (int m = 0; m < 4; ++m) _Pragma("unroll") for (int k = 0; k < 2; ++k) dst[m][k] = *(const PG8_LAS bf16x8*)(lds + PG8_SA(b, h) + aoff + m * 2048 + k * 1024); } while (0)
; #define PG8_LDB(dst, b, h) do { _Pragma("unroll") for (int n = 0; n < 2; ++n) _Pragma("unroll") for (int k = 0; k < 2; ++k) dst[n][k] = *(const PG8_LAS bf16x8*)(lds + PG8_SB(b, h) + boff + n * 2048 + k * 1024); } while (0)
; #define PG8_MMA(ai, bj, At, Bt) do { __builtin_amdgcn_s_setprio(1); _Pragma("unroll") for (int m = 0; m < 4; ++m) _Pragma("unroll") for (int n = 0; n < 2; ++n) _Pragma("unroll") for (int k = 0; k < 2; ++k) \
;         acc[ai][bj][m][n] = __builtin_amdgcn_mfma_f32_16x16x32_bf16(Bt[n][k], At[m][k], acc[ai][bj][m][n], 0, 0, 0); __builtin_amdgcn_s_setprio(0); } while (0)
; #define PG8_WAIT_V(n) asm volatile("s_waitcnt vmcnt(" #n ")" ::: "memory")
; #define PG8_WAIT_L(n) asm volatile("s_waitcnt lgkmcnt(" #n ")" ::: "memory")
; #define PG8_BAR __builtin_amdgcn_s_barrier()
; template <class Epi, class Sched, bool ALIGN_EPI = false, bool SP2 = false>
; __device__ __forceinline__ void gemm_phase(PG8_LAS unsigned char* lds, const Gemm g, const Sched& S, const Epi& E, const int wv  ) {
;     ...
;         for (int t = 0; t < nt; t += 2) {
;             const bool last = (t == nt - 2);
;             const char* a1 = cA + (size_t)(t + 1) * kstep;
;             const char* a2 = last ? nA : cA + (size_t)(t + 2) * kstep; const char* b2 = last ? nB : cB + (size_t)(t + 2) * kstep;
;             const char* a3 = a2 + kstep; const char* b3 = b2 + kstep;
;             if (last && has_next) S.a_ready(nxt);
;             if constexpr (SP2) {
;             PG8_LDB(B0, 0, 0); PG8_LDB(B1, 0, 1); PG8_SCHED; PG8_LDA(At, 0, 0); PG8_STAGE(PG8_SA(1, 1), a1 + hstepA, voffA);
;             PG8_WAIT_V(8); PG8_WAIT_L(0); PG8_BAR; PG8_MMA(0, 0, At, B0); PG8_MMA(0, 1, At, B1); PG8_BAR; PG8_SCHED;
;             PG8_LDA(At, 0, 1); PG8_STAGE(PG8_SB(0, 0), b2, voffB); PG8_STAGE(PG8_SB(0, 1), b2 + hstepB, voffB); PG8_STAGE(PG8_SA(0, 0), a2, voffA);
.LBB0_892:
	ds_read_b128 v[142:145], v148
	ds_read_b128 v[152:155], v148 offset:1024
	ds_read_b128 v[156:159], v148 offset:2048
	ds_read_b128 v[160:163], v148 offset:3072
	ds_read_b128 v[164:167], v149
	ds_read_b128 v[168:171], v149 offset:1024
	ds_read_b128 v[172:175], v149 offset:2048
	ds_read_b128 v[176:179], v149 offset:3072
	s_add_u32 s60, s58, 0xfff00080
	s_addc_u32 s61, s59, -1
	s_cmp_eq_u32 s92, 60
	s_cselect_b32 s63, s49, s61
	s_cselect_b32 s62, s86, s60
	s_cselect_b32 s61, s47, s91
	s_cselect_b32 s60, s87, s90
	v_lshl_add_u64 v[212:213], s[58:59], 0, v[138:139]
	s_add_i32 m0, s71, 0xc000
	ds_read_b128 v[180:183], v150
	ds_read_b128 v[184:187], v150 offset:1024
	ds_read_b128 v[188:191], v150 offset:2048
	ds_read_b128 v[192:195], v150 offset:3072
	ds_read_b128 v[196:199], v150 offset:4096
	ds_read_b128 v[200:203], v150 offset:5120
	ds_read_b128 v[204:207], v150 offset:6144
	ds_read_b128 v[208:211], v150 offset:7168
	global_load_lds_dwordx4 v[212:213], off
	v_lshl_add_u64 v[212:213], s[58:59], 0, v[140:141]
	s_add_i32 m0, s71, 0xe000
	s_nop 0
	global_load_lds_dwordx4 v[212:213], off
	s_waitcnt vmcnt(8)
	s_waitcnt lgkmcnt(0)
	s_barrier
	s_setprio 2
	s_waitcnt lgkmcnt(0)
	v_mfma_f32_16x16x32_bf16 v[76:79], v[142:145], v[180:183], v[76:79]
	v_mfma_f32_16x16x32_bf16 v[72:75], v[156:159], v[180:183], v[72:75]
	v_mfma_f32_16x16x32_bf16 v[68:71], v[142:145], v[188:191], v[68:71]
	v_mfma_f32_16x16x32_bf16 v[64:67], v[156:159], v[188:191], v[64:67]
	v_mfma_f32_16x16x32_bf16 v[56:59], v[142:145], v[196:199], v[56:59]
	v_mfma_f32_16x16x32_bf16 v[52:55], v[156:159], v[196:199], v[52:55]
	v_mfma_f32_16x16x32_bf16 v[44:47], v[142:145], v[204:207], v[44:47]
	v_mfma_f32_16x16x32_bf16 v[40:43], v[156:159], v[204:207], v[40:43]
	s_setprio 0
	s_setprio 2
	v_mfma_f32_16x16x32_bf16 v[76:79], v[152:155], v[184:187], v[76:79]
	v_mfma_f32_16x16x32_bf16 v[72:75], v[160:163], v[184:187], v[72:75]
	v_mfma_f32_16x16x32_bf16 v[68:71], v[152:155], v[192:195], v[68:71]
	v_mfma_f32_16x16x32_bf16 v[64:67], v[160:163], v[192:195], v[64:67]
	v_mfma_f32_16x16x32_bf16 v[56:59], v[152:155], v[200:203], v[56:59]
	v_mfma_f32_16x16x32_bf16 v[52:55], v[160:163], v[200:203], v[52:55]
	v_mfma_f32_16x16x32_bf16 v[44:47], v[152:155], v[208:211], v[44:47]
	v_mfma_f32_16x16x32_bf16 v[40:43], v[160:163], v[208:211], v[40:43]
	s_setprio 0
	s_setprio 2
	v_mfma_f32_16x16x32_bf16 v[124:127], v[164:167], v[180:183], v[124:127]
	v_mfma_f32_16x16x32_bf16 v[120:123], v[172:175], v[180:183], v[120:123]
	v_mfma_f32_16x16x32_bf16 v[116:119], v[164:167], v[188:191], v[116:119]
	v_mfma_f32_16x16x32_bf16 v[112:115], v[172:175], v[188:191], v[112:115]
	v_mfma_f32_16x16x32_bf16 v[108:111], v[164:167], v[196:199], v[108:111]
	v_mfma_f32_16x16x32_bf16 v[104:107], v[172:175], v[196:199], v[104:107]
	v_mfma_f32_16x16x32_bf16 v[100:103], v[164:167], v[204:207], v[100:103]
	v_mfma_f32_16x16x32_bf16 v[96:99], v[172:175], v[204:207], v[96:99]
	s_setprio 0
	s_setprio 2
	v_mfma_f32_16x16x32_bf16 v[124:127], v[168:171], v[184:187], v[124:127]
	v_mfma_f32_16x16x32_bf16 v[120:123], v[176:179], v[184:187], v[120:123]
	v_mfma_f32_16x16x32_bf16 v[116:119], v[168:171], v[192:195], v[116:119]
	v_mfma_f32_16x16x32_bf16 v[112:115], v[176:179], v[192:195], v[112:115]
	v_mfma_f32_16x16x32_bf16 v[108:111], v[168:171], v[200:203], v[108:111]
	v_mfma_f32_16x16x32_bf16 v[104:107], v[176:179], v[200:203], v[104:107]
	v_mfma_f32_16x16x32_bf16 v[100:103], v[168:171], v[208:211], v[100:103]
	s_setprio 3
	s_barrier
	v_mfma_f32_16x16x32_bf16 v[96:99], v[176:179], v[208:211], v[96:99]
	s_setprio 0
	s_add_i32 s93, s84, s69
	v_lshl_add_u64 v[212:213], s[60:61], 0, v[132:133]
	s_mov_b32 m0, s93
	ds_read_b128 v[180:183], v150 offset:16384
	ds_read_b128 v[184:187], v150 offset:17408
	ds_read_b128 v[188:191], v150 offset:18432
	ds_read_b128 v[192:195], v150 offset:19456
	ds_read_b128 v[196:199], v150 offset:20480
	ds_read_b128 v[200:203], v150 offset:21504
	ds_read_b128 v[204:207], v150 offset:22528
	ds_read_b128 v[208:211], v150 offset:23552
	global_load_lds_dwordx4 v[212:213], off
	s_add_i32 m0, s93, 0x2000
	s_add_u32 s94, s60, 0x100000
	v_lshl_add_u64 v[214:215], s[60:61], 0, v[128:129]
	s_addc_u32 s95, s61, 0
	s_add_i32 s93, s85, s69
	global_load_lds_dwordx4 v[214:215], off
	v_lshl_add_u64 v[216:217], s[94:95], 0, v[132:133]
	s_mov_b32 m0, s93
	v_lshl_add_u64 v[218:219], s[62:63], 0, v[130:131]
	global_load_lds_dwordx4 v[216:217], off
	v_lshl_add_u64 v[216:217], s[94:95], 0, v[128:129]
	s_add_i32 m0, s93, 0x2000
	s_nop 0
	global_load_lds_dwordx4 v[216:217], off
	v_lshl_add_u64 v[216:217], s[62:63], 0, v[134:135]
	s_mov_b32 m0, s71
	s_nop 0
	global_load_lds_dwordx4 v[216:217], off
	s_mov_b32 m0, s72
	s_nop 0
	global_load_lds_dwordx4 v[218:219], off
	s_waitcnt vmcnt(8)
	s_waitcnt lgkmcnt(0)
	s_barrier
; #define PG8_STAGE(bufoff, gbase, voff) do { _Pragma("unroll") for (int _i = 0; _i < 2; ++_i) \
;         __builtin_amdgcn_global_load_lds((const unsigned*)((const char*)(gbase) + (voff)[_i]), (PG8_LAS unsigned*)(lds + (bufoff) + ldsw + _i * 8192), 16, 0, 0); } while (0)
; #define PG8_LDA(dst, b, h) do { _Pragma("unroll") for (int m = 0; m < 4; ++m) _Pragma("unroll") for (int k = 0; k < 2; ++k) dst[m][k] = *(const PG8_LAS bf16x8*)(lds + PG8_SA(b, h) + aoff + m * 2048 + k * 1024); } while (0)
; #define PG8_LDB(dst, b, h) do { _Pragma("unroll") for (int n = 0; n < 2; ++n) _Pragma("unroll") for (int k = 0; k < 2; ++k) dst[n][k] = *(const PG8_LAS bf16x8*)(lds + PG8_SB(b, h) + boff + n * 2048 + k * 1024); } while (0)
; #define PG8_MMA(ai, bj, At, Bt) do { __builtin_amdgcn_s_setprio(1); _Pragma("unroll") for (int m = 0; m < 4; ++m) _Pragma("unroll") for (int n = 0; n < 2; ++n) _Pragma("unroll") for (int k = 0; k < 2; ++k) \
;         acc[ai][bj][m][n] = __builtin_amdgcn_mfma_f32_16x16x32_bf16(Bt[n][k], At[m][k], acc[ai][bj][m][n], 0, 0, 0); __builtin_amdgcn_s_setprio(0); } while (0)
; #define PG8_WAIT_V(n) asm volatile("s_waitcnt vmcnt(" #n ")" ::: "memory")
; #define PG8_WAIT_L(n) asm volatile("s_waitcnt lgkmcnt(" #n ")" ::: "memory")
; #define PG8_BAR __builtin_amdgcn_s_barrier()
; #define PG8_SCHED __builtin_amdgcn_sched_barrier(0)
; template <class Epi, class Sched, bool ALIGN_EPI = false, bool SP2 = false>
; __device__ __forceinline__ void gemm_phase(PG8_LAS unsigned char* lds, const Gemm g, const Sched& S, const Epi& E, const int wv  ) {
;     ...
;             PG8_WAIT_V(8); PG8_WAIT_L(0); PG8_BAR; PG8_MMA(1, 0, At, B0); PG8_MMA(1, 1, At, B1); PG8_BAR; PG8_SCHED;
;             PG8_LDB(B0, 1, 0); PG8_LDB(B1, 1, 1); PG8_SCHED; PG8_LDA(At, 1, 0); PG8_STAGE(PG8_SA(0, 1), a2 + hstepA, voffA);
;             PG8_WAIT_V(8); PG8_WAIT_L(0); PG8_BAR; PG8_MMA(0, 0, At, B0); PG8_MMA(0, 1, At, B1); PG8_BAR; PG8_SCHED;
	s_setprio 2
	s_waitcnt lgkmcnt(0)
	v_mfma_f32_16x16x32_bf16 v[28:31], v[142:145], v[180:183], v[28:31]
	v_mfma_f32_16x16x32_bf16 v[24:27], v[156:159], v[180:183], v[24:27]
	v_mfma_f32_16x16x32_bf16 v[20:23], v[142:145], v[188:191], v[20:23]
	v_mfma_f32_16x16x32_bf16 v[16:19], v[156:159], v[188:191], v[16:19]
	v_mfma_f32_16x16x32_bf16 v[12:15], v[142:145], v[196:199], v[12:15]
	v_mfma_f32_16x16x32_bf16 v[8:11], v[156:159], v[196:199], v[8:11]
	v_mfma_f32_16x16x32_bf16 v[4:7], v[142:145], v[204:207], v[4:7]
	v_mfma_f32_16x16x32_bf16 v[0:3], v[156:159], v[204:207], v[0:3]
	s_setprio 0
	s_setprio 2
	v_mfma_f32_16x16x32_bf16 v[28:31], v[152:155], v[184:187], v[28:31]
	v_mfma_f32_16x16x32_bf16 v[24:27], v[160:163], v[184:187], v[24:27]
	v_mfma_f32_16x16x32_bf16 v[20:23], v[152:155], v[192:195], v[20:23]
	v_mfma_f32_16x16x32_bf16 v[16:19], v[160:163], v[192:195], v[16:19]
	v_mfma_f32_16x16x32_bf16 v[12:15], v[152:155], v[200:203], v[12:15]
	v_mfma_f32_16x16x32_bf16 v[8:11], v[160:163], v[200:203], v[8:11]
	v_mfma_f32_16x16x32_bf16 v[4:7], v[152:155], v[208:211], v[4:7]
	v_mfma_f32_16x16x32_bf16 v[0:3], v[160:163], v[208:211], v[0:3]
	s_setprio 0
	s_setprio 2
	v_mfma_f32_16x16x32_bf16 v[92:95], v[164:167], v[180:183], v[92:95]
	v_mfma_f32_16x16x32_bf16 v[88:91], v[172:175], v[180:183], v[88:91]
	v_mfma_f32_16x16x32_bf16 v[84:87], v[164:167], v[188:191], v[84:87]
	v_mfma_f32_16x16x32_bf16 v[80:83], v[172:175], v[188:191], v[80:83]
	v_mfma_f32_16x16x32_bf16 v[60:63], v[164:167], v[196:199], v[60:63]
	v_mfma_f32_16x16x32_bf16 v[48:51], v[172:175], v[196:199], v[48:51]
	v_mfma_f32_16x16x32_bf16 v[36:39], v[164:167], v[204:207], v[36:39]
	v_mfma_f32_16x16x32_bf16 v[32:35], v[172:175], v[204:207], v[32:35]
	s_setprio 0
	s_setprio 2
	v_mfma_f32_16x16x32_bf16 v[92:95], v[168:171], v[184:187], v[92:95]
	v_mfma_f32_16x16x32_bf16 v[88:91], v[176:179], v[184:187], v[88:91]
	v_mfma_f32_16x16x32_bf16 v[84:87], v[168:171], v[192:195], v[84:87]
	v_mfma_f32_16x16x32_bf16 v[80:83], v[176:179], v[192:195], v[80:83]
	v_mfma_f32_16x16x32_bf16 v[60:63], v[168:171], v[200:203], v[60:63]
	v_mfma_f32_16x16x32_bf16 v[48:51], v[176:179], v[200:203], v[48:51]
	v_mfma_f32_16x16x32_bf16 v[36:39], v[168:171], v[208:211], v[36:39]
	s_setprio 3
	s_barrier
	v_mfma_f32_16x16x32_bf16 v[32:35], v[176:179], v[208:211], v[32:35]
	s_setprio 0
	s_add_i32 s93, 0, 0x18000
	v_add_u32_e32 v151, s93, v146
	s_add_i32 s94, 0, 0x1c000
	ds_read_b128 v[142:145], v151
	ds_read_b128 v[152:155], v151 offset:1024
	ds_read_b128 v[156:159], v151 offset:2048
	ds_read_b128 v[160:163], v151 offset:3072
	v_add_u32_e32 v151, s94, v146
	ds_read_b128 v[164:167], v151
	ds_read_b128 v[168:171], v151 offset:1024
	ds_read_b128 v[172:175], v151 offset:2048
	ds_read_b128 v[176:179], v151 offset:3072
	s_add_u32 s62, s62, 0x100000
	s_addc_u32 s63, s63, 0
	s_mov_b32 m0, s73
	v_lshl_add_u64 v[220:221], s[62:63], 0, v[134:135]
	ds_read_b128 v[180:183], v150 offset:32768
	ds_read_b128 v[184:187], v150 offset:33792
	ds_read_b128 v[188:191], v150 offset:34816
	ds_read_b128 v[192:195], v150 offset:35840
	ds_read_b128 v[196:199], v150 offset:36864
	ds_read_b128 v[200:203], v150 offset:37888
	ds_read_b128 v[204:207], v150 offset:38912
	ds_read_b128 v[208:211], v150 offset:39936
	global_load_lds_dwordx4 v[220:221], off
	v_lshl_add_u64 v[220:221], s[62:63], 0, v[130:131]
	s_mov_b32 m0, s74
	s_nop 0
	global_load_lds_dwordx4 v[220:221], off
	s_waitcnt vmcnt(8)
	s_waitcnt lgkmcnt(0)
	s_barrier
	s_setprio 2
	s_waitcnt lgkmcnt(0)
	v_mfma_f32_16x16x32_bf16 v[76:79], v[142:145], v[180:183], v[76:79]
	v_mfma_f32_16x16x32_bf16 v[72:75], v[156:159], v[180:183], v[72:75]
	v_mfma_f32_16x16x32_bf16 v[68:71], v[142:145], v[188:191], v[68:71]
	v_mfma_f32_16x16x32_bf16 v[64:67], v[156:159], v[188:191], v[64:67]
	v_mfma_f32_16x16x32_bf16 v[56:59], v[142:145], v[196:199], v[56:59]
	v_mfma_f32_16x16x32_bf16 v[52:55], v[156:159], v[196:199], v[52:55]
	v_mfma_f32_16x16x32_bf16 v[44:47], v[142:145], v[204:207], v[44:47]
	v_mfma_f32_16x16x32_bf16 v[40:43], v[156:159], v[204:207], v[40:43]
	s_setprio 0
	s_setprio 2
	v_mfma_f32_16x16x32_bf16 v[76:79], v[152:155], v[184:187], v[76:79]
	v_mfma_f32_16x16x32_bf16 v[72:75], v[160:163], v[184:187], v[72:75]
	v_mfma_f32_16x16x32_bf16 v[68:71], v[152:155], v[192:195], v[68:71]
	v_mfma_f32_16x16x32_bf16 v[64:67], v[160:163], v[192:195], v[64:67]
	v_mfma_f32_16x16x32_bf16 v[56:59], v[152:155], v[200:203], v[56:59]
	v_mfma_f32_16x16x32_bf16 v[52:55], v[160:163], v[200:203], v[52:55]
	v_mfma_f32_16x16x32_bf16 v[44:47], v[152:155], v[208:211], v[44:47]
	v_mfma_f32_16x16x32_bf16 v[40:43], v[160:163], v[208:211], v[40:43]
	s_setprio 0
	s_setprio 2
	v_mfma_f32_16x16x32_bf16 v[124:127], v[164:167], v[180:183], v[124:127]
	v_mfma_f32_16x16x32_bf16 v[120:123], v[172:175], v[180:183], v[120:123]
	v_mfma_f32_16x16x32_bf16 v[116:119], v[164:167], v[188:191], v[116:119]
	v_mfma_f32_16x16x32_bf16 v[112:115], v[172:175], v[188:191], v[112:115]
	v_mfma_f32_16x16x32_bf16 v[108:111], v[164:167], v[196:199], v[108:111]
	v_mfma_f32_16x16x32_bf16 v[104:107], v[172:175], v[196:199], v[104:107]
	v_mfma_f32_16x16x32_bf16 v[100:103], v[164:167], v[204:207], v[100:103]
	v_mfma_f32_16x16x32_bf16 v[96:99], v[172:175], v[204:207], v[96:99]
	s_setprio 0
	s_setprio 2
	v_mfma_f32_16x16x32_bf16 v[124:127], v[168:171], v[184:187], v[124:127]
	v_mfma_f32_16x16x32_bf16 v[120:123], v[176:179], v[184:187], v[120:123]
	v_mfma_f32_16x16x32_bf16 v[116:119], v[168:171], v[192:195], v[116:119]
	v_mfma_f32_16x16x32_bf16 v[112:115], v[176:179], v[192:195], v[112:115]
	v_mfma_f32_16x16x32_bf16 v[108:111], v[168:171], v[200:203], v[108:111]
	v_mfma_f32_16x16x32_bf16 v[104:107], v[176:179], v[200:203], v[104:107]
	v_mfma_f32_16x16x32_bf16 v[100:103], v[168:171], v[208:211], v[100:103]
	s_setprio 3
	s_barrier
; #define PG8_STAGE(bufoff, gbase, voff) do { _Pragma("unroll") for (int _i = 0; _i < 2; ++_i) \
;         __builtin_amdgcn_global_load_lds((const unsigned*)((const char*)(gbase) + (voff)[_i]), (PG8_LAS unsigned*)(lds + (bufoff) + ldsw + _i * 8192), 16, 0, 0); } while (0)
; #define PG8_LDA(dst, b, h) do { _Pragma("unroll") for (int m = 0; m < 4; ++m) _Pragma("unroll") for (int k = 0; k < 2; ++k) dst[m][k] = *(const PG8_LAS bf16x8*)(lds + PG8_SA(b, h) + aoff + m * 2048 + k * 1024); } while (0)
; #define PG8_MMA(ai, bj, At, Bt) do { __builtin_amdgcn_s_setprio(1); _Pragma("unroll") for (int m = 0; m < 4; ++m) _Pragma("unroll") for (int n = 0; n < 2; ++n) _Pragma("unroll") for (int k = 0; k < 2; ++k) \
;         acc[ai][bj][m][n] = __builtin_amdgcn_mfma_f32_16x16x32_bf16(Bt[n][k], At[m][k], acc[ai][bj][m][n], 0, 0, 0); __builtin_amdgcn_s_setprio(0); } while (0)
; #define PG8_WAIT_V(n) asm volatile("s_waitcnt vmcnt(" #n ")" ::: "memory")
; #define PG8_WAIT_L(n) asm volatile("s_waitcnt lgkmcnt(" #n ")" ::: "memory")
; #define PG8_BAR __builtin_amdgcn_s_barrier()
; #define PG8_SCHED __builtin_amdgcn_sched_barrier(0)
; template <class Epi, class Sched, bool ALIGN_EPI = false, bool SP2 = false>
; __device__ __forceinline__ void gemm_phase(PG8_LAS unsigned char* lds, const Gemm g, const Sched& S, const Epi& E, const int wv  ) {
;     ...
;             PG8_LDA(At, 1, 1); PG8_STAGE(PG8_SB(1, 0), b3, voffB); PG8_STAGE(PG8_SB(1, 1), b3 + hstepB, voffB); PG8_STAGE(PG8_SA(1, 0), a3, voffA);
;             PG8_WAIT_V(8); PG8_WAIT_L(0); PG8_BAR; PG8_MMA(1, 0, At, B0); PG8_MMA(1, 1, At, B1); PG8_BAR; PG8_SCHED;
;     ...
;         if constexpr (ALIGN_EPI) { if (wr == 0) PG8_BAR; }
;         if constexpr (!Epi::AFTER_DRAIN) { E(acc, cur, wr, wc, fr, fq); S.done(cur); }
;         if (!has_next) break;
	v_mfma_f32_16x16x32_bf16 v[96:99], v[176:179], v[208:211], v[96:99]
	s_setprio 0
	s_add_i32 s62, s93, s69
	v_lshl_add_u64 v[212:213], v[212:213], 0, s[8:9]
	s_mov_b32 m0, s62
	ds_read_b128 v[180:183], v150 offset:49152
	ds_read_b128 v[184:187], v150 offset:50176
	ds_read_b128 v[188:191], v150 offset:51200
	ds_read_b128 v[192:195], v150 offset:52224
	ds_read_b128 v[196:199], v150 offset:53248
	ds_read_b128 v[200:203], v150 offset:54272
	ds_read_b128 v[204:207], v150 offset:55296
	ds_read_b128 v[208:211], v150 offset:56320
	global_load_lds_dwordx4 v[212:213], off
	s_add_i32 m0, s62, 0x2000
	s_add_u32 s60, s60, 0x100080
	v_lshl_add_u64 v[212:213], v[214:215], 0, s[8:9]
	s_addc_u32 s61, s61, 0
	s_add_i32 s62, s94, s69
	global_load_lds_dwordx4 v[212:213], off
	v_lshl_add_u64 v[212:213], s[60:61], 0, v[132:133]
	s_mov_b32 m0, s62
	s_nop 0
	global_load_lds_dwordx4 v[212:213], off
	v_lshl_add_u64 v[212:213], s[60:61], 0, v[128:129]
	s_add_i32 m0, s62, 0x2000
	s_nop 0
	global_load_lds_dwordx4 v[212:213], off
	v_lshl_add_u64 v[212:213], v[216:217], 0, s[8:9]
	s_mov_b32 m0, s81
	s_nop 0
	global_load_lds_dwordx4 v[212:213], off
	v_lshl_add_u64 v[212:213], v[218:219], 0, s[8:9]
	s_mov_b32 m0, s82
	s_nop 0
	global_load_lds_dwordx4 v[212:213], off
	s_waitcnt vmcnt(8)
	s_waitcnt lgkmcnt(0)
	s_barrier
	s_setprio 2
	s_waitcnt lgkmcnt(0)
	v_mfma_f32_16x16x32_bf16 v[28:31], v[142:145], v[180:183], v[28:31]
	v_mfma_f32_16x16x32_bf16 v[24:27], v[156:159], v[180:183], v[24:27]
	v_mfma_f32_16x16x32_bf16 v[20:23], v[142:145], v[188:191], v[20:23]
	v_mfma_f32_16x16x32_bf16 v[16:19], v[156:159], v[188:191], v[16:19]
	v_mfma_f32_16x16x32_bf16 v[12:15], v[142:145], v[196:199], v[12:15]
	v_mfma_f32_16x16x32_bf16 v[8:11], v[156:159], v[196:199], v[8:11]
	v_mfma_f32_16x16x32_bf16 v[4:7], v[142:145], v[204:207], v[4:7]
	v_mfma_f32_16x16x32_bf16 v[0:3], v[156:159], v[204:207], v[0:3]
	s_setprio 0
	s_setprio 2
	v_mfma_f32_16x16x32_bf16 v[28:31], v[152:155], v[184:187], v[28:31]
	v_mfma_f32_16x16x32_bf16 v[24:27], v[160:163], v[184:187], v[24:27]
	v_mfma_f32_16x16x32_bf16 v[20:23], v[152:155], v[192:195], v[20:23]
	v_mfma_f32_16x16x32_bf16 v[16:19], v[160:163], v[192:195], v[16:19]
	v_mfma_f32_16x16x32_bf16 v[12:15], v[152:155], v[200:203], v[12:15]
	v_mfma_f32_16x16x32_bf16 v[8:11], v[160:163], v[200:203], v[8:11]
	v_mfma_f32_16x16x32_bf16 v[4:7], v[152:155], v[208:211], v[4:7]
	v_mfma_f32_16x16x32_bf16 v[0:3], v[160:163], v[208:211], v[0:3]
	s_setprio 0
	s_setprio 2
	v_mfma_f32_16x16x32_bf16 v[92:95], v[164:167], v[180:183], v[92:95]
	v_mfma_f32_16x16x32_bf16 v[88:91], v[172:175], v[180:183], v[88:91]
	v_mfma_f32_16x16x32_bf16 v[84:87], v[164:167], v[188:191], v[84:87]
	v_mfma_f32_16x16x32_bf16 v[80:83], v[172:175], v[188:191], v[80:83]
	v_mfma_f32_16x16x32_bf16 v[60:63], v[164:167], v[196:199], v[60:63]
	v_mfma_f32_16x16x32_bf16 v[48:51], v[172:175], v[196:199], v[48:51]
	v_mfma_f32_16x16x32_bf16 v[36:39], v[164:167], v[204:207], v[36:39]
	v_mfma_f32_16x16x32_bf16 v[32:35], v[172:175], v[204:207], v[32:35]
	s_setprio 0
	s_setprio 2
	v_mfma_f32_16x16x32_bf16 v[92:95], v[168:171], v[184:187], v[92:95]
	v_mfma_f32_16x16x32_bf16 v[88:91], v[176:179], v[184:187], v[88:91]
	v_mfma_f32_16x16x32_bf16 v[84:87], v[168:171], v[192:195], v[84:87]
	v_mfma_f32_16x16x32_bf16 v[80:83], v[176:179], v[192:195], v[80:83]
	v_mfma_f32_16x16x32_bf16 v[60:63], v[168:171], v[200:203], v[60:63]
	v_mfma_f32_16x16x32_bf16 v[48:51], v[176:179], v[200:203], v[48:51]
	v_mfma_f32_16x16x32_bf16 v[36:39], v[168:171], v[208:211], v[36:39]
	s_setprio 3
	s_barrier
	v_mfma_f32_16x16x32_bf16 v[32:35], v[176:179], v[208:211], v[32:35]
	s_setprio 0
	s_add_i32 s92, s92, 2
	s_add_u32 s58, s58, 0x100
	s_addc_u32 s59, s59, 0
	s_add_u32 s90, s90, 0x100
	s_addc_u32 s91, s91, 0
	s_cmp_gt_u32 s92, 61
	s_cbranch_scc0 .LBB0_892
	s_and_b64 vcc, exec, s[10:11]
	s_cbranch_vccz .LBB0_895
	s_barrier

; #define PG8_STAGE(bufoff, gbase, voff) do { _Pragma("unroll") for (int _i = 0; _i < 2; ++_i) \
;         __builtin_amdgcn_global_load_lds((const unsigned*)((const char*)(gbase) + (voff)[_i]), (PG8_LAS unsigned*)(lds + (bufoff) + ldsw + _i * 8192), 16, 0, 0); } while (0)
; #define PG8_LDA(dst, b, h) do { _Pragma("unroll") for (int m = 0; m < 4; ++m) _Pragma("unroll") for (int k = 0; k < 2; ++k) dst[m][k] = *(const PG8_LAS bf16x8*)(lds + PG8_SA(b, h) + aoff + m * 2048 + k * 1024); } while (0)
; #define PG8_LDB(dst, b, h) do { _Pragma("unroll") for (int n = 0; n < 2; ++n) _Pragma("unroll") for (int k = 0; k < 2; ++k) dst[n][k] = *(const PG8_LAS bf16x8*)(lds + PG8_SB(b, h) + boff + n * 2048 + k * 1024); } while (0)
; #define PG8_MMA(ai, bj, At, Bt) do { __builtin_amdgcn_s_setprio(1); _Pragma("unroll") for (int m = 0; m < 4; ++m) _Pragma("unroll") for (int n = 0; n < 2; ++n) _Pragma("unroll") for (int k = 0; k < 2; ++k) \
;         acc[ai][bj][m][n] = __builtin_amdgcn_mfma_f32_16x16x32_bf16(Bt[n][k], At[m][k], acc[ai][bj][m][n], 0, 0, 0); __builtin_amdgcn_s_setprio(0); } while (0)
; #define PG8_WAIT_V(n) asm volatile("s_waitcnt vmcnt(" #n ")" ::: "memory")
; #define PG8_WAIT_L(n) asm volatile("s_waitcnt lgkmcnt(" #n ")" ::: "memory")
; #define PG8_BAR __builtin_amdgcn_s_barrier()
; template <class Epi, class Sched, bool ALIGN_EPI = false, bool SP2 = false>
; __device__ __forceinline__ void gemm_phase(PG8_LAS unsigned char* lds, const Gemm g, const Sched& S, const Epi& E, const int wv  ) {
;     ...
;         for (int t = 0; t < nt; t += 2) {
;             const bool last = (t == nt - 2);
;             const char* a1 = cA + (size_t)(t + 1) * kstep;
;             const char* a2 = last ? nA : cA + (size_t)(t + 2) * kstep; const char* b2 = last ? nB : cB + (size_t)(t + 2) * kstep;
;             const char* a3 = a2 + kstep; const char* b3 = b2 + kstep;
;             if (last && has_next) S.a_ready(nxt);
;             if constexpr (SP2) {
;             PG8_LDB(B0, 0, 0); PG8_LDB(B1, 0, 1); PG8_SCHED; PG8_LDA(At, 0, 0); PG8_STAGE(PG8_SA(1, 1), a1 + hstepA, voffA);
;             PG8_WAIT_V(8); PG8_WAIT_L(0); PG8_BAR; PG8_MMA(0, 0, At, B0); PG8_MMA(0, 1, At, B1); PG8_BAR; PG8_SCHED;
;             PG8_LDA(At, 0, 1); PG8_STAGE(PG8_SB(0, 0), b2, voffB); PG8_STAGE(PG8_SB(0, 1), b2 + hstepB, voffB); PG8_STAGE(PG8_SA(0, 0), a2, voffA);
.LBB0_1049:
	ds_read_b128 v[146:149], v152
	ds_read_b128 v[156:159], v152 offset:1024
	ds_read_b128 v[160:163], v152 offset:2048
	ds_read_b128 v[164:167], v152 offset:3072
	ds_read_b128 v[168:171], v153
	ds_read_b128 v[172:175], v153 offset:1024
	ds_read_b128 v[176:179], v153 offset:2048
	ds_read_b128 v[180:183], v153 offset:3072
	s_add_u32 s60, s58, 0xfffc0080
	s_addc_u32 s61, s59, -1
	s_cmp_eq_u32 s87, 12
	s_cselect_b32 s63, s51, s61
	s_cselect_b32 s62, s83, s60
	s_cselect_b32 s61, s49, s86
	s_cselect_b32 s60, s84, s85
	v_lshl_add_u64 v[216:217], s[58:59], 0, v[138:139]
	s_add_i32 m0, s68, 0xc000
	ds_read_b128 v[184:187], v154
	ds_read_b128 v[188:191], v154 offset:1024
	ds_read_b128 v[192:195], v154 offset:2048
	ds_read_b128 v[196:199], v154 offset:3072
	ds_read_b128 v[200:203], v154 offset:4096
	ds_read_b128 v[204:207], v154 offset:5120
	ds_read_b128 v[208:211], v154 offset:6144
	ds_read_b128 v[212:215], v154 offset:7168
	global_load_lds_dwordx4 v[216:217], off
	v_lshl_add_u64 v[216:217], s[58:59], 0, v[140:141]
	s_add_i32 m0, s68, 0xe000
	s_nop 0
	global_load_lds_dwordx4 v[216:217], off
	s_waitcnt vmcnt(8)
	s_waitcnt lgkmcnt(0)
	s_barrier
	s_setprio 2
	s_waitcnt lgkmcnt(0)
	v_mfma_f32_16x16x32_bf16 v[76:79], v[146:149], v[184:187], v[76:79]
	v_mfma_f32_16x16x32_bf16 v[72:75], v[160:163], v[184:187], v[72:75]
	v_mfma_f32_16x16x32_bf16 v[68:71], v[146:149], v[192:195], v[68:71]
	v_mfma_f32_16x16x32_bf16 v[64:67], v[160:163], v[192:195], v[64:67]
	v_mfma_f32_16x16x32_bf16 v[56:59], v[146:149], v[200:203], v[56:59]
	v_mfma_f32_16x16x32_bf16 v[52:55], v[160:163], v[200:203], v[52:55]
	v_mfma_f32_16x16x32_bf16 v[44:47], v[146:149], v[208:211], v[44:47]
	v_mfma_f32_16x16x32_bf16 v[40:43], v[160:163], v[208:211], v[40:43]
	s_setprio 0
	s_setprio 2
	v_mfma_f32_16x16x32_bf16 v[76:79], v[156:159], v[188:191], v[76:79]
	v_mfma_f32_16x16x32_bf16 v[72:75], v[164:167], v[188:191], v[72:75]
	v_mfma_f32_16x16x32_bf16 v[68:71], v[156:159], v[196:199], v[68:71]
	v_mfma_f32_16x16x32_bf16 v[64:67], v[164:167], v[196:199], v[64:67]
	v_mfma_f32_16x16x32_bf16 v[56:59], v[156:159], v[204:207], v[56:59]
	v_mfma_f32_16x16x32_bf16 v[52:55], v[164:167], v[204:207], v[52:55]
	v_mfma_f32_16x16x32_bf16 v[44:47], v[156:159], v[212:215], v[44:47]
	v_mfma_f32_16x16x32_bf16 v[40:43], v[164:167], v[212:215], v[40:43]
	s_setprio 0
	s_setprio 2
	v_mfma_f32_16x16x32_bf16 v[124:127], v[168:171], v[184:187], v[124:127]
	v_mfma_f32_16x16x32_bf16 v[120:123], v[176:179], v[184:187], v[120:123]
	v_mfma_f32_16x16x32_bf16 v[116:119], v[168:171], v[192:195], v[116:119]
	v_mfma_f32_16x16x32_bf16 v[112:115], v[176:179], v[192:195], v[112:115]
	v_mfma_f32_16x16x32_bf16 v[108:111], v[168:171], v[200:203], v[108:111]
	v_mfma_f32_16x16x32_bf16 v[104:107], v[176:179], v[200:203], v[104:107]
	v_mfma_f32_16x16x32_bf16 v[100:103], v[168:171], v[208:211], v[100:103]
	v_mfma_f32_16x16x32_bf16 v[96:99], v[176:179], v[208:211], v[96:99]
	s_setprio 0
	s_setprio 2
	v_mfma_f32_16x16x32_bf16 v[124:127], v[172:175], v[188:191], v[124:127]
	v_mfma_f32_16x16x32_bf16 v[120:123], v[180:183], v[188:191], v[120:123]
	v_mfma_f32_16x16x32_bf16 v[116:119], v[172:175], v[196:199], v[116:119]
	v_mfma_f32_16x16x32_bf16 v[112:115], v[180:183], v[196:199], v[112:115]
	v_mfma_f32_16x16x32_bf16 v[108:111], v[172:175], v[204:207], v[108:111]
	v_mfma_f32_16x16x32_bf16 v[104:107], v[180:183], v[204:207], v[104:107]
	v_mfma_f32_16x16x32_bf16 v[100:103], v[172:175], v[212:215], v[100:103]
	s_setprio 3
	s_barrier
	v_mfma_f32_16x16x32_bf16 v[96:99], v[180:183], v[212:215], v[96:99]
	s_setprio 0
	s_add_i32 s90, s77, s67
	v_lshl_add_u64 v[216:217], s[60:61], 0, v[130:131]
	s_mov_b32 m0, s90
	ds_read_b128 v[184:187], v154 offset:16384
	ds_read_b128 v[188:191], v154 offset:17408
	ds_read_b128 v[192:195], v154 offset:18432
	ds_read_b128 v[196:199], v154 offset:19456
	ds_read_b128 v[200:203], v154 offset:20480
	ds_read_b128 v[204:207], v154 offset:21504
	ds_read_b128 v[208:211], v154 offset:22528
	ds_read_b128 v[212:215], v154 offset:23552
	global_load_lds_dwordx4 v[216:217], off
	s_add_i32 m0, s90, 0x2000
	s_add_u32 s90, s60, 0x40000
	v_lshl_add_u64 v[218:219], s[60:61], 0, v[134:135]
	s_addc_u32 s91, s61, 0
	s_add_i32 s92, s78, s67
	global_load_lds_dwordx4 v[218:219], off
	v_lshl_add_u64 v[220:221], s[90:91], 0, v[130:131]
	s_mov_b32 m0, s92
	v_lshl_add_u64 v[222:223], s[62:63], 0, v[132:133]
	global_load_lds_dwordx4 v[220:221], off
	v_lshl_add_u64 v[220:221], s[90:91], 0, v[134:135]
	s_add_i32 m0, s92, 0x2000
	s_nop 0
	global_load_lds_dwordx4 v[220:221], off
	v_lshl_add_u64 v[220:221], s[62:63], 0, v[128:129]
	s_mov_b32 m0, s68
	s_nop 0
	global_load_lds_dwordx4 v[220:221], off
	s_mov_b32 m0, s69
	s_nop 0
	global_load_lds_dwordx4 v[222:223], off
	s_waitcnt vmcnt(8)
	s_waitcnt lgkmcnt(0)
	s_barrier
; #define PG8_STAGE(bufoff, gbase, voff) do { _Pragma("unroll") for (int _i = 0; _i < 2; ++_i) \
;         __builtin_amdgcn_global_load_lds((const unsigned*)((const char*)(gbase) + (voff)[_i]), (PG8_LAS unsigned*)(lds + (bufoff) + ldsw + _i * 8192), 16, 0, 0); } while (0)
; #define PG8_LDA(dst, b, h) do { _Pragma("unroll") for (int m = 0; m < 4; ++m) _Pragma("unroll") for (int k = 0; k < 2; ++k) dst[m][k] = *(const PG8_LAS bf16x8*)(lds + PG8_SA(b, h) + aoff + m * 2048 + k * 1024); } while (0)
; #define PG8_LDB(dst, b, h) do { _Pragma("unroll") for (int n = 0; n < 2; ++n) _Pragma("unroll") for (int k = 0; k < 2; ++k) dst[n][k] = *(const PG8_LAS bf16x8*)(lds + PG8_SB(b, h) + boff + n * 2048 + k * 1024); } while (0)
; #define PG8_MMA(ai, bj, At, Bt) do { __builtin_amdgcn_s_setprio(1); _Pragma("unroll") for (int m = 0; m < 4; ++m) _Pragma("unroll") for (int n = 0; n < 2; ++n) _Pragma("unroll") for (int k = 0; k < 2; ++k) \
;         acc[ai][bj][m][n] = __builtin_amdgcn_mfma_f32_16x16x32_bf16(Bt[n][k], At[m][k], acc[ai][bj][m][n], 0, 0, 0); __builtin_amdgcn_s_setprio(0); } while (0)
; #define PG8_WAIT_V(n) asm volatile("s_waitcnt vmcnt(" #n ")" ::: "memory")
; #define PG8_WAIT_L(n) asm volatile("s_waitcnt lgkmcnt(" #n ")" ::: "memory")
; #define PG8_BAR __builtin_amdgcn_s_barrier()
; #define PG8_SCHED __builtin_amdgcn_sched_barrier(0)
; template <class Epi, class Sched, bool ALIGN_EPI = false, bool SP2 = false>
; __device__ __forceinline__ void gemm_phase(PG8_LAS unsigned char* lds, const Gemm g, const Sched& S, const Epi& E, const int wv  ) {
;     ...
;             PG8_WAIT_V(8); PG8_WAIT_L(0); PG8_BAR; PG8_MMA(1, 0, At, B0); PG8_MMA(1, 1, At, B1); PG8_BAR; PG8_SCHED;
;             PG8_LDB(B0, 1, 0); PG8_LDB(B1, 1, 1); PG8_SCHED; PG8_LDA(At, 1, 0); PG8_STAGE(PG8_SA(0, 1), a2 + hstepA, voffA);
;             PG8_WAIT_V(8); PG8_WAIT_L(0); PG8_BAR; PG8_MMA(0, 0, At, B0); PG8_MMA(0, 1, At, B1); PG8_BAR; PG8_SCHED;
	s_setprio 2
	s_waitcnt lgkmcnt(0)
	v_mfma_f32_16x16x32_bf16 v[28:31], v[146:149], v[184:187], v[28:31]
	v_mfma_f32_16x16x32_bf16 v[24:27], v[160:163], v[184:187], v[24:27]
	v_mfma_f32_16x16x32_bf16 v[20:23], v[146:149], v[192:195], v[20:23]
	v_mfma_f32_16x16x32_bf16 v[16:19], v[160:163], v[192:195], v[16:19]
	v_mfma_f32_16x16x32_bf16 v[12:15], v[146:149], v[200:203], v[12:15]
	v_mfma_f32_16x16x32_bf16 v[8:11], v[160:163], v[200:203], v[8:11]
	v_mfma_f32_16x16x32_bf16 v[4:7], v[146:149], v[208:211], v[4:7]
	v_mfma_f32_16x16x32_bf16 v[0:3], v[160:163], v[208:211], v[0:3]
	s_setprio 0
	s_setprio 2
	v_mfma_f32_16x16x32_bf16 v[28:31], v[156:159], v[188:191], v[28:31]
	v_mfma_f32_16x16x32_bf16 v[24:27], v[164:167], v[188:191], v[24:27]
	v_mfma_f32_16x16x32_bf16 v[20:23], v[156:159], v[196:199], v[20:23]
	v_mfma_f32_16x16x32_bf16 v[16:19], v[164:167], v[196:199], v[16:19]
	v_mfma_f32_16x16x32_bf16 v[12:15], v[156:159], v[204:207], v[12:15]
	v_mfma_f32_16x16x32_bf16 v[8:11], v[164:167], v[204:207], v[8:11]
	v_mfma_f32_16x16x32_bf16 v[4:7], v[156:159], v[212:215], v[4:7]
	v_mfma_f32_16x16x32_bf16 v[0:3], v[164:167], v[212:215], v[0:3]
	s_setprio 0
	s_setprio 2
	v_mfma_f32_16x16x32_bf16 v[92:95], v[168:171], v[184:187], v[92:95]
	v_mfma_f32_16x16x32_bf16 v[88:91], v[176:179], v[184:187], v[88:91]
	v_mfma_f32_16x16x32_bf16 v[84:87], v[168:171], v[192:195], v[84:87]
	v_mfma_f32_16x16x32_bf16 v[80:83], v[176:179], v[192:195], v[80:83]
	v_mfma_f32_16x16x32_bf16 v[60:63], v[168:171], v[200:203], v[60:63]
	v_mfma_f32_16x16x32_bf16 v[48:51], v[176:179], v[200:203], v[48:51]
	v_mfma_f32_16x16x32_bf16 v[36:39], v[168:171], v[208:211], v[36:39]
	v_mfma_f32_16x16x32_bf16 v[32:35], v[176:179], v[208:211], v[32:35]
	s_setprio 0
	s_setprio 2
	v_mfma_f32_16x16x32_bf16 v[92:95], v[172:175], v[188:191], v[92:95]
	v_mfma_f32_16x16x32_bf16 v[88:91], v[180:183], v[188:191], v[88:91]
	v_mfma_f32_16x16x32_bf16 v[84:87], v[172:175], v[196:199], v[84:87]
	v_mfma_f32_16x16x32_bf16 v[80:83], v[180:183], v[196:199], v[80:83]
	v_mfma_f32_16x16x32_bf16 v[60:63], v[172:175], v[204:207], v[60:63]
	v_mfma_f32_16x16x32_bf16 v[48:51], v[180:183], v[204:207], v[48:51]
	v_mfma_f32_16x16x32_bf16 v[36:39], v[172:175], v[212:215], v[36:39]
	s_setprio 3
	s_barrier
	v_mfma_f32_16x16x32_bf16 v[32:35], v[180:183], v[212:215], v[32:35]
	s_setprio 0
	s_add_i32 s90, 0, 0x18000
	v_add_u32_e32 v155, s90, v150
	s_add_i32 s91, 0, 0x1c000
	ds_read_b128 v[146:149], v155
	ds_read_b128 v[156:159], v155 offset:1024
	ds_read_b128 v[160:163], v155 offset:2048
	ds_read_b128 v[164:167], v155 offset:3072
	v_add_u32_e32 v155, s91, v150
	ds_read_b128 v[168:171], v155
	ds_read_b128 v[172:175], v155 offset:1024
	ds_read_b128 v[176:179], v155 offset:2048
	ds_read_b128 v[180:183], v155 offset:3072
	s_add_u32 s62, s62, 0x40000
	s_addc_u32 s63, s63, 0
	s_mov_b32 m0, s70
	v_lshl_add_u64 v[224:225], s[62:63], 0, v[128:129]
	ds_read_b128 v[184:187], v154 offset:32768
	ds_read_b128 v[188:191], v154 offset:33792
	ds_read_b128 v[192:195], v154 offset:34816
	ds_read_b128 v[196:199], v154 offset:35840
	ds_read_b128 v[200:203], v154 offset:36864
	ds_read_b128 v[204:207], v154 offset:37888
	ds_read_b128 v[208:211], v154 offset:38912
	ds_read_b128 v[212:215], v154 offset:39936
	global_load_lds_dwordx4 v[224:225], off
	v_lshl_add_u64 v[224:225], s[62:63], 0, v[132:133]
	s_mov_b32 m0, s71
	s_nop 0
	global_load_lds_dwordx4 v[224:225], off
	s_waitcnt vmcnt(8)
	s_waitcnt lgkmcnt(0)
	s_barrier
	s_setprio 2
	s_waitcnt lgkmcnt(0)
	v_mfma_f32_16x16x32_bf16 v[76:79], v[146:149], v[184:187], v[76:79]
	v_mfma_f32_16x16x32_bf16 v[72:75], v[160:163], v[184:187], v[72:75]
	v_mfma_f32_16x16x32_bf16 v[68:71], v[146:149], v[192:195], v[68:71]
	v_mfma_f32_16x16x32_bf16 v[64:67], v[160:163], v[192:195], v[64:67]
	v_mfma_f32_16x16x32_bf16 v[56:59], v[146:149], v[200:203], v[56:59]
	v_mfma_f32_16x16x32_bf16 v[52:55], v[160:163], v[200:203], v[52:55]
	v_mfma_f32_16x16x32_bf16 v[44:47], v[146:149], v[208:211], v[44:47]
	v_mfma_f32_16x16x32_bf16 v[40:43], v[160:163], v[208:211], v[40:43]
	s_setprio 0
	s_setprio 2
	v_mfma_f32_16x16x32_bf16 v[76:79], v[156:159], v[188:191], v[76:79]
	v_mfma_f32_16x16x32_bf16 v[72:75], v[164:167], v[188:191], v[72:75]
	v_mfma_f32_16x16x32_bf16 v[68:71], v[156:159], v[196:199], v[68:71]
	v_mfma_f32_16x16x32_bf16 v[64:67], v[164:167], v[196:199], v[64:67]
	v_mfma_f32_16x16x32_bf16 v[56:59], v[156:159], v[204:207], v[56:59]
	v_mfma_f32_16x16x32_bf16 v[52:55], v[164:167], v[204:207], v[52:55]
	v_mfma_f32_16x16x32_bf16 v[44:47], v[156:159], v[212:215], v[44:47]
	v_mfma_f32_16x16x32_bf16 v[40:43], v[164:167], v[212:215], v[40:43]
	s_setprio 0
	s_setprio 2
	v_mfma_f32_16x16x32_bf16 v[124:127], v[168:171], v[184:187], v[124:127]
	v_mfma_f32_16x16x32_bf16 v[120:123], v[176:179], v[184:187], v[120:123]
	v_mfma_f32_16x16x32_bf16 v[116:119], v[168:171], v[192:195], v[116:119]
	v_mfma_f32_16x16x32_bf16 v[112:115], v[176:179], v[192:195], v[112:115]
	v_mfma_f32_16x16x32_bf16 v[108:111], v[168:171], v[200:203], v[108:111]
	v_mfma_f32_16x16x32_bf16 v[104:107], v[176:179], v[200:203], v[104:107]
	v_mfma_f32_16x16x32_bf16 v[100:103], v[168:171], v[208:211], v[100:103]
	v_mfma_f32_16x16x32_bf16 v[96:99], v[176:179], v[208:211], v[96:99]
	s_setprio 0
	s_setprio 2
	v_mfma_f32_16x16x32_bf16 v[124:127], v[172:175], v[188:191], v[124:127]
	v_mfma_f32_16x16x32_bf16 v[120:123], v[180:183], v[188:191], v[120:123]
	v_mfma_f32_16x16x32_bf16 v[116:119], v[172:175], v[196:199], v[116:119]
	v_mfma_f32_16x16x32_bf16 v[112:115], v[180:183], v[196:199], v[112:115]
	v_mfma_f32_16x16x32_bf16 v[108:111], v[172:175], v[204:207], v[108:111]
	v_mfma_f32_16x16x32_bf16 v[104:107], v[180:183], v[204:207], v[104:107]
	v_mfma_f32_16x16x32_bf16 v[100:103], v[172:175], v[212:215], v[100:103]
	s_setprio 3
	s_barrier
; #define PG8_STAGE(bufoff, gbase, voff) do { _Pragma("unroll") for (int _i = 0; _i < 2; ++_i) \
;         __builtin_amdgcn_global_load_lds((const unsigned*)((const char*)(gbase) + (voff)[_i]), (PG8_LAS unsigned*)(lds + (bufoff) + ldsw + _i * 8192), 16, 0, 0); } while (0)
; #define PG8_LDA(dst, b, h) do { _Pragma("unroll") for (int m = 0; m < 4; ++m) _Pragma("unroll") for (int k = 0; k < 2; ++k) dst[m][k] = *(const PG8_LAS bf16x8*)(lds + PG8_SA(b, h) + aoff + m * 2048 + k * 1024); } while (0)
; #define PG8_MMA(ai, bj, At, Bt) do { __builtin_amdgcn_s_setprio(1); _Pragma("unroll") for (int m = 0; m < 4; ++m) _Pragma("unroll") for (int n = 0; n < 2; ++n) _Pragma("unroll") for (int k = 0; k < 2; ++k) \
;         acc[ai][bj][m][n] = __builtin_amdgcn_mfma_f32_16x16x32_bf16(Bt[n][k], At[m][k], acc[ai][bj][m][n], 0, 0, 0); __builtin_amdgcn_s_setprio(0); } while (0)
; #define PG8_WAIT_V(n) asm volatile("s_waitcnt vmcnt(" #n ")" ::: "memory")
; #define PG8_WAIT_L(n) asm volatile("s_waitcnt lgkmcnt(" #n ")" ::: "memory")
; #define PG8_BAR __builtin_amdgcn_s_barrier()
; #define PG8_SCHED __builtin_amdgcn_sched_barrier(0)
; template <class Epi, class Sched, bool ALIGN_EPI = false, bool SP2 = false>
; __device__ __forceinline__ void gemm_phase(PG8_LAS unsigned char* lds, const Gemm g, const Sched& S, const Epi& E, const int wv  ) {
;     ...
;             PG8_LDA(At, 1, 1); PG8_STAGE(PG8_SB(1, 0), b3, voffB); PG8_STAGE(PG8_SB(1, 1), b3 + hstepB, voffB); PG8_STAGE(PG8_SA(1, 0), a3, voffA);
;             PG8_WAIT_V(8); PG8_WAIT_L(0); PG8_BAR; PG8_MMA(1, 0, At, B0); PG8_MMA(1, 1, At, B1); PG8_BAR; PG8_SCHED;
;     ...
;         if constexpr (ALIGN_EPI) { if (wr == 0) PG8_BAR; }
;         if constexpr (!Epi::AFTER_DRAIN) { E(acc, cur, wr, wc, fr, fq); S.done(cur); }
;         if (!has_next) break;
	v_mfma_f32_16x16x32_bf16 v[96:99], v[180:183], v[212:215], v[96:99]
	s_setprio 0
	s_add_i32 s62, s90, s67
	v_lshl_add_u64 v[216:217], v[216:217], 0, s[10:11]
	s_mov_b32 m0, s62
	ds_read_b128 v[184:187], v154 offset:49152
	ds_read_b128 v[188:191], v154 offset:50176
	ds_read_b128 v[192:195], v154 offset:51200
	ds_read_b128 v[196:199], v154 offset:52224
	ds_read_b128 v[200:203], v154 offset:53248
	ds_read_b128 v[204:207], v154 offset:54272
	ds_read_b128 v[208:211], v154 offset:55296
	ds_read_b128 v[212:215], v154 offset:56320
	global_load_lds_dwordx4 v[216:217], off
	s_add_i32 m0, s62, 0x2000
	s_add_u32 s60, s60, 0x40080
	v_lshl_add_u64 v[216:217], v[218:219], 0, s[10:11]
	s_addc_u32 s61, s61, 0
	s_add_i32 s62, s91, s67
	global_load_lds_dwordx4 v[216:217], off
	v_lshl_add_u64 v[216:217], s[60:61], 0, v[130:131]
	s_mov_b32 m0, s62
	s_nop 0
	global_load_lds_dwordx4 v[216:217], off
	v_lshl_add_u64 v[216:217], s[60:61], 0, v[134:135]
	s_add_i32 m0, s62, 0x2000
	s_nop 0
	global_load_lds_dwordx4 v[216:217], off
	v_lshl_add_u64 v[216:217], v[220:221], 0, s[10:11]
	s_mov_b32 m0, s74
	s_nop 0
	global_load_lds_dwordx4 v[216:217], off
	v_lshl_add_u64 v[216:217], v[222:223], 0, s[10:11]
	s_mov_b32 m0, s75
	s_nop 0
	global_load_lds_dwordx4 v[216:217], off
	s_waitcnt vmcnt(8)
	s_waitcnt lgkmcnt(0)
	s_barrier
	s_setprio 2
	s_waitcnt lgkmcnt(0)
	v_mfma_f32_16x16x32_bf16 v[28:31], v[146:149], v[184:187], v[28:31]
	v_mfma_f32_16x16x32_bf16 v[24:27], v[160:163], v[184:187], v[24:27]
	v_mfma_f32_16x16x32_bf16 v[20:23], v[146:149], v[192:195], v[20:23]
	v_mfma_f32_16x16x32_bf16 v[16:19], v[160:163], v[192:195], v[16:19]
	v_mfma_f32_16x16x32_bf16 v[12:15], v[146:149], v[200:203], v[12:15]
	v_mfma_f32_16x16x32_bf16 v[8:11], v[160:163], v[200:203], v[8:11]
	v_mfma_f32_16x16x32_bf16 v[4:7], v[146:149], v[208:211], v[4:7]
	v_mfma_f32_16x16x32_bf16 v[0:3], v[160:163], v[208:211], v[0:3]
	s_setprio 0
	s_setprio 2
	v_mfma_f32_16x16x32_bf16 v[28:31], v[156:159], v[188:191], v[28:31]
	v_mfma_f32_16x16x32_bf16 v[24:27], v[164:167], v[188:191], v[24:27]
	v_mfma_f32_16x16x32_bf16 v[20:23], v[156:159], v[196:199], v[20:23]
	v_mfma_f32_16x16x32_bf16 v[16:19], v[164:167], v[196:199], v[16:19]
	v_mfma_f32_16x16x32_bf16 v[12:15], v[156:159], v[204:207], v[12:15]
	v_mfma_f32_16x16x32_bf16 v[8:11], v[164:167], v[204:207], v[8:11]
	v_mfma_f32_16x16x32_bf16 v[4:7], v[156:159], v[212:215], v[4:7]
	v_mfma_f32_16x16x32_bf16 v[0:3], v[164:167], v[212:215], v[0:3]
	s_setprio 0
	s_setprio 2
	v_mfma_f32_16x16x32_bf16 v[92:95], v[168:171], v[184:187], v[92:95]
	v_mfma_f32_16x16x32_bf16 v[88:91], v[176:179], v[184:187], v[88:91]
	v_mfma_f32_16x16x32_bf16 v[84:87], v[168:171], v[192:195], v[84:87]
	v_mfma_f32_16x16x32_bf16 v[80:83], v[176:179], v[192:195], v[80:83]
	v_mfma_f32_16x16x32_bf16 v[60:63], v[168:171], v[200:203], v[60:63]
	v_mfma_f32_16x16x32_bf16 v[48:51], v[176:179], v[200:203], v[48:51]
	v_mfma_f32_16x16x32_bf16 v[36:39], v[168:171], v[208:211], v[36:39]
	v_mfma_f32_16x16x32_bf16 v[32:35], v[176:179], v[208:211], v[32:35]
	s_setprio 0
	s_setprio 2
	v_mfma_f32_16x16x32_bf16 v[92:95], v[172:175], v[188:191], v[92:95]
	v_mfma_f32_16x16x32_bf16 v[88:91], v[180:183], v[188:191], v[88:91]
	v_mfma_f32_16x16x32_bf16 v[84:87], v[172:175], v[196:199], v[84:87]
	v_mfma_f32_16x16x32_bf16 v[80:83], v[180:183], v[196:199], v[80:83]
	v_mfma_f32_16x16x32_bf16 v[60:63], v[172:175], v[204:207], v[60:63]
	v_mfma_f32_16x16x32_bf16 v[48:51], v[180:183], v[204:207], v[48:51]
	v_mfma_f32_16x16x32_bf16 v[36:39], v[172:175], v[212:215], v[36:39]
	s_setprio 3
	s_barrier
	v_mfma_f32_16x16x32_bf16 v[32:35], v[180:183], v[212:215], v[32:35]
	s_setprio 0
	s_add_i32 s87, s87, 2
	s_add_u32 s58, s58, 0x100
	s_addc_u32 s59, s59, 0
	s_add_u32 s85, s85, 0x100
	s_addc_u32 s86, s86, 0
	s_cmp_gt_u32 s87, 13
	s_cbranch_scc0 .LBB0_1049
	s_and_b64 vcc, exec, s[12:13]
	s_cbranch_vccz .LBB0_1052
	s_barrier

; #define PG8_STAGE(bufoff, gbase, voff) do { _Pragma("unroll") for (int _i = 0; _i < 2; ++_i) \
;         __builtin_amdgcn_global_load_lds((const unsigned*)((const char*)(gbase) + (voff)[_i]), (PG8_LAS unsigned*)(lds + (bufoff) + ldsw + _i * 8192), 16, 0, 0); } while (0)
; #define PG8_LDA(dst, b, h) do { _Pragma("unroll") for (int m = 0; m < 4; ++m) _Pragma("unroll") for (int k = 0; k < 2; ++k) dst[m][k] = *(const PG8_LAS bf16x8*)(lds + PG8_SA(b, h) + aoff + m * 2048 + k * 1024); } while (0)
; #define PG8_LDB(dst, b, h) do { _Pragma("unroll") for (int n = 0; n < 2; ++n) _Pragma("unroll") for (int k = 0; k < 2; ++k) dst[n][k] = *(const PG8_LAS bf16x8*)(lds + PG8_SB(b, h) + boff + n * 2048 + k * 1024); } while (0)
; #define PG8_MMA(ai, bj, At, Bt) do { __builtin_amdgcn_s_setprio(1); _Pragma("unroll") for (int m = 0; m < 4; ++m) _Pragma("unroll") for (int n = 0; n < 2; ++n) _Pragma("unroll") for (int k = 0; k < 2; ++k) \
;         acc[ai][bj][m][n] = __builtin_amdgcn_mfma_f32_16x16x32_bf16(Bt[n][k], At[m][k], acc[ai][bj][m][n], 0, 0, 0); __builtin_amdgcn_s_setprio(0); } while (0)
; #define PG8_WAIT_V(n) asm volatile("s_waitcnt vmcnt(" #n ")" ::: "memory")
; #define PG8_WAIT_L(n) asm volatile("s_waitcnt lgkmcnt(" #n ")" ::: "memory")
; #define PG8_BAR __builtin_amdgcn_s_barrier()
; template <class Epi, class Sched, bool ALIGN_EPI = false, bool SP2 = false>
; __device__ __forceinline__ void gemm_phase(PG8_LAS unsigned char* lds, const Gemm g, const Sched& S, const Epi& E, const int wv  ) {
;     ...
;         for (int t = 0; t < nt; t += 2) {
;             const bool last = (t == nt - 2);
;             const char* a1 = cA + (size_t)(t + 1) * kstep;
;             const char* a2 = last ? nA : cA + (size_t)(t + 2) * kstep; const char* b2 = last ? nB : cB + (size_t)(t + 2) * kstep;
;             const char* a3 = a2 + kstep; const char* b3 = b2 + kstep;
;             if (last && has_next) S.a_ready(nxt);
;             if constexpr (SP2) {
;             PG8_LDB(B0, 0, 0); PG8_LDB(B1, 0, 1); PG8_SCHED; PG8_LDA(At, 0, 0); PG8_STAGE(PG8_SA(1, 1), a1 + hstepA, voffA);
;             PG8_WAIT_V(8); PG8_WAIT_L(0); PG8_BAR; PG8_MMA(0, 0, At, B0); PG8_MMA(0, 1, At, B1); PG8_BAR; PG8_SCHED;
;             PG8_LDA(At, 0, 1); PG8_STAGE(PG8_SB(0, 0), b2, voffB); PG8_STAGE(PG8_SB(0, 1), b2 + hstepB, voffB); PG8_STAGE(PG8_SA(0, 0), a2, voffA);
.LBB0_1187:
	ds_read_b128 v[44:47], v196
	ds_read_b128 v[48:51], v196 offset:1024
	ds_read_b128 v[52:55], v196 offset:2048
	ds_read_b128 v[56:59], v196 offset:3072
	ds_read_b128 v[60:63], v197
	ds_read_b128 v[68:71], v197 offset:1024
	ds_read_b128 v[72:75], v197 offset:2048
	ds_read_b128 v[76:79], v197 offset:3072
	s_add_u32 s68, s66, 0xfff00080
	s_addc_u32 s69, s67, -1
	s_cmp_eq_u32 s94, 60
	s_cselect_b32 s71, s57, s69
	s_cselect_b32 s70, s63, s68
	s_cselect_b32 s69, s55, s93
	s_cselect_b32 s68, s65, s92
	v_lshl_add_u64 v[224:225], s[66:67], 0, v[172:173]
	s_add_i32 m0, s75, 0xc000
	ds_read_b128 v[180:183], v198
	ds_read_b128 v[184:187], v198 offset:1024
	ds_read_b128 v[200:203], v198 offset:2048
	ds_read_b128 v[204:207], v198 offset:3072
	ds_read_b128 v[208:211], v198 offset:4096
	ds_read_b128 v[212:215], v198 offset:5120
	ds_read_b128 v[216:219], v198 offset:6144
	ds_read_b128 v[220:223], v198 offset:7168
	global_load_lds_dwordx4 v[224:225], off
	v_lshl_add_u64 v[224:225], s[66:67], 0, v[174:175]
	s_add_i32 m0, s75, 0xe000
	s_nop 0
	global_load_lds_dwordx4 v[224:225], off
	s_waitcnt vmcnt(8)
	s_waitcnt lgkmcnt(0)
	s_barrier
	s_setprio 2
	s_waitcnt lgkmcnt(0)
	v_mfma_f32_16x16x32_bf16 v[104:107], v[44:47], v[180:183], v[104:107]
	v_mfma_f32_16x16x32_bf16 v[100:103], v[52:55], v[180:183], v[100:103]
	v_mfma_f32_16x16x32_bf16 v[156:159], v[44:47], v[200:203], v[156:159]
	v_mfma_f32_16x16x32_bf16 v[148:151], v[52:55], v[200:203], v[148:151]
	v_mfma_f32_16x16x32_bf16 v[140:143], v[44:47], v[208:211], v[140:143]
	v_mfma_f32_16x16x32_bf16 v[132:135], v[52:55], v[208:211], v[132:135]
	v_mfma_f32_16x16x32_bf16 v[124:127], v[44:47], v[216:219], v[124:127]
	v_mfma_f32_16x16x32_bf16 v[120:123], v[52:55], v[216:219], v[120:123]
	s_setprio 0
	s_setprio 2
	v_mfma_f32_16x16x32_bf16 v[104:107], v[48:51], v[184:187], v[104:107]
	v_mfma_f32_16x16x32_bf16 v[100:103], v[56:59], v[184:187], v[100:103]
	v_mfma_f32_16x16x32_bf16 v[156:159], v[48:51], v[204:207], v[156:159]
	v_mfma_f32_16x16x32_bf16 v[148:151], v[56:59], v[204:207], v[148:151]
	v_mfma_f32_16x16x32_bf16 v[140:143], v[48:51], v[212:215], v[140:143]
	v_mfma_f32_16x16x32_bf16 v[132:135], v[56:59], v[212:215], v[132:135]
	v_mfma_f32_16x16x32_bf16 v[124:127], v[48:51], v[220:223], v[124:127]
	v_mfma_f32_16x16x32_bf16 v[120:123], v[56:59], v[220:223], v[120:123]
	s_setprio 0
	s_setprio 2
	v_mfma_f32_16x16x32_bf16 v[92:95], v[60:63], v[180:183], v[92:95]
	v_mfma_f32_16x16x32_bf16 v[88:91], v[72:75], v[180:183], v[88:91]
	v_mfma_f32_16x16x32_bf16 v[152:155], v[60:63], v[200:203], v[152:155]
	v_mfma_f32_16x16x32_bf16 v[144:147], v[72:75], v[200:203], v[144:147]
	v_mfma_f32_16x16x32_bf16 v[136:139], v[60:63], v[208:211], v[136:139]
	v_mfma_f32_16x16x32_bf16 v[128:131], v[72:75], v[208:211], v[128:131]
	v_mfma_f32_16x16x32_bf16 v[116:119], v[60:63], v[216:219], v[116:119]
	v_mfma_f32_16x16x32_bf16 v[112:115], v[72:75], v[216:219], v[112:115]
	s_setprio 0
	s_setprio 2
	v_mfma_f32_16x16x32_bf16 v[92:95], v[68:71], v[184:187], v[92:95]
	v_mfma_f32_16x16x32_bf16 v[88:91], v[76:79], v[184:187], v[88:91]
	v_mfma_f32_16x16x32_bf16 v[152:155], v[68:71], v[204:207], v[152:155]
	v_mfma_f32_16x16x32_bf16 v[144:147], v[76:79], v[204:207], v[144:147]
	v_mfma_f32_16x16x32_bf16 v[136:139], v[68:71], v[212:215], v[136:139]
	v_mfma_f32_16x16x32_bf16 v[128:131], v[76:79], v[212:215], v[128:131]
	v_mfma_f32_16x16x32_bf16 v[116:119], v[68:71], v[220:223], v[116:119]
	s_setprio 3
	s_barrier
	v_mfma_f32_16x16x32_bf16 v[112:115], v[76:79], v[220:223], v[112:115]
	s_setprio 0
	s_add_i32 s95, s87, s74
	v_lshl_add_u64 v[228:229], s[68:69], 0, v[162:163]
	s_mov_b32 m0, s95
	ds_read_b128 v[180:183], v198 offset:16384
	ds_read_b128 v[184:187], v198 offset:17408
	ds_read_b128 v[200:203], v198 offset:18432
	ds_read_b128 v[204:207], v198 offset:19456
	ds_read_b128 v[208:211], v198 offset:20480
	ds_read_b128 v[212:215], v198 offset:21504
	ds_read_b128 v[216:219], v198 offset:22528
	ds_read_b128 v[220:223], v198 offset:23552
	global_load_lds_dwordx4 v[228:229], off
	s_add_i32 m0, s95, 0x2000
	s_add_u32 s96, s68, 0x100000
	v_lshl_add_u64 v[230:231], s[68:69], 0, v[166:167]
	s_addc_u32 s97, s69, 0
	s_add_i32 s95, s90, s74
	global_load_lds_dwordx4 v[230:231], off
	v_lshl_add_u64 v[224:225], s[96:97], 0, v[162:163]
	s_mov_b32 m0, s95
	v_lshl_add_u64 v[232:233], s[70:71], 0, v[160:161]
	global_load_lds_dwordx4 v[224:225], off
	v_lshl_add_u64 v[224:225], s[96:97], 0, v[166:167]
	s_add_i32 m0, s95, 0x2000
	v_lshl_add_u64 v[234:235], s[70:71], 0, v[164:165]
	global_load_lds_dwordx4 v[224:225], off
	s_mov_b32 m0, s75
	s_nop 0
	global_load_lds_dwordx4 v[232:233], off
	s_mov_b32 m0, s76
	s_nop 0
	global_load_lds_dwordx4 v[234:235], off
	s_waitcnt vmcnt(8)
	s_waitcnt lgkmcnt(0)
	s_barrier
; #define PG8_STAGE(bufoff, gbase, voff) do { _Pragma("unroll") for (int _i = 0; _i < 2; ++_i) \
;         __builtin_amdgcn_global_load_lds((const unsigned*)((const char*)(gbase) + (voff)[_i]), (PG8_LAS unsigned*)(lds + (bufoff) + ldsw + _i * 8192), 16, 0, 0); } while (0)
; #define PG8_LDA(dst, b, h) do { _Pragma("unroll") for (int m = 0; m < 4; ++m) _Pragma("unroll") for (int k = 0; k < 2; ++k) dst[m][k] = *(const PG8_LAS bf16x8*)(lds + PG8_SA(b, h) + aoff + m * 2048 + k * 1024); } while (0)
; #define PG8_LDB(dst, b, h) do { _Pragma("unroll") for (int n = 0; n < 2; ++n) _Pragma("unroll") for (int k = 0; k < 2; ++k) dst[n][k] = *(const PG8_LAS bf16x8*)(lds + PG8_SB(b, h) + boff + n * 2048 + k * 1024); } while (0)
; #define PG8_MMA(ai, bj, At, Bt) do { __builtin_amdgcn_s_setprio(1); _Pragma("unroll") for (int m = 0; m < 4; ++m) _Pragma("unroll") for (int n = 0; n < 2; ++n) _Pragma("unroll") for (int k = 0; k < 2; ++k) \
;         acc[ai][bj][m][n] = __builtin_amdgcn_mfma_f32_16x16x32_bf16(Bt[n][k], At[m][k], acc[ai][bj][m][n], 0, 0, 0); __builtin_amdgcn_s_setprio(0); } while (0)
; #define PG8_WAIT_V(n) asm volatile("s_waitcnt vmcnt(" #n ")" ::: "memory")
; #define PG8_WAIT_L(n) asm volatile("s_waitcnt lgkmcnt(" #n ")" ::: "memory")
; #define PG8_BAR __builtin_amdgcn_s_barrier()
; #define PG8_SCHED __builtin_amdgcn_sched_barrier(0)
; template <class Epi, class Sched, bool ALIGN_EPI = false, bool SP2 = false>
; __device__ __forceinline__ void gemm_phase(PG8_LAS unsigned char* lds, const Gemm g, const Sched& S, const Epi& E, const int wv  ) {
;     ...
;             PG8_WAIT_V(8); PG8_WAIT_L(0); PG8_BAR; PG8_MMA(1, 0, At, B0); PG8_MMA(1, 1, At, B1); PG8_BAR; PG8_SCHED;
;             PG8_LDB(B0, 1, 0); PG8_LDB(B1, 1, 1); PG8_SCHED; PG8_LDA(At, 1, 0); PG8_STAGE(PG8_SA(0, 1), a2 + hstepA, voffA);
;             PG8_WAIT_V(8); PG8_WAIT_L(0); PG8_BAR; PG8_MMA(0, 0, At, B0); PG8_MMA(0, 1, At, B1); PG8_BAR; PG8_SCHED;
	s_setprio 2
	s_waitcnt lgkmcnt(0)
	v_mfma_f32_16x16x32_bf16 v[108:111], v[44:47], v[180:183], v[108:111]
	v_mfma_f32_16x16x32_bf16 v[96:99], v[52:55], v[180:183], v[96:99]
	v_mfma_f32_16x16x32_bf16 v[64:67], v[44:47], v[200:203], v[64:67]
	v_mfma_f32_16x16x32_bf16 v[36:39], v[52:55], v[200:203], v[36:39]
	v_mfma_f32_16x16x32_bf16 v[28:31], v[44:47], v[208:211], v[28:31]
	v_mfma_f32_16x16x32_bf16 v[20:23], v[52:55], v[208:211], v[20:23]
	v_mfma_f32_16x16x32_bf16 v[12:15], v[44:47], v[216:219], v[12:15]
	v_mfma_f32_16x16x32_bf16 v[4:7], v[52:55], v[216:219], v[4:7]
	s_setprio 0
	s_setprio 2
	v_mfma_f32_16x16x32_bf16 v[108:111], v[48:51], v[184:187], v[108:111]
	v_mfma_f32_16x16x32_bf16 v[96:99], v[56:59], v[184:187], v[96:99]
	v_mfma_f32_16x16x32_bf16 v[64:67], v[48:51], v[204:207], v[64:67]
	v_mfma_f32_16x16x32_bf16 v[36:39], v[56:59], v[204:207], v[36:39]
	v_mfma_f32_16x16x32_bf16 v[28:31], v[48:51], v[212:215], v[28:31]
	v_mfma_f32_16x16x32_bf16 v[20:23], v[56:59], v[212:215], v[20:23]
	v_mfma_f32_16x16x32_bf16 v[12:15], v[48:51], v[220:223], v[12:15]
	v_mfma_f32_16x16x32_bf16 v[4:7], v[56:59], v[220:223], v[4:7]
	s_setprio 0
	s_setprio 2
	v_mfma_f32_16x16x32_bf16 v[40:43], v[60:63], v[200:203], v[40:43]
	v_mfma_f32_16x16x32_bf16 v[32:35], v[72:75], v[200:203], v[32:35]
	v_mfma_f32_16x16x32_bf16 v[24:27], v[60:63], v[208:211], v[24:27]
	v_mfma_f32_16x16x32_bf16 v[16:19], v[72:75], v[208:211], v[16:19]
	v_mfma_f32_16x16x32_bf16 v[8:11], v[60:63], v[216:219], v[8:11]
	v_mfma_f32_16x16x32_bf16 v[0:3], v[72:75], v[216:219], v[0:3]
	v_mfma_f32_16x16x32_bf16 v[44:47], v[60:63], v[180:183], v[84:87]
	v_mfma_f32_16x16x32_bf16 v[48:51], v[72:75], v[180:183], v[80:83]
	s_setprio 0
	s_setprio 2
	v_mfma_f32_16x16x32_bf16 v[40:43], v[68:71], v[204:207], v[40:43]
	v_mfma_f32_16x16x32_bf16 v[32:35], v[76:79], v[204:207], v[32:35]
	v_mfma_f32_16x16x32_bf16 v[24:27], v[68:71], v[212:215], v[24:27]
	v_mfma_f32_16x16x32_bf16 v[16:19], v[76:79], v[212:215], v[16:19]
	v_mfma_f32_16x16x32_bf16 v[8:11], v[68:71], v[220:223], v[8:11]
	v_mfma_f32_16x16x32_bf16 v[0:3], v[76:79], v[220:223], v[0:3]
	v_mfma_f32_16x16x32_bf16 v[44:47], v[68:71], v[184:187], v[44:47]
	s_setprio 3
	s_barrier
	v_mfma_f32_16x16x32_bf16 v[48:51], v[76:79], v[184:187], v[48:51]
	s_setprio 0
	s_add_i32 s95, 0, 0x18000
	s_add_i32 s96, 0, 0x1c000
	v_add_u32_e32 v68, s95, v190
	v_add_u32_e32 v80, s96, v190
	ds_read_b128 v[52:55], v68
	ds_read_b128 v[56:59], v68 offset:1024
	ds_read_b128 v[60:63], v68 offset:2048
	ds_read_b128 v[68:71], v68 offset:3072
	ds_read_b128 v[72:75], v80
	ds_read_b128 v[76:79], v80 offset:1024
	ds_read_b128 v[180:183], v80 offset:2048
	ds_read_b128 v[184:187], v80 offset:3072
	s_add_u32 s70, s70, 0x100000
	s_addc_u32 s71, s71, 0
	s_mov_b32 m0, s77
	v_lshl_add_u64 v[224:225], s[70:71], 0, v[160:161]
	ds_read_b128 v[80:83], v198 offset:32768
	ds_read_b128 v[84:87], v198 offset:33792
	ds_read_b128 v[200:203], v198 offset:34816
	ds_read_b128 v[204:207], v198 offset:35840
	ds_read_b128 v[208:211], v198 offset:36864
	ds_read_b128 v[212:215], v198 offset:37888
	ds_read_b128 v[216:219], v198 offset:38912
	ds_read_b128 v[220:223], v198 offset:39936
	global_load_lds_dwordx4 v[224:225], off
	v_lshl_add_u64 v[224:225], s[70:71], 0, v[164:165]
	s_mov_b32 m0, s78
	s_nop 0
	global_load_lds_dwordx4 v[224:225], off
	s_waitcnt vmcnt(8)
	s_waitcnt lgkmcnt(0)
	s_barrier
	s_setprio 2
	s_waitcnt lgkmcnt(0)
	v_mfma_f32_16x16x32_bf16 v[104:107], v[52:55], v[80:83], v[104:107]
	v_mfma_f32_16x16x32_bf16 v[100:103], v[60:63], v[80:83], v[100:103]
	v_mfma_f32_16x16x32_bf16 v[156:159], v[52:55], v[200:203], v[156:159]
	v_mfma_f32_16x16x32_bf16 v[148:151], v[60:63], v[200:203], v[148:151]
	v_mfma_f32_16x16x32_bf16 v[140:143], v[52:55], v[208:211], v[140:143]
	v_mfma_f32_16x16x32_bf16 v[132:135], v[60:63], v[208:211], v[132:135]
	v_mfma_f32_16x16x32_bf16 v[124:127], v[52:55], v[216:219], v[124:127]
	v_mfma_f32_16x16x32_bf16 v[120:123], v[60:63], v[216:219], v[120:123]
	s_setprio 0
	s_setprio 2
	v_mfma_f32_16x16x32_bf16 v[104:107], v[56:59], v[84:87], v[104:107]
	v_mfma_f32_16x16x32_bf16 v[100:103], v[68:71], v[84:87], v[100:103]
	v_mfma_f32_16x16x32_bf16 v[156:159], v[56:59], v[204:207], v[156:159]
	v_mfma_f32_16x16x32_bf16 v[148:151], v[68:71], v[204:207], v[148:151]
	v_mfma_f32_16x16x32_bf16 v[140:143], v[56:59], v[212:215], v[140:143]
	v_mfma_f32_16x16x32_bf16 v[132:135], v[68:71], v[212:215], v[132:135]
	v_mfma_f32_16x16x32_bf16 v[124:127], v[56:59], v[220:223], v[124:127]
	v_mfma_f32_16x16x32_bf16 v[120:123], v[68:71], v[220:223], v[120:123]
	s_setprio 0
	s_setprio 2
	v_mfma_f32_16x16x32_bf16 v[92:95], v[72:75], v[80:83], v[92:95]
	v_mfma_f32_16x16x32_bf16 v[80:83], v[180:183], v[80:83], v[88:91]
	v_mfma_f32_16x16x32_bf16 v[88:91], v[184:187], v[84:87], v[80:83]
	v_mfma_f32_16x16x32_bf16 v[80:83], v[72:75], v[200:203], v[152:155]
	v_mfma_f32_16x16x32_bf16 v[152:155], v[76:79], v[204:207], v[80:83]
	v_mfma_f32_16x16x32_bf16 v[80:83], v[180:183], v[200:203], v[144:147]
	v_mfma_f32_16x16x32_bf16 v[144:147], v[184:187], v[204:207], v[80:83]
	v_mfma_f32_16x16x32_bf16 v[80:83], v[72:75], v[208:211], v[136:139]
	s_setprio 0
	s_setprio 2
	v_mfma_f32_16x16x32_bf16 v[136:139], v[76:79], v[212:215], v[80:83]
	v_mfma_f32_16x16x32_bf16 v[80:83], v[180:183], v[208:211], v[128:131]
	v_mfma_f32_16x16x32_bf16 v[128:131], v[184:187], v[212:215], v[80:83]
	v_mfma_f32_16x16x32_bf16 v[80:83], v[72:75], v[216:219], v[116:119]
	v_mfma_f32_16x16x32_bf16 v[116:119], v[76:79], v[220:223], v[80:83]
	v_mfma_f32_16x16x32_bf16 v[80:83], v[180:183], v[216:219], v[112:115]
	v_mfma_f32_16x16x32_bf16 v[92:95], v[76:79], v[84:87], v[92:95]
	s_setprio 3
	s_barrier
; #define PG8_STAGE(bufoff, gbase, voff) do { _Pragma("unroll") for (int _i = 0; _i < 2; ++_i) \
;         __builtin_amdgcn_global_load_lds((const unsigned*)((const char*)(gbase) + (voff)[_i]), (PG8_LAS unsigned*)(lds + (bufoff) + ldsw + _i * 8192), 16, 0, 0); } while (0)
; #define PG8_LDA(dst, b, h) do { _Pragma("unroll") for (int m = 0; m < 4; ++m) _Pragma("unroll") for (int k = 0; k < 2; ++k) dst[m][k] = *(const PG8_LAS bf16x8*)(lds + PG8_SA(b, h) + aoff + m * 2048 + k * 1024); } while (0)
; #define PG8_MMA(ai, bj, At, Bt) do { __builtin_amdgcn_s_setprio(1); _Pragma("unroll") for (int m = 0; m < 4; ++m) _Pragma("unroll") for (int n = 0; n < 2; ++n) _Pragma("unroll") for (int k = 0; k < 2; ++k) \
;         acc[ai][bj][m][n] = __builtin_amdgcn_mfma_f32_16x16x32_bf16(Bt[n][k], At[m][k], acc[ai][bj][m][n], 0, 0, 0); __builtin_amdgcn_s_setprio(0); } while (0)
; #define PG8_WAIT_V(n) asm volatile("s_waitcnt vmcnt(" #n ")" ::: "memory")
; #define PG8_WAIT_L(n) asm volatile("s_waitcnt lgkmcnt(" #n ")" ::: "memory")
; #define PG8_BAR __builtin_amdgcn_s_barrier()
; #define PG8_SCHED __builtin_amdgcn_sched_barrier(0)
; template <class Epi, class Sched, bool ALIGN_EPI = false, bool SP2 = false>
; __device__ __forceinline__ void gemm_phase(PG8_LAS unsigned char* lds, const Gemm g, const Sched& S, const Epi& E, const int wv  ) {
;     ...
;             PG8_LDA(At, 1, 1); PG8_STAGE(PG8_SB(1, 0), b3, voffB); PG8_STAGE(PG8_SB(1, 1), b3 + hstepB, voffB); PG8_STAGE(PG8_SA(1, 0), a3, voffA);
;             PG8_WAIT_V(8); PG8_WAIT_L(0); PG8_BAR; PG8_MMA(1, 0, At, B0); PG8_MMA(1, 1, At, B1); PG8_BAR; PG8_SCHED;
;     ...
;         if constexpr (ALIGN_EPI) { if (wr == 0) PG8_BAR; }
;         if constexpr (!Epi::AFTER_DRAIN) { E(acc, cur, wr, wc, fr, fq); S.done(cur); }
;         if (!has_next) break;
	v_mfma_f32_16x16x32_bf16 v[112:115], v[184:187], v[220:223], v[80:83]
	s_setprio 0
	s_add_i32 s70, s95, s74
	v_lshl_add_u64 v[84:85], v[228:229], 0, s[18:19]
	s_mov_b32 m0, s70
	s_nop 0
	ds_read_b128 v[80:83], v198 offset:49152
	ds_read_b128 v[200:203], v198 offset:50176
	ds_read_b128 v[204:207], v198 offset:51200
	ds_read_b128 v[208:211], v198 offset:52224
	ds_read_b128 v[212:215], v198 offset:53248
	ds_read_b128 v[216:219], v198 offset:54272
	ds_read_b128 v[220:223], v198 offset:55296
	ds_read_b128 v[224:227], v198 offset:56320
	global_load_lds_dwordx4 v[84:85], off
	s_add_i32 m0, s70, 0x2000
	s_add_u32 s68, s68, 0x100080
	v_lshl_add_u64 v[84:85], v[230:231], 0, s[18:19]
	s_addc_u32 s69, s69, 0
	s_add_i32 s70, s96, s74
	global_load_lds_dwordx4 v[84:85], off
	v_lshl_add_u64 v[84:85], s[68:69], 0, v[162:163]
	s_mov_b32 m0, s70
	s_nop 0
	global_load_lds_dwordx4 v[84:85], off
	v_lshl_add_u64 v[84:85], s[68:69], 0, v[166:167]
	s_add_i32 m0, s70, 0x2000
	s_nop 0
	global_load_lds_dwordx4 v[84:85], off
	v_lshl_add_u64 v[84:85], v[232:233], 0, s[18:19]
	s_mov_b32 m0, s82
	s_nop 0
	global_load_lds_dwordx4 v[84:85], off
	v_lshl_add_u64 v[84:85], v[234:235], 0, s[18:19]
	s_mov_b32 m0, s83
	s_nop 0
	global_load_lds_dwordx4 v[84:85], off
	s_waitcnt vmcnt(8)
	s_waitcnt lgkmcnt(0)
	s_barrier
	s_setprio 2
	s_waitcnt lgkmcnt(0)
	v_mfma_f32_16x16x32_bf16 v[84:87], v[52:55], v[80:83], v[108:111]
	v_mfma_f32_16x16x32_bf16 v[108:111], v[56:59], v[200:203], v[84:87]
	v_mfma_f32_16x16x32_bf16 v[84:87], v[60:63], v[80:83], v[96:99]
	v_mfma_f32_16x16x32_bf16 v[64:67], v[52:55], v[204:207], v[64:67]
	v_mfma_f32_16x16x32_bf16 v[36:39], v[60:63], v[204:207], v[36:39]
	v_mfma_f32_16x16x32_bf16 v[28:31], v[52:55], v[212:215], v[28:31]
	v_mfma_f32_16x16x32_bf16 v[20:23], v[60:63], v[212:215], v[20:23]
	v_mfma_f32_16x16x32_bf16 v[12:15], v[52:55], v[220:223], v[12:15]
	s_setprio 0
	s_setprio 2
	v_mfma_f32_16x16x32_bf16 v[4:7], v[60:63], v[220:223], v[4:7]
	v_mfma_f32_16x16x32_bf16 v[96:99], v[68:71], v[200:203], v[84:87]
	v_mfma_f32_16x16x32_bf16 v[64:67], v[56:59], v[208:211], v[64:67]
	v_mfma_f32_16x16x32_bf16 v[36:39], v[68:71], v[208:211], v[36:39]
	v_mfma_f32_16x16x32_bf16 v[28:31], v[56:59], v[216:219], v[28:31]
	v_mfma_f32_16x16x32_bf16 v[20:23], v[68:71], v[216:219], v[20:23]
	v_mfma_f32_16x16x32_bf16 v[12:15], v[56:59], v[224:227], v[12:15]
	v_mfma_f32_16x16x32_bf16 v[4:7], v[68:71], v[224:227], v[4:7]
	s_setprio 0
	s_setprio 2
	v_mfma_f32_16x16x32_bf16 v[44:47], v[72:75], v[80:83], v[44:47]
	v_mfma_f32_16x16x32_bf16 v[84:87], v[76:79], v[200:203], v[44:47]
	v_mfma_f32_16x16x32_bf16 v[44:47], v[180:183], v[80:83], v[48:51]
	v_mfma_f32_16x16x32_bf16 v[40:43], v[72:75], v[204:207], v[40:43]
	v_mfma_f32_16x16x32_bf16 v[32:35], v[180:183], v[204:207], v[32:35]
	v_mfma_f32_16x16x32_bf16 v[24:27], v[72:75], v[212:215], v[24:27]
	v_mfma_f32_16x16x32_bf16 v[16:19], v[180:183], v[212:215], v[16:19]
	v_mfma_f32_16x16x32_bf16 v[8:11], v[72:75], v[220:223], v[8:11]
	s_setprio 0
	s_setprio 2
	v_mfma_f32_16x16x32_bf16 v[0:3], v[180:183], v[220:223], v[0:3]
	v_mfma_f32_16x16x32_bf16 v[80:83], v[184:187], v[200:203], v[44:47]
	v_mfma_f32_16x16x32_bf16 v[40:43], v[76:79], v[208:211], v[40:43]
	v_mfma_f32_16x16x32_bf16 v[32:35], v[184:187], v[208:211], v[32:35]
	v_mfma_f32_16x16x32_bf16 v[24:27], v[76:79], v[216:219], v[24:27]
	v_mfma_f32_16x16x32_bf16 v[16:19], v[184:187], v[216:219], v[16:19]
	v_mfma_f32_16x16x32_bf16 v[8:11], v[76:79], v[224:227], v[8:11]
	s_setprio 3
	s_barrier
	v_mfma_f32_16x16x32_bf16 v[0:3], v[184:187], v[224:227], v[0:3]
	s_setprio 0
	s_add_i32 s94, s94, 2
	s_add_u32 s66, s66, 0x100
	s_addc_u32 s67, s67, 0
	s_add_u32 s92, s92, 0x100
	s_addc_u32 s93, s93, 0
	s_cmp_gt_u32 s94, 61
	s_cbranch_scc0 .LBB0_1187
	s_and_b64 vcc, exec, s[20:21]
	s_cbranch_vccz .LBB0_1190
	s_barrier

; #define PG8_STAGE(bufoff, gbase, voff) do { _Pragma("unroll") for (int _i = 0; _i < 2; ++_i) \
;         __builtin_amdgcn_global_load_lds((const unsigned*)((const char*)(gbase) + (voff)[_i]), (PG8_LAS unsigned*)(lds + (bufoff) + ldsw + _i * 8192), 16, 0, 0); } while (0)
; #define PG8_LDA(dst, b, h) do { _Pragma("unroll") for (int m = 0; m < 4; ++m) _Pragma("unroll") for (int k = 0; k < 2; ++k) dst[m][k] = *(const PG8_LAS bf16x8*)(lds + PG8_SA(b, h) + aoff + m * 2048 + k * 1024); } while (0)
; #define PG8_LDB(dst, b, h) do { _Pragma("unroll") for (int n = 0; n < 2; ++n) _Pragma("unroll") for (int k = 0; k < 2; ++k) dst[n][k] = *(const PG8_LAS bf16x8*)(lds + PG8_SB(b, h) + boff + n * 2048 + k * 1024); } while (0)
; #define PG8_MMA(ai, bj, At, Bt) do { __builtin_amdgcn_s_setprio(1); _Pragma("unroll") for (int m = 0; m < 4; ++m) _Pragma("unroll") for (int n = 0; n < 2; ++n) _Pragma("unroll") for (int k = 0; k < 2; ++k) \
;         acc[ai][bj][m][n] = __builtin_amdgcn_mfma_f32_16x16x32_bf16(Bt[n][k], At[m][k], acc[ai][bj][m][n], 0, 0, 0); __builtin_amdgcn_s_setprio(0); } while (0)
; #define PG8_WAIT_V(n) asm volatile("s_waitcnt vmcnt(" #n ")" ::: "memory")
; #define PG8_WAIT_L(n) asm volatile("s_waitcnt lgkmcnt(" #n ")" ::: "memory")
; #define PG8_BAR __builtin_amdgcn_s_barrier()
; template <class Epi, class Sched, bool ALIGN_EPI = false, bool SP2 = false>
; __device__ __forceinline__ void gemm_phase(PG8_LAS unsigned char* lds, const Gemm g, const Sched& S, const Epi& E, const int wv  ) {
;     ...
;         for (int t = 0; t < nt; t += 2) {
;             const bool last = (t == nt - 2);
;             const char* a1 = cA + (size_t)(t + 1) * kstep;
;             const char* a2 = last ? nA : cA + (size_t)(t + 2) * kstep; const char* b2 = last ? nB : cB + (size_t)(t + 2) * kstep;
;             const char* a3 = a2 + kstep; const char* b3 = b2 + kstep;
;             if (last && has_next) S.a_ready(nxt);
;             if constexpr (SP2) {
;             PG8_LDB(B0, 0, 0); PG8_LDB(B1, 0, 1); PG8_SCHED; PG8_LDA(At, 0, 0); PG8_STAGE(PG8_SA(1, 1), a1 + hstepA, voffA);
;             PG8_WAIT_V(8); PG8_WAIT_L(0); PG8_BAR; PG8_MMA(0, 0, At, B0); PG8_MMA(0, 1, At, B1); PG8_BAR; PG8_SCHED;
;             PG8_LDA(At, 0, 1); PG8_STAGE(PG8_SB(0, 0), b2, voffB); PG8_STAGE(PG8_SB(0, 1), b2 + hstepB, voffB); PG8_STAGE(PG8_SA(0, 0), a2, voffA);
.LBB0_1544:
	ds_read_b128 v[146:149], v152
	ds_read_b128 v[156:159], v152 offset:1024
	ds_read_b128 v[160:163], v152 offset:2048
	ds_read_b128 v[164:167], v152 offset:3072
	ds_read_b128 v[168:171], v153
	ds_read_b128 v[172:175], v153 offset:1024
	ds_read_b128 v[176:179], v153 offset:2048
	ds_read_b128 v[180:183], v153 offset:3072
	s_add_u32 s54, s52, 0x100
	s_addc_u32 s55, s53, 0
	s_cmpk_eq_i32 s85, 0xa8
	s_cselect_b32 s59, s7, s55
	s_cselect_b32 s58, s6, s54
	s_cselect_b32 s57, s51, s84
	s_cselect_b32 s56, s50, s83
	v_lshl_add_u64 v[216:217], s[52:53], 0, v[138:139]
	s_add_i32 m0, s64, 0xc000
	ds_read_b128 v[184:187], v154
	ds_read_b128 v[188:191], v154 offset:1024
	ds_read_b128 v[192:195], v154 offset:2048
	ds_read_b128 v[196:199], v154 offset:3072
	ds_read_b128 v[200:203], v154 offset:4096
	ds_read_b128 v[204:207], v154 offset:5120
	ds_read_b128 v[208:211], v154 offset:6144
	ds_read_b128 v[212:215], v154 offset:7168
	global_load_lds_dwordx4 v[216:217], off
	v_lshl_add_u64 v[216:217], s[52:53], 0, v[140:141]
	s_add_i32 m0, s64, 0xe000
	s_nop 0
	global_load_lds_dwordx4 v[216:217], off
	s_waitcnt vmcnt(8)
	s_waitcnt lgkmcnt(0)
	s_barrier
	s_setprio 2
	s_waitcnt lgkmcnt(0)
	v_mfma_f32_16x16x32_bf16 v[76:79], v[146:149], v[184:187], v[76:79]
	v_mfma_f32_16x16x32_bf16 v[72:75], v[160:163], v[184:187], v[72:75]
	v_mfma_f32_16x16x32_bf16 v[68:71], v[146:149], v[192:195], v[68:71]
	v_mfma_f32_16x16x32_bf16 v[64:67], v[160:163], v[192:195], v[64:67]
	v_mfma_f32_16x16x32_bf16 v[56:59], v[146:149], v[200:203], v[56:59]
	v_mfma_f32_16x16x32_bf16 v[52:55], v[160:163], v[200:203], v[52:55]
	v_mfma_f32_16x16x32_bf16 v[44:47], v[146:149], v[208:211], v[44:47]
	v_mfma_f32_16x16x32_bf16 v[40:43], v[160:163], v[208:211], v[40:43]
	s_setprio 0
	s_setprio 2
	v_mfma_f32_16x16x32_bf16 v[76:79], v[156:159], v[188:191], v[76:79]
	v_mfma_f32_16x16x32_bf16 v[72:75], v[164:167], v[188:191], v[72:75]
	v_mfma_f32_16x16x32_bf16 v[68:71], v[156:159], v[196:199], v[68:71]
	v_mfma_f32_16x16x32_bf16 v[64:67], v[164:167], v[196:199], v[64:67]
	v_mfma_f32_16x16x32_bf16 v[56:59], v[156:159], v[204:207], v[56:59]
	v_mfma_f32_16x16x32_bf16 v[52:55], v[164:167], v[204:207], v[52:55]
	v_mfma_f32_16x16x32_bf16 v[44:47], v[156:159], v[212:215], v[44:47]
	v_mfma_f32_16x16x32_bf16 v[40:43], v[164:167], v[212:215], v[40:43]
	s_setprio 0
	s_setprio 2
	v_mfma_f32_16x16x32_bf16 v[124:127], v[168:171], v[184:187], v[124:127]
	v_mfma_f32_16x16x32_bf16 v[120:123], v[176:179], v[184:187], v[120:123]
	v_mfma_f32_16x16x32_bf16 v[116:119], v[168:171], v[192:195], v[116:119]
	v_mfma_f32_16x16x32_bf16 v[112:115], v[176:179], v[192:195], v[112:115]
	v_mfma_f32_16x16x32_bf16 v[108:111], v[168:171], v[200:203], v[108:111]
	v_mfma_f32_16x16x32_bf16 v[104:107], v[176:179], v[200:203], v[104:107]
	v_mfma_f32_16x16x32_bf16 v[100:103], v[168:171], v[208:211], v[100:103]
	v_mfma_f32_16x16x32_bf16 v[96:99], v[176:179], v[208:211], v[96:99]
	s_setprio 0
	s_setprio 2
	v_mfma_f32_16x16x32_bf16 v[124:127], v[172:175], v[188:191], v[124:127]
	v_mfma_f32_16x16x32_bf16 v[120:123], v[180:183], v[188:191], v[120:123]
	v_mfma_f32_16x16x32_bf16 v[116:119], v[172:175], v[196:199], v[116:119]
	v_mfma_f32_16x16x32_bf16 v[112:115], v[180:183], v[196:199], v[112:115]
	v_mfma_f32_16x16x32_bf16 v[108:111], v[172:175], v[204:207], v[108:111]
	v_mfma_f32_16x16x32_bf16 v[104:107], v[180:183], v[204:207], v[104:107]
	v_mfma_f32_16x16x32_bf16 v[100:103], v[172:175], v[212:215], v[100:103]
	s_setprio 3
	s_barrier
	v_mfma_f32_16x16x32_bf16 v[96:99], v[180:183], v[212:215], v[96:99]
	s_setprio 0
	s_add_i32 s52, s73, s63
	v_lshl_add_u64 v[216:217], s[56:57], 0, v[130:131]
	s_mov_b32 m0, s52
	ds_read_b128 v[184:187], v154 offset:16384
	ds_read_b128 v[188:191], v154 offset:17408
	ds_read_b128 v[192:195], v154 offset:18432
	ds_read_b128 v[196:199], v154 offset:19456
	ds_read_b128 v[200:203], v154 offset:20480
	ds_read_b128 v[204:207], v154 offset:21504
	ds_read_b128 v[208:211], v154 offset:22528
	ds_read_b128 v[212:215], v154 offset:23552
	global_load_lds_dwordx4 v[216:217], off
	s_add_i32 m0, s52, 0x2000
	s_add_u32 s52, s56, 0x2b0000
	v_lshl_add_u64 v[218:219], s[56:57], 0, v[134:135]
	s_addc_u32 s53, s57, 0
	s_add_i32 s86, s74, s63
	global_load_lds_dwordx4 v[218:219], off
	v_lshl_add_u64 v[220:221], s[52:53], 0, v[130:131]
	s_mov_b32 m0, s86
	v_lshl_add_u64 v[222:223], s[58:59], 0, v[132:133]
	global_load_lds_dwordx4 v[220:221], off
	v_lshl_add_u64 v[220:221], s[52:53], 0, v[134:135]
	s_add_i32 m0, s86, 0x2000
	s_nop 0
	global_load_lds_dwordx4 v[220:221], off
	v_lshl_add_u64 v[220:221], s[58:59], 0, v[128:129]
	s_mov_b32 m0, s64
	s_nop 0
	global_load_lds_dwordx4 v[220:221], off
	s_mov_b32 m0, s65
	s_nop 0
	global_load_lds_dwordx4 v[222:223], off
	s_waitcnt vmcnt(8)
	s_waitcnt lgkmcnt(0)
	s_barrier
; #define PG8_STAGE(bufoff, gbase, voff) do { _Pragma("unroll") for (int _i = 0; _i < 2; ++_i) \
;         __builtin_amdgcn_global_load_lds((const unsigned*)((const char*)(gbase) + (voff)[_i]), (PG8_LAS unsigned*)(lds + (bufoff) + ldsw + _i * 8192), 16, 0, 0); } while (0)
; #define PG8_LDA(dst, b, h) do { _Pragma("unroll") for (int m = 0; m < 4; ++m) _Pragma("unroll") for (int k = 0; k < 2; ++k) dst[m][k] = *(const PG8_LAS bf16x8*)(lds + PG8_SA(b, h) + aoff + m * 2048 + k * 1024); } while (0)
; #define PG8_LDB(dst, b, h) do { _Pragma("unroll") for (int n = 0; n < 2; ++n) _Pragma("unroll") for (int k = 0; k < 2; ++k) dst[n][k] = *(const PG8_LAS bf16x8*)(lds + PG8_SB(b, h) + boff + n * 2048 + k * 1024); } while (0)
; #define PG8_MMA(ai, bj, At, Bt) do { __builtin_amdgcn_s_setprio(1); _Pragma("unroll") for (int m = 0; m < 4; ++m) _Pragma("unroll") for (int n = 0; n < 2; ++n) _Pragma("unroll") for (int k = 0; k < 2; ++k) \
;         acc[ai][bj][m][n] = __builtin_amdgcn_mfma_f32_16x16x32_bf16(Bt[n][k], At[m][k], acc[ai][bj][m][n], 0, 0, 0); __builtin_amdgcn_s_setprio(0); } while (0)
; #define PG8_WAIT_V(n) asm volatile("s_waitcnt vmcnt(" #n ")" ::: "memory")
; #define PG8_WAIT_L(n) asm volatile("s_waitcnt lgkmcnt(" #n ")" ::: "memory")
; #define PG8_BAR __builtin_amdgcn_s_barrier()
; #define PG8_SCHED __builtin_amdgcn_sched_barrier(0)
; template <class Epi, class Sched, bool ALIGN_EPI = false, bool SP2 = false>
; __device__ __forceinline__ void gemm_phase(PG8_LAS unsigned char* lds, const Gemm g, const Sched& S, const Epi& E, const int wv  ) {
;     ...
;             PG8_WAIT_V(8); PG8_WAIT_L(0); PG8_BAR; PG8_MMA(1, 0, At, B0); PG8_MMA(1, 1, At, B1); PG8_BAR; PG8_SCHED;
;             PG8_LDB(B0, 1, 0); PG8_LDB(B1, 1, 1); PG8_SCHED; PG8_LDA(At, 1, 0); PG8_STAGE(PG8_SA(0, 1), a2 + hstepA, voffA);
;             PG8_WAIT_V(8); PG8_WAIT_L(0); PG8_BAR; PG8_MMA(0, 0, At, B0); PG8_MMA(0, 1, At, B1); PG8_BAR; PG8_SCHED;
	s_setprio 2
	s_waitcnt lgkmcnt(0)
	v_mfma_f32_16x16x32_bf16 v[28:31], v[146:149], v[184:187], v[28:31]
	v_mfma_f32_16x16x32_bf16 v[24:27], v[160:163], v[184:187], v[24:27]
	v_mfma_f32_16x16x32_bf16 v[20:23], v[146:149], v[192:195], v[20:23]
	v_mfma_f32_16x16x32_bf16 v[16:19], v[160:163], v[192:195], v[16:19]
	v_mfma_f32_16x16x32_bf16 v[12:15], v[146:149], v[200:203], v[12:15]
	v_mfma_f32_16x16x32_bf16 v[8:11], v[160:163], v[200:203], v[8:11]
	v_mfma_f32_16x16x32_bf16 v[4:7], v[146:149], v[208:211], v[4:7]
	v_mfma_f32_16x16x32_bf16 v[0:3], v[160:163], v[208:211], v[0:3]
	s_setprio 0
	s_setprio 2
	v_mfma_f32_16x16x32_bf16 v[28:31], v[156:159], v[188:191], v[28:31]
	v_mfma_f32_16x16x32_bf16 v[24:27], v[164:167], v[188:191], v[24:27]
	v_mfma_f32_16x16x32_bf16 v[20:23], v[156:159], v[196:199], v[20:23]
	v_mfma_f32_16x16x32_bf16 v[16:19], v[164:167], v[196:199], v[16:19]
	v_mfma_f32_16x16x32_bf16 v[12:15], v[156:159], v[204:207], v[12:15]
	v_mfma_f32_16x16x32_bf16 v[8:11], v[164:167], v[204:207], v[8:11]
	v_mfma_f32_16x16x32_bf16 v[4:7], v[156:159], v[212:215], v[4:7]
	v_mfma_f32_16x16x32_bf16 v[0:3], v[164:167], v[212:215], v[0:3]
	s_setprio 0
	s_setprio 2
	v_mfma_f32_16x16x32_bf16 v[92:95], v[168:171], v[184:187], v[92:95]
	v_mfma_f32_16x16x32_bf16 v[88:91], v[176:179], v[184:187], v[88:91]
	v_mfma_f32_16x16x32_bf16 v[84:87], v[168:171], v[192:195], v[84:87]
	v_mfma_f32_16x16x32_bf16 v[80:83], v[176:179], v[192:195], v[80:83]
	v_mfma_f32_16x16x32_bf16 v[60:63], v[168:171], v[200:203], v[60:63]
	v_mfma_f32_16x16x32_bf16 v[48:51], v[176:179], v[200:203], v[48:51]
	v_mfma_f32_16x16x32_bf16 v[36:39], v[168:171], v[208:211], v[36:39]
	v_mfma_f32_16x16x32_bf16 v[32:35], v[176:179], v[208:211], v[32:35]
	s_setprio 0
	s_setprio 2
	v_mfma_f32_16x16x32_bf16 v[92:95], v[172:175], v[188:191], v[92:95]
	v_mfma_f32_16x16x32_bf16 v[88:91], v[180:183], v[188:191], v[88:91]
	v_mfma_f32_16x16x32_bf16 v[84:87], v[172:175], v[196:199], v[84:87]
	v_mfma_f32_16x16x32_bf16 v[80:83], v[180:183], v[196:199], v[80:83]
	v_mfma_f32_16x16x32_bf16 v[60:63], v[172:175], v[204:207], v[60:63]
	v_mfma_f32_16x16x32_bf16 v[48:51], v[180:183], v[204:207], v[48:51]
	v_mfma_f32_16x16x32_bf16 v[36:39], v[172:175], v[212:215], v[36:39]
	s_setprio 3
	s_barrier
	v_mfma_f32_16x16x32_bf16 v[32:35], v[180:183], v[212:215], v[32:35]
	s_setprio 0
	s_add_i32 s86, 0, 0x18000
	v_add_u32_e32 v155, s86, v150
	s_add_i32 s87, 0, 0x1c000
	ds_read_b128 v[146:149], v155
	ds_read_b128 v[156:159], v155 offset:1024
	ds_read_b128 v[160:163], v155 offset:2048
	ds_read_b128 v[164:167], v155 offset:3072
	v_add_u32_e32 v155, s87, v150
	ds_read_b128 v[168:171], v155
	ds_read_b128 v[172:175], v155 offset:1024
	ds_read_b128 v[176:179], v155 offset:2048
	ds_read_b128 v[180:183], v155 offset:3072
	s_add_u32 s52, s58, 0x2b0000
	s_addc_u32 s53, s59, 0
	s_mov_b32 m0, s66
	v_lshl_add_u64 v[224:225], s[52:53], 0, v[128:129]
	ds_read_b128 v[184:187], v154 offset:32768
	ds_read_b128 v[188:191], v154 offset:33792
	ds_read_b128 v[192:195], v154 offset:34816
	ds_read_b128 v[196:199], v154 offset:35840
	ds_read_b128 v[200:203], v154 offset:36864
	ds_read_b128 v[204:207], v154 offset:37888
	ds_read_b128 v[208:211], v154 offset:38912
	ds_read_b128 v[212:215], v154 offset:39936
	global_load_lds_dwordx4 v[224:225], off
	v_lshl_add_u64 v[224:225], s[52:53], 0, v[132:133]
	s_mov_b32 m0, s67
	s_nop 0
	global_load_lds_dwordx4 v[224:225], off
	s_waitcnt vmcnt(8)
	s_waitcnt lgkmcnt(0)
	s_barrier
	s_setprio 2
	s_waitcnt lgkmcnt(0)
	v_mfma_f32_16x16x32_bf16 v[76:79], v[146:149], v[184:187], v[76:79]
	v_mfma_f32_16x16x32_bf16 v[72:75], v[160:163], v[184:187], v[72:75]
	v_mfma_f32_16x16x32_bf16 v[68:71], v[146:149], v[192:195], v[68:71]
	v_mfma_f32_16x16x32_bf16 v[64:67], v[160:163], v[192:195], v[64:67]
	v_mfma_f32_16x16x32_bf16 v[56:59], v[146:149], v[200:203], v[56:59]
	v_mfma_f32_16x16x32_bf16 v[52:55], v[160:163], v[200:203], v[52:55]
	v_mfma_f32_16x16x32_bf16 v[44:47], v[146:149], v[208:211], v[44:47]
	v_mfma_f32_16x16x32_bf16 v[40:43], v[160:163], v[208:211], v[40:43]
	s_setprio 0
	s_setprio 2
	v_mfma_f32_16x16x32_bf16 v[76:79], v[156:159], v[188:191], v[76:79]
	v_mfma_f32_16x16x32_bf16 v[72:75], v[164:167], v[188:191], v[72:75]
	v_mfma_f32_16x16x32_bf16 v[68:71], v[156:159], v[196:199], v[68:71]
	v_mfma_f32_16x16x32_bf16 v[64:67], v[164:167], v[196:199], v[64:67]
	v_mfma_f32_16x16x32_bf16 v[56:59], v[156:159], v[204:207], v[56:59]
	v_mfma_f32_16x16x32_bf16 v[52:55], v[164:167], v[204:207], v[52:55]
	v_mfma_f32_16x16x32_bf16 v[44:47], v[156:159], v[212:215], v[44:47]
	v_mfma_f32_16x16x32_bf16 v[40:43], v[164:167], v[212:215], v[40:43]
	s_setprio 0
	s_setprio 2
	v_mfma_f32_16x16x32_bf16 v[124:127], v[168:171], v[184:187], v[124:127]
	v_mfma_f32_16x16x32_bf16 v[120:123], v[176:179], v[184:187], v[120:123]
	v_mfma_f32_16x16x32_bf16 v[116:119], v[168:171], v[192:195], v[116:119]
	v_mfma_f32_16x16x32_bf16 v[112:115], v[176:179], v[192:195], v[112:115]
	v_mfma_f32_16x16x32_bf16 v[108:111], v[168:171], v[200:203], v[108:111]
	v_mfma_f32_16x16x32_bf16 v[104:107], v[176:179], v[200:203], v[104:107]
	v_mfma_f32_16x16x32_bf16 v[100:103], v[168:171], v[208:211], v[100:103]
	v_mfma_f32_16x16x32_bf16 v[96:99], v[176:179], v[208:211], v[96:99]
	s_setprio 0
	s_setprio 2
	v_mfma_f32_16x16x32_bf16 v[124:127], v[172:175], v[188:191], v[124:127]
	v_mfma_f32_16x16x32_bf16 v[120:123], v[180:183], v[188:191], v[120:123]
	v_mfma_f32_16x16x32_bf16 v[116:119], v[172:175], v[196:199], v[116:119]
	v_mfma_f32_16x16x32_bf16 v[112:115], v[180:183], v[196:199], v[112:115]
	v_mfma_f32_16x16x32_bf16 v[108:111], v[172:175], v[204:207], v[108:111]
	v_mfma_f32_16x16x32_bf16 v[104:107], v[180:183], v[204:207], v[104:107]
	v_mfma_f32_16x16x32_bf16 v[100:103], v[172:175], v[212:215], v[100:103]
	s_setprio 3
	s_barrier
; #define PG8_STAGE(bufoff, gbase, voff) do { _Pragma("unroll") for (int _i = 0; _i < 2; ++_i) \
;         __builtin_amdgcn_global_load_lds((const unsigned*)((const char*)(gbase) + (voff)[_i]), (PG8_LAS unsigned*)(lds + (bufoff) + ldsw + _i * 8192), 16, 0, 0); } while (0)
; #define PG8_LDA(dst, b, h) do { _Pragma("unroll") for (int m = 0; m < 4; ++m) _Pragma("unroll") for (int k = 0; k < 2; ++k) dst[m][k] = *(const PG8_LAS bf16x8*)(lds + PG8_SA(b, h) + aoff + m * 2048 + k * 1024); } while (0)
; #define PG8_MMA(ai, bj, At, Bt) do { __builtin_amdgcn_s_setprio(1); _Pragma("unroll") for (int m = 0; m < 4; ++m) _Pragma("unroll") for (int n = 0; n < 2; ++n) _Pragma("unroll") for (int k = 0; k < 2; ++k) \
;         acc[ai][bj][m][n] = __builtin_amdgcn_mfma_f32_16x16x32_bf16(Bt[n][k], At[m][k], acc[ai][bj][m][n], 0, 0, 0); __builtin_amdgcn_s_setprio(0); } while (0)
; #define PG8_WAIT_V(n) asm volatile("s_waitcnt vmcnt(" #n ")" ::: "memory")
; #define PG8_WAIT_L(n) asm volatile("s_waitcnt lgkmcnt(" #n ")" ::: "memory")
; #define PG8_BAR __builtin_amdgcn_s_barrier()
; #define PG8_SCHED __builtin_amdgcn_sched_barrier(0)
; template <class Epi, class Sched, bool ALIGN_EPI = false, bool SP2 = false>
; __device__ __forceinline__ void gemm_phase(PG8_LAS unsigned char* lds, const Gemm g, const Sched& S, const Epi& E, const int wv  ) {
;     ...
;             PG8_LDA(At, 1, 1); PG8_STAGE(PG8_SB(1, 0), b3, voffB); PG8_STAGE(PG8_SB(1, 1), b3 + hstepB, voffB); PG8_STAGE(PG8_SA(1, 0), a3, voffA);
;             PG8_WAIT_V(8); PG8_WAIT_L(0); PG8_BAR; PG8_MMA(1, 0, At, B0); PG8_MMA(1, 1, At, B1); PG8_BAR; PG8_SCHED;
;     ...
;         if constexpr (ALIGN_EPI) { if (wr == 0) PG8_BAR; }
;         if constexpr (!Epi::AFTER_DRAIN) { E(acc, cur, wr, wc, fr, fq); S.done(cur); }
;         if (!has_next) break;
	v_mfma_f32_16x16x32_bf16 v[96:99], v[180:183], v[212:215], v[96:99]
	s_setprio 0
	s_add_i32 s52, s86, s63
	v_lshl_add_u64 v[216:217], v[216:217], 0, s[12:13]
	s_mov_b32 m0, s52
	ds_read_b128 v[184:187], v154 offset:49152
	ds_read_b128 v[188:191], v154 offset:50176
	ds_read_b128 v[192:195], v154 offset:51200
	ds_read_b128 v[196:199], v154 offset:52224
	ds_read_b128 v[200:203], v154 offset:53248
	ds_read_b128 v[204:207], v154 offset:54272
	ds_read_b128 v[208:211], v154 offset:55296
	ds_read_b128 v[212:215], v154 offset:56320
	global_load_lds_dwordx4 v[216:217], off
	s_add_i32 m0, s52, 0x2000
	s_add_u32 s52, s56, 0x2b0080
	v_lshl_add_u64 v[216:217], v[218:219], 0, s[12:13]
	s_addc_u32 s53, s57, 0
	s_add_i32 s56, s87, s63
	global_load_lds_dwordx4 v[216:217], off
	v_lshl_add_u64 v[216:217], s[52:53], 0, v[130:131]
	s_mov_b32 m0, s56
	s_nop 0
	global_load_lds_dwordx4 v[216:217], off
	v_lshl_add_u64 v[216:217], s[52:53], 0, v[134:135]
	s_add_i32 m0, s56, 0x2000
	s_nop 0
	global_load_lds_dwordx4 v[216:217], off
	v_lshl_add_u64 v[216:217], v[220:221], 0, s[12:13]
	s_mov_b32 m0, s70
	s_nop 0
	global_load_lds_dwordx4 v[216:217], off
	v_lshl_add_u64 v[216:217], v[222:223], 0, s[12:13]
	s_mov_b32 m0, s71
	s_nop 0
	global_load_lds_dwordx4 v[216:217], off
	s_waitcnt vmcnt(8)
	s_waitcnt lgkmcnt(0)
	s_barrier
	s_setprio 2
	s_waitcnt lgkmcnt(0)
	v_mfma_f32_16x16x32_bf16 v[28:31], v[146:149], v[184:187], v[28:31]
	v_mfma_f32_16x16x32_bf16 v[24:27], v[160:163], v[184:187], v[24:27]
	v_mfma_f32_16x16x32_bf16 v[20:23], v[146:149], v[192:195], v[20:23]
	v_mfma_f32_16x16x32_bf16 v[16:19], v[160:163], v[192:195], v[16:19]
	v_mfma_f32_16x16x32_bf16 v[12:15], v[146:149], v[200:203], v[12:15]
	v_mfma_f32_16x16x32_bf16 v[8:11], v[160:163], v[200:203], v[8:11]
	v_mfma_f32_16x16x32_bf16 v[4:7], v[146:149], v[208:211], v[4:7]
	v_mfma_f32_16x16x32_bf16 v[0:3], v[160:163], v[208:211], v[0:3]
	s_setprio 0
	s_setprio 2
	v_mfma_f32_16x16x32_bf16 v[28:31], v[156:159], v[188:191], v[28:31]
	v_mfma_f32_16x16x32_bf16 v[24:27], v[164:167], v[188:191], v[24:27]
	v_mfma_f32_16x16x32_bf16 v[20:23], v[156:159], v[196:199], v[20:23]
	v_mfma_f32_16x16x32_bf16 v[16:19], v[164:167], v[196:199], v[16:19]
	v_mfma_f32_16x16x32_bf16 v[12:15], v[156:159], v[204:207], v[12:15]
	v_mfma_f32_16x16x32_bf16 v[8:11], v[164:167], v[204:207], v[8:11]
	v_mfma_f32_16x16x32_bf16 v[4:7], v[156:159], v[212:215], v[4:7]
	v_mfma_f32_16x16x32_bf16 v[0:3], v[164:167], v[212:215], v[0:3]
	s_setprio 0
	s_setprio 2
	v_mfma_f32_16x16x32_bf16 v[92:95], v[168:171], v[184:187], v[92:95]
	v_mfma_f32_16x16x32_bf16 v[88:91], v[176:179], v[184:187], v[88:91]
	v_mfma_f32_16x16x32_bf16 v[84:87], v[168:171], v[192:195], v[84:87]
	v_mfma_f32_16x16x32_bf16 v[80:83], v[176:179], v[192:195], v[80:83]
	v_mfma_f32_16x16x32_bf16 v[60:63], v[168:171], v[200:203], v[60:63]
	v_mfma_f32_16x16x32_bf16 v[48:51], v[176:179], v[200:203], v[48:51]
	v_mfma_f32_16x16x32_bf16 v[36:39], v[168:171], v[208:211], v[36:39]
	v_mfma_f32_16x16x32_bf16 v[32:35], v[176:179], v[208:211], v[32:35]
	s_setprio 0
	s_setprio 2
	v_mfma_f32_16x16x32_bf16 v[92:95], v[172:175], v[188:191], v[92:95]
	v_mfma_f32_16x16x32_bf16 v[88:91], v[180:183], v[188:191], v[88:91]
	v_mfma_f32_16x16x32_bf16 v[84:87], v[172:175], v[196:199], v[84:87]
	v_mfma_f32_16x16x32_bf16 v[80:83], v[180:183], v[196:199], v[80:83]
	v_mfma_f32_16x16x32_bf16 v[60:63], v[172:175], v[204:207], v[60:63]
	v_mfma_f32_16x16x32_bf16 v[48:51], v[180:183], v[204:207], v[48:51]
	v_mfma_f32_16x16x32_bf16 v[36:39], v[172:175], v[212:215], v[36:39]
	s_setprio 3
	s_barrier
	v_mfma_f32_16x16x32_bf16 v[32:35], v[180:183], v[212:215], v[32:35]
	s_setprio 0
	s_add_i32 s85, s85, 2
	s_add_u32 s83, s83, 0x100
	s_addc_u32 s84, s84, 0
	s_cmpk_gt_u32 s85, 0xa9
	s_mov_b64 s[52:53], s[54:55]
	s_cbranch_scc0 .LBB0_1544
	s_and_b64 vcc, exec, s[14:15]
	s_cbranch_vccz .LBB0_1547
	s_barrier

; #define PG8_STAGE(bufoff, gbase, voff) do { _Pragma("unroll") for (int _i = 0; _i < 2; ++_i) \
;         __builtin_amdgcn_global_load_lds((const unsigned*)((const char*)(gbase) + (voff)[_i]), (PG8_LAS unsigned*)(lds + (bufoff) + ldsw + _i * 8192), 16, 0, 0); } while (0)
; #define PG8_LDA(dst, b, h) do { _Pragma("unroll") for (int m = 0; m < 4; ++m) _Pragma("unroll") for (int k = 0; k < 2; ++k) dst[m][k] = *(const PG8_LAS bf16x8*)(lds + PG8_SA(b, h) + aoff + m * 2048 + k * 1024); } while (0)
; #define PG8_LDB(dst, b, h) do { _Pragma("unroll") for (int n = 0; n < 2; ++n) _Pragma("unroll") for (int k = 0; k < 2; ++k) dst[n][k] = *(const PG8_LAS bf16x8*)(lds + PG8_SB(b, h) + boff + n * 2048 + k * 1024); } while (0)
; #define PG8_MMA(ai, bj, At, Bt) do { __builtin_amdgcn_s_setprio(1); _Pragma("unroll") for (int m = 0; m < 4; ++m) _Pragma("unroll") for (int n = 0; n < 2; ++n) _Pragma("unroll") for (int k = 0; k < 2; ++k) \
;         acc[ai][bj][m][n] = __builtin_amdgcn_mfma_f32_16x16x32_bf16(Bt[n][k], At[m][k], acc[ai][bj][m][n], 0, 0, 0); __builtin_amdgcn_s_setprio(0); } while (0)
; #define PG8_WAIT_V(n) asm volatile("s_waitcnt vmcnt(" #n ")" ::: "memory")
; #define PG8_WAIT_L(n) asm volatile("s_waitcnt lgkmcnt(" #n ")" ::: "memory")
; #define PG8_BAR __builtin_amdgcn_s_barrier()
; template <class Epi, class Sched, bool ALIGN_EPI = false, bool SP2 = false>
; __device__ __forceinline__ void gemm_phase(PG8_LAS unsigned char* lds, const Gemm g, const Sched& S, const Epi& E, const int wv  ) {
;     ...
;         for (int t = 0; t < nt; t += 2) {
;             const bool last = (t == nt - 2);
;             const char* a1 = cA + (size_t)(t + 1) * kstep;
;             const char* a2 = last ? nA : cA + (size_t)(t + 2) * kstep; const char* b2 = last ? nB : cB + (size_t)(t + 2) * kstep;
;             const char* a3 = a2 + kstep; const char* b3 = b2 + kstep;
;             if (last && has_next) S.a_ready(nxt);
;             if constexpr (SP2) {
;             PG8_LDB(B0, 0, 0); PG8_LDB(B1, 0, 1); PG8_SCHED; PG8_LDA(At, 0, 0); PG8_STAGE(PG8_SA(1, 1), a1 + hstepA, voffA);
;             PG8_WAIT_V(8); PG8_WAIT_L(0); PG8_BAR; PG8_MMA(0, 0, At, B0); PG8_MMA(0, 1, At, B1); PG8_BAR; PG8_SCHED;
;             PG8_LDA(At, 0, 1); PG8_STAGE(PG8_SB(0, 0), b2, voffB); PG8_STAGE(PG8_SB(0, 1), b2 + hstepB, voffB); PG8_STAGE(PG8_SA(0, 0), a2, voffA);
.LBB0_1717:
	ds_read_b128 v[146:149], v152
	ds_read_b128 v[156:159], v152 offset:1024
	ds_read_b128 v[160:163], v152 offset:2048
	ds_read_b128 v[164:167], v152 offset:3072
	ds_read_b128 v[168:171], v153
	ds_read_b128 v[172:175], v153 offset:1024
	ds_read_b128 v[176:179], v153 offset:2048
	ds_read_b128 v[180:183], v153 offset:3072
	s_add_u32 s60, s58, 0xfff00080
	s_addc_u32 s61, s59, -1
	s_cmp_eq_u32 s87, 60
	s_cselect_b32 s63, s51, s61
	s_cselect_b32 s62, s83, s60
	s_cselect_b32 s61, s49, s86
	s_cselect_b32 s60, s84, s85
	v_lshl_add_u64 v[216:217], s[58:59], 0, v[138:139]
	s_add_i32 m0, s70, 0xc000
	ds_read_b128 v[184:187], v154
	ds_read_b128 v[188:191], v154 offset:1024
	ds_read_b128 v[192:195], v154 offset:2048
	ds_read_b128 v[196:199], v154 offset:3072
	ds_read_b128 v[200:203], v154 offset:4096
	ds_read_b128 v[204:207], v154 offset:5120
	ds_read_b128 v[208:211], v154 offset:6144
	ds_read_b128 v[212:215], v154 offset:7168
	global_load_lds_dwordx4 v[216:217], off
	v_lshl_add_u64 v[216:217], s[58:59], 0, v[140:141]
	s_add_i32 m0, s70, 0xe000
	s_nop 0
	global_load_lds_dwordx4 v[216:217], off
	s_waitcnt vmcnt(8)
	s_waitcnt lgkmcnt(0)
	s_barrier
	s_setprio 2
	s_waitcnt lgkmcnt(0)
	v_mfma_f32_16x16x32_bf16 v[76:79], v[146:149], v[184:187], v[76:79]
	v_mfma_f32_16x16x32_bf16 v[72:75], v[160:163], v[184:187], v[72:75]
	v_mfma_f32_16x16x32_bf16 v[68:71], v[146:149], v[192:195], v[68:71]
	v_mfma_f32_16x16x32_bf16 v[64:67], v[160:163], v[192:195], v[64:67]
	v_mfma_f32_16x16x32_bf16 v[56:59], v[146:149], v[200:203], v[56:59]
	v_mfma_f32_16x16x32_bf16 v[52:55], v[160:163], v[200:203], v[52:55]
	v_mfma_f32_16x16x32_bf16 v[44:47], v[146:149], v[208:211], v[44:47]
	v_mfma_f32_16x16x32_bf16 v[40:43], v[160:163], v[208:211], v[40:43]
	s_setprio 0
	s_setprio 2
	v_mfma_f32_16x16x32_bf16 v[76:79], v[156:159], v[188:191], v[76:79]
	v_mfma_f32_16x16x32_bf16 v[72:75], v[164:167], v[188:191], v[72:75]
	v_mfma_f32_16x16x32_bf16 v[68:71], v[156:159], v[196:199], v[68:71]
	v_mfma_f32_16x16x32_bf16 v[64:67], v[164:167], v[196:199], v[64:67]
	v_mfma_f32_16x16x32_bf16 v[56:59], v[156:159], v[204:207], v[56:59]
	v_mfma_f32_16x16x32_bf16 v[52:55], v[164:167], v[204:207], v[52:55]
	v_mfma_f32_16x16x32_bf16 v[44:47], v[156:159], v[212:215], v[44:47]
	v_mfma_f32_16x16x32_bf16 v[40:43], v[164:167], v[212:215], v[40:43]
	s_setprio 0
	s_setprio 2
	v_mfma_f32_16x16x32_bf16 v[124:127], v[168:171], v[184:187], v[124:127]
	v_mfma_f32_16x16x32_bf16 v[120:123], v[176:179], v[184:187], v[120:123]
	v_mfma_f32_16x16x32_bf16 v[116:119], v[168:171], v[192:195], v[116:119]
	v_mfma_f32_16x16x32_bf16 v[112:115], v[176:179], v[192:195], v[112:115]
	v_mfma_f32_16x16x32_bf16 v[108:111], v[168:171], v[200:203], v[108:111]
	v_mfma_f32_16x16x32_bf16 v[104:107], v[176:179], v[200:203], v[104:107]
	v_mfma_f32_16x16x32_bf16 v[100:103], v[168:171], v[208:211], v[100:103]
	v_mfma_f32_16x16x32_bf16 v[96:99], v[176:179], v[208:211], v[96:99]
	s_setprio 0
	s_setprio 2
	v_mfma_f32_16x16x32_bf16 v[124:127], v[172:175], v[188:191], v[124:127]
	v_mfma_f32_16x16x32_bf16 v[120:123], v[180:183], v[188:191], v[120:123]
	v_mfma_f32_16x16x32_bf16 v[116:119], v[172:175], v[196:199], v[116:119]
	v_mfma_f32_16x16x32_bf16 v[112:115], v[180:183], v[196:199], v[112:115]
	v_mfma_f32_16x16x32_bf16 v[108:111], v[172:175], v[204:207], v[108:111]
	v_mfma_f32_16x16x32_bf16 v[104:107], v[180:183], v[204:207], v[104:107]
	v_mfma_f32_16x16x32_bf16 v[100:103], v[172:175], v[212:215], v[100:103]
	s_setprio 3
	s_barrier
	v_mfma_f32_16x16x32_bf16 v[96:99], v[180:183], v[212:215], v[96:99]
	s_setprio 0
	s_add_i32 s90, s77, s69
	v_lshl_add_u64 v[216:217], s[60:61], 0, v[130:131]
	s_mov_b32 m0, s90
	ds_read_b128 v[184:187], v154 offset:16384
	ds_read_b128 v[188:191], v154 offset:17408
	ds_read_b128 v[192:195], v154 offset:18432
	ds_read_b128 v[196:199], v154 offset:19456
	ds_read_b128 v[200:203], v154 offset:20480
	ds_read_b128 v[204:207], v154 offset:21504
	ds_read_b128 v[208:211], v154 offset:22528
	ds_read_b128 v[212:215], v154 offset:23552
	global_load_lds_dwordx4 v[216:217], off
	s_add_i32 m0, s90, 0x2000
	s_add_u32 s90, s60, 0x100000
	v_lshl_add_u64 v[218:219], s[60:61], 0, v[134:135]
	s_addc_u32 s91, s61, 0
	s_add_i32 s92, s78, s69
	global_load_lds_dwordx4 v[218:219], off
	v_lshl_add_u64 v[220:221], s[90:91], 0, v[130:131]
	s_mov_b32 m0, s92
	v_lshl_add_u64 v[222:223], s[62:63], 0, v[132:133]
	global_load_lds_dwordx4 v[220:221], off
	v_lshl_add_u64 v[220:221], s[90:91], 0, v[134:135]
	s_add_i32 m0, s92, 0x2000
	s_nop 0
	global_load_lds_dwordx4 v[220:221], off
	v_lshl_add_u64 v[220:221], s[62:63], 0, v[128:129]
	s_mov_b32 m0, s70
	s_nop 0
	global_load_lds_dwordx4 v[220:221], off
	s_mov_b32 m0, s71
	s_nop 0
	global_load_lds_dwordx4 v[222:223], off
	s_waitcnt vmcnt(8)
	s_waitcnt lgkmcnt(0)
	s_barrier
; #define PG8_STAGE(bufoff, gbase, voff) do { _Pragma("unroll") for (int _i = 0; _i < 2; ++_i) \
;         __builtin_amdgcn_global_load_lds((const unsigned*)((const char*)(gbase) + (voff)[_i]), (PG8_LAS unsigned*)(lds + (bufoff) + ldsw + _i * 8192), 16, 0, 0); } while (0)
; #define PG8_LDA(dst, b, h) do { _Pragma("unroll") for (int m = 0; m < 4; ++m) _Pragma("unroll") for (int k = 0; k < 2; ++k) dst[m][k] = *(const PG8_LAS bf16x8*)(lds + PG8_SA(b, h) + aoff + m * 2048 + k * 1024); } while (0)
; #define PG8_LDB(dst, b, h) do { _Pragma("unroll") for (int n = 0; n < 2; ++n) _Pragma("unroll") for (int k = 0; k < 2; ++k) dst[n][k] = *(const PG8_LAS bf16x8*)(lds + PG8_SB(b, h) + boff + n * 2048 + k * 1024); } while (0)
; #define PG8_MMA(ai, bj, At, Bt) do { __builtin_amdgcn_s_setprio(1); _Pragma("unroll") for (int m = 0; m < 4; ++m) _Pragma("unroll") for (int n = 0; n < 2; ++n) _Pragma("unroll") for (int k = 0; k < 2; ++k) \
;         acc[ai][bj][m][n] = __builtin_amdgcn_mfma_f32_16x16x32_bf16(Bt[n][k], At[m][k], acc[ai][bj][m][n], 0, 0, 0); __builtin_amdgcn_s_setprio(0); } while (0)
; #define PG8_WAIT_V(n) asm volatile("s_waitcnt vmcnt(" #n ")" ::: "memory")
; #define PG8_WAIT_L(n) asm volatile("s_waitcnt lgkmcnt(" #n ")" ::: "memory")
; #define PG8_BAR __builtin_amdgcn_s_barrier()
; #define PG8_SCHED __builtin_amdgcn_sched_barrier(0)
; template <class Epi, class Sched, bool ALIGN_EPI = false, bool SP2 = false>
; __device__ __forceinline__ void gemm_phase(PG8_LAS unsigned char* lds, const Gemm g, const Sched& S, const Epi& E, const int wv  ) {
;     ...
;             PG8_WAIT_V(8); PG8_WAIT_L(0); PG8_BAR; PG8_MMA(1, 0, At, B0); PG8_MMA(1, 1, At, B1); PG8_BAR; PG8_SCHED;
;             PG8_LDB(B0, 1, 0); PG8_LDB(B1, 1, 1); PG8_SCHED; PG8_LDA(At, 1, 0); PG8_STAGE(PG8_SA(0, 1), a2 + hstepA, voffA);
;             PG8_WAIT_V(8); PG8_WAIT_L(0); PG8_BAR; PG8_MMA(0, 0, At, B0); PG8_MMA(0, 1, At, B1); PG8_BAR; PG8_SCHED;
	s_setprio 2
	s_waitcnt lgkmcnt(0)
	v_mfma_f32_16x16x32_bf16 v[28:31], v[146:149], v[184:187], v[28:31]
	v_mfma_f32_16x16x32_bf16 v[24:27], v[160:163], v[184:187], v[24:27]
	v_mfma_f32_16x16x32_bf16 v[20:23], v[146:149], v[192:195], v[20:23]
	v_mfma_f32_16x16x32_bf16 v[16:19], v[160:163], v[192:195], v[16:19]
	v_mfma_f32_16x16x32_bf16 v[12:15], v[146:149], v[200:203], v[12:15]
	v_mfma_f32_16x16x32_bf16 v[8:11], v[160:163], v[200:203], v[8:11]
	v_mfma_f32_16x16x32_bf16 v[4:7], v[146:149], v[208:211], v[4:7]
	v_mfma_f32_16x16x32_bf16 v[0:3], v[160:163], v[208:211], v[0:3]
	s_setprio 0
	s_setprio 2
	v_mfma_f32_16x16x32_bf16 v[28:31], v[156:159], v[188:191], v[28:31]
	v_mfma_f32_16x16x32_bf16 v[24:27], v[164:167], v[188:191], v[24:27]
	v_mfma_f32_16x16x32_bf16 v[20:23], v[156:159], v[196:199], v[20:23]
	v_mfma_f32_16x16x32_bf16 v[16:19], v[164:167], v[196:199], v[16:19]
	v_mfma_f32_16x16x32_bf16 v[12:15], v[156:159], v[204:207], v[12:15]
	v_mfma_f32_16x16x32_bf16 v[8:11], v[164:167], v[204:207], v[8:11]
	v_mfma_f32_16x16x32_bf16 v[4:7], v[156:159], v[212:215], v[4:7]
	v_mfma_f32_16x16x32_bf16 v[0:3], v[164:167], v[212:215], v[0:3]
	s_setprio 0
	s_setprio 2
	v_mfma_f32_16x16x32_bf16 v[92:95], v[168:171], v[184:187], v[92:95]
	v_mfma_f32_16x16x32_bf16 v[88:91], v[176:179], v[184:187], v[88:91]
	v_mfma_f32_16x16x32_bf16 v[84:87], v[168:171], v[192:195], v[84:87]
	v_mfma_f32_16x16x32_bf16 v[80:83], v[176:179], v[192:195], v[80:83]
	v_mfma_f32_16x16x32_bf16 v[60:63], v[168:171], v[200:203], v[60:63]
	v_mfma_f32_16x16x32_bf16 v[48:51], v[176:179], v[200:203], v[48:51]
	v_mfma_f32_16x16x32_bf16 v[36:39], v[168:171], v[208:211], v[36:39]
	v_mfma_f32_16x16x32_bf16 v[32:35], v[176:179], v[208:211], v[32:35]
	s_setprio 0
	s_setprio 2
	v_mfma_f32_16x16x32_bf16 v[92:95], v[172:175], v[188:191], v[92:95]
	v_mfma_f32_16x16x32_bf16 v[88:91], v[180:183], v[188:191], v[88:91]
	v_mfma_f32_16x16x32_bf16 v[84:87], v[172:175], v[196:199], v[84:87]
	v_mfma_f32_16x16x32_bf16 v[80:83], v[180:183], v[196:199], v[80:83]
	v_mfma_f32_16x16x32_bf16 v[60:63], v[172:175], v[204:207], v[60:63]
	v_mfma_f32_16x16x32_bf16 v[48:51], v[180:183], v[204:207], v[48:51]
	v_mfma_f32_16x16x32_bf16 v[36:39], v[172:175], v[212:215], v[36:39]
	s_setprio 3
	s_barrier
	v_mfma_f32_16x16x32_bf16 v[32:35], v[180:183], v[212:215], v[32:35]
	s_setprio 0
	s_add_i32 s90, 0, 0x18000
	v_add_u32_e32 v155, s90, v150
	s_add_i32 s91, 0, 0x1c000
	ds_read_b128 v[146:149], v155
	ds_read_b128 v[156:159], v155 offset:1024
	ds_read_b128 v[160:163], v155 offset:2048
	ds_read_b128 v[164:167], v155 offset:3072
	v_add_u32_e32 v155, s91, v150
	ds_read_b128 v[168:171], v155
	ds_read_b128 v[172:175], v155 offset:1024
	ds_read_b128 v[176:179], v155 offset:2048
	ds_read_b128 v[180:183], v155 offset:3072
	s_add_u32 s62, s62, 0x100000
	s_addc_u32 s63, s63, 0
	s_mov_b32 m0, s72
	v_lshl_add_u64 v[224:225], s[62:63], 0, v[128:129]
	ds_read_b128 v[184:187], v154 offset:32768
	ds_read_b128 v[188:191], v154 offset:33792
	ds_read_b128 v[192:195], v154 offset:34816
	ds_read_b128 v[196:199], v154 offset:35840
	ds_read_b128 v[200:203], v154 offset:36864
	ds_read_b128 v[204:207], v154 offset:37888
	ds_read_b128 v[208:211], v154 offset:38912
	ds_read_b128 v[212:215], v154 offset:39936
	global_load_lds_dwordx4 v[224:225], off
	v_lshl_add_u64 v[224:225], s[62:63], 0, v[132:133]
	s_mov_b32 m0, s73
	s_nop 0
	global_load_lds_dwordx4 v[224:225], off
	s_waitcnt vmcnt(8)
	s_waitcnt lgkmcnt(0)
	s_barrier
	s_setprio 2
	s_waitcnt lgkmcnt(0)
	v_mfma_f32_16x16x32_bf16 v[76:79], v[146:149], v[184:187], v[76:79]
	v_mfma_f32_16x16x32_bf16 v[72:75], v[160:163], v[184:187], v[72:75]
	v_mfma_f32_16x16x32_bf16 v[68:71], v[146:149], v[192:195], v[68:71]
	v_mfma_f32_16x16x32_bf16 v[64:67], v[160:163], v[192:195], v[64:67]
	v_mfma_f32_16x16x32_bf16 v[56:59], v[146:149], v[200:203], v[56:59]
	v_mfma_f32_16x16x32_bf16 v[52:55], v[160:163], v[200:203], v[52:55]
	v_mfma_f32_16x16x32_bf16 v[44:47], v[146:149], v[208:211], v[44:47]
	v_mfma_f32_16x16x32_bf16 v[40:43], v[160:163], v[208:211], v[40:43]
	s_setprio 0
	s_setprio 2
	v_mfma_f32_16x16x32_bf16 v[76:79], v[156:159], v[188:191], v[76:79]
	v_mfma_f32_16x16x32_bf16 v[72:75], v[164:167], v[188:191], v[72:75]
	v_mfma_f32_16x16x32_bf16 v[68:71], v[156:159], v[196:199], v[68:71]
	v_mfma_f32_16x16x32_bf16 v[64:67], v[164:167], v[196:199], v[64:67]
	v_mfma_f32_16x16x32_bf16 v[56:59], v[156:159], v[204:207], v[56:59]
	v_mfma_f32_16x16x32_bf16 v[52:55], v[164:167], v[204:207], v[52:55]
	v_mfma_f32_16x16x32_bf16 v[44:47], v[156:159], v[212:215], v[44:47]
	v_mfma_f32_16x16x32_bf16 v[40:43], v[164:167], v[212:215], v[40:43]
	s_setprio 0
	s_setprio 2
	v_mfma_f32_16x16x32_bf16 v[124:127], v[168:171], v[184:187], v[124:127]
	v_mfma_f32_16x16x32_bf16 v[120:123], v[176:179], v[184:187], v[120:123]
	v_mfma_f32_16x16x32_bf16 v[116:119], v[168:171], v[192:195], v[116:119]
	v_mfma_f32_16x16x32_bf16 v[112:115], v[176:179], v[192:195], v[112:115]
	v_mfma_f32_16x16x32_bf16 v[108:111], v[168:171], v[200:203], v[108:111]
	v_mfma_f32_16x16x32_bf16 v[104:107], v[176:179], v[200:203], v[104:107]
	v_mfma_f32_16x16x32_bf16 v[100:103], v[168:171], v[208:211], v[100:103]
	v_mfma_f32_16x16x32_bf16 v[96:99], v[176:179], v[208:211], v[96:99]
	s_setprio 0
	s_setprio 2
	v_mfma_f32_16x16x32_bf16 v[124:127], v[172:175], v[188:191], v[124:127]
	v_mfma_f32_16x16x32_bf16 v[120:123], v[180:183], v[188:191], v[120:123]
	v_mfma_f32_16x16x32_bf16 v[116:119], v[172:175], v[196:199], v[116:119]
	v_mfma_f32_16x16x32_bf16 v[112:115], v[180:183], v[196:199], v[112:115]
	v_mfma_f32_16x16x32_bf16 v[108:111], v[172:175], v[204:207], v[108:111]
	v_mfma_f32_16x16x32_bf16 v[104:107], v[180:183], v[204:207], v[104:107]
	v_mfma_f32_16x16x32_bf16 v[100:103], v[172:175], v[212:215], v[100:103]
	s_setprio 3
	s_barrier
; #define PG8_STAGE(bufoff, gbase, voff) do { _Pragma("unroll") for (int _i = 0; _i < 2; ++_i) \
;         __builtin_amdgcn_global_load_lds((const unsigned*)((const char*)(gbase) + (voff)[_i]), (PG8_LAS unsigned*)(lds + (bufoff) + ldsw + _i * 8192), 16, 0, 0); } while (0)
; #define PG8_LDA(dst, b, h) do { _Pragma("unroll") for (int m = 0; m < 4; ++m) _Pragma("unroll") for (int k = 0; k < 2; ++k) dst[m][k] = *(const PG8_LAS bf16x8*)(lds + PG8_SA(b, h) + aoff + m * 2048 + k * 1024); } while (0)
; #define PG8_MMA(ai, bj, At, Bt) do { __builtin_amdgcn_s_setprio(1); _Pragma("unroll") for (int m = 0; m < 4; ++m) _Pragma("unroll") for (int n = 0; n < 2; ++n) _Pragma("unroll") for (int k = 0; k < 2; ++k) \
;         acc[ai][bj][m][n] = __builtin_amdgcn_mfma_f32_16x16x32_bf16(Bt[n][k], At[m][k], acc[ai][bj][m][n], 0, 0, 0); __builtin_amdgcn_s_setprio(0); } while (0)
; #define PG8_WAIT_V(n) asm volatile("s_waitcnt vmcnt(" #n ")" ::: "memory")
; #define PG8_WAIT_L(n) asm volatile("s_waitcnt lgkmcnt(" #n ")" ::: "memory")
; #define PG8_BAR __builtin_amdgcn_s_barrier()
; #define PG8_SCHED __builtin_amdgcn_sched_barrier(0)
; template <class Epi, class Sched, bool ALIGN_EPI = false, bool SP2 = false>
; __device__ __forceinline__ void gemm_phase(PG8_LAS unsigned char* lds, const Gemm g, const Sched& S, const Epi& E, const int wv  ) {
;     ...
;             PG8_LDA(At, 1, 1); PG8_STAGE(PG8_SB(1, 0), b3, voffB); PG8_STAGE(PG8_SB(1, 1), b3 + hstepB, voffB); PG8_STAGE(PG8_SA(1, 0), a3, voffA);
;             PG8_WAIT_V(8); PG8_WAIT_L(0); PG8_BAR; PG8_MMA(1, 0, At, B0); PG8_MMA(1, 1, At, B1); PG8_BAR; PG8_SCHED;
;     ...
;         if constexpr (ALIGN_EPI) { if (wr == 0) PG8_BAR; }
;         if constexpr (!Epi::AFTER_DRAIN) { E(acc, cur, wr, wc, fr, fq); S.done(cur); }
;         if (!has_next) break;
	v_mfma_f32_16x16x32_bf16 v[96:99], v[180:183], v[212:215], v[96:99]
	s_setprio 0
	s_add_i32 s62, s90, s69
	v_lshl_add_u64 v[216:217], v[216:217], 0, s[10:11]
	s_mov_b32 m0, s62
	ds_read_b128 v[184:187], v154 offset:49152
	ds_read_b128 v[188:191], v154 offset:50176
	ds_read_b128 v[192:195], v154 offset:51200
	ds_read_b128 v[196:199], v154 offset:52224
	ds_read_b128 v[200:203], v154 offset:53248
	ds_read_b128 v[204:207], v154 offset:54272
	ds_read_b128 v[208:211], v154 offset:55296
	ds_read_b128 v[212:215], v154 offset:56320
	global_load_lds_dwordx4 v[216:217], off
	s_add_i32 m0, s62, 0x2000
	s_add_u32 s60, s60, 0x100080
	v_lshl_add_u64 v[216:217], v[218:219], 0, s[10:11]
	s_addc_u32 s61, s61, 0
	s_add_i32 s62, s91, s69
	global_load_lds_dwordx4 v[216:217], off
	v_lshl_add_u64 v[216:217], s[60:61], 0, v[130:131]
	s_mov_b32 m0, s62
	s_nop 0
	global_load_lds_dwordx4 v[216:217], off
	v_lshl_add_u64 v[216:217], s[60:61], 0, v[134:135]
	s_add_i32 m0, s62, 0x2000
	s_nop 0
	global_load_lds_dwordx4 v[216:217], off
	v_lshl_add_u64 v[216:217], v[220:221], 0, s[10:11]
	s_mov_b32 m0, s64
	s_nop 0
	global_load_lds_dwordx4 v[216:217], off
	v_lshl_add_u64 v[216:217], v[222:223], 0, s[10:11]
	s_mov_b32 m0, s65
	s_nop 0
	global_load_lds_dwordx4 v[216:217], off
	s_waitcnt vmcnt(8)
	s_waitcnt lgkmcnt(0)
	s_barrier
	s_setprio 2
	s_waitcnt lgkmcnt(0)
	v_mfma_f32_16x16x32_bf16 v[28:31], v[146:149], v[184:187], v[28:31]
	v_mfma_f32_16x16x32_bf16 v[24:27], v[160:163], v[184:187], v[24:27]
	v_mfma_f32_16x16x32_bf16 v[20:23], v[146:149], v[192:195], v[20:23]
	v_mfma_f32_16x16x32_bf16 v[16:19], v[160:163], v[192:195], v[16:19]
	v_mfma_f32_16x16x32_bf16 v[12:15], v[146:149], v[200:203], v[12:15]
	v_mfma_f32_16x16x32_bf16 v[8:11], v[160:163], v[200:203], v[8:11]
	v_mfma_f32_16x16x32_bf16 v[4:7], v[146:149], v[208:211], v[4:7]
	v_mfma_f32_16x16x32_bf16 v[0:3], v[160:163], v[208:211], v[0:3]
	s_setprio 0
	s_setprio 2
	v_mfma_f32_16x16x32_bf16 v[28:31], v[156:159], v[188:191], v[28:31]
	v_mfma_f32_16x16x32_bf16 v[24:27], v[164:167], v[188:191], v[24:27]
	v_mfma_f32_16x16x32_bf16 v[20:23], v[156:159], v[196:199], v[20:23]
	v_mfma_f32_16x16x32_bf16 v[16:19], v[164:167], v[196:199], v[16:19]
	v_mfma_f32_16x16x32_bf16 v[12:15], v[156:159], v[204:207], v[12:15]
	v_mfma_f32_16x16x32_bf16 v[8:11], v[164:167], v[204:207], v[8:11]
	v_mfma_f32_16x16x32_bf16 v[4:7], v[156:159], v[212:215], v[4:7]
	v_mfma_f32_16x16x32_bf16 v[0:3], v[164:167], v[212:215], v[0:3]
	s_setprio 0
	s_setprio 2
	v_mfma_f32_16x16x32_bf16 v[92:95], v[168:171], v[184:187], v[92:95]
	v_mfma_f32_16x16x32_bf16 v[88:91], v[176:179], v[184:187], v[88:91]
	v_mfma_f32_16x16x32_bf16 v[84:87], v[168:171], v[192:195], v[84:87]
	v_mfma_f32_16x16x32_bf16 v[80:83], v[176:179], v[192:195], v[80:83]
	v_mfma_f32_16x16x32_bf16 v[60:63], v[168:171], v[200:203], v[60:63]
	v_mfma_f32_16x16x32_bf16 v[48:51], v[176:179], v[200:203], v[48:51]
	v_mfma_f32_16x16x32_bf16 v[36:39], v[168:171], v[208:211], v[36:39]
	v_mfma_f32_16x16x32_bf16 v[32:35], v[176:179], v[208:211], v[32:35]
	s_setprio 0
	s_setprio 2
	v_mfma_f32_16x16x32_bf16 v[92:95], v[172:175], v[188:191], v[92:95]
	v_mfma_f32_16x16x32_bf16 v[88:91], v[180:183], v[188:191], v[88:91]
	v_mfma_f32_16x16x32_bf16 v[84:87], v[172:175], v[196:199], v[84:87]
	v_mfma_f32_16x16x32_bf16 v[80:83], v[180:183], v[196:199], v[80:83]
	v_mfma_f32_16x16x32_bf16 v[60:63], v[172:175], v[204:207], v[60:63]
	v_mfma_f32_16x16x32_bf16 v[48:51], v[180:183], v[204:207], v[48:51]
	v_mfma_f32_16x16x32_bf16 v[36:39], v[172:175], v[212:215], v[36:39]
	s_setprio 3
	s_barrier
	v_mfma_f32_16x16x32_bf16 v[32:35], v[180:183], v[212:215], v[32:35]
	s_setprio 0
	s_add_i32 s87, s87, 2
	s_add_u32 s58, s58, 0x100
	s_addc_u32 s59, s59, 0
	s_add_u32 s85, s85, 0x100
	s_addc_u32 s86, s86, 0
	s_cmp_gt_u32 s87, 61
	s_cbranch_scc0 .LBB0_1717
	s_and_b64 vcc, exec, s[12:13]
	s_cbranch_vccz .LBB0_1720
	s_barrier

; #define PG8_STAGE(bufoff, gbase, voff) do { _Pragma("unroll") for (int _i = 0; _i < 2; ++_i) \
;         __builtin_amdgcn_global_load_lds((const unsigned*)((const char*)(gbase) + (voff)[_i]), (PG8_LAS unsigned*)(lds + (bufoff) + ldsw + _i * 8192), 16, 0, 0); } while (0)
; #define PG8_LDA(dst, b, h) do { _Pragma("unroll") for (int m = 0; m < 4; ++m) _Pragma("unroll") for (int k = 0; k < 2; ++k) dst[m][k] = *(const PG8_LAS bf16x8*)(lds + PG8_SA(b, h) + aoff + m * 2048 + k * 1024); } while (0)
; #define PG8_LDB(dst, b, h) do { _Pragma("unroll") for (int n = 0; n < 2; ++n) _Pragma("unroll") for (int k = 0; k < 2; ++k) dst[n][k] = *(const PG8_LAS bf16x8*)(lds + PG8_SB(b, h) + boff + n * 2048 + k * 1024); } while (0)
; #define PG8_MMA(ai, bj, At, Bt) do { __builtin_amdgcn_s_setprio(1); _Pragma("unroll") for (int m = 0; m < 4; ++m) _Pragma("unroll") for (int n = 0; n < 2; ++n) _Pragma("unroll") for (int k = 0; k < 2; ++k) \
;         acc[ai][bj][m][n] = __builtin_amdgcn_mfma_f32_16x16x32_bf16(Bt[n][k], At[m][k], acc[ai][bj][m][n], 0, 0, 0); __builtin_amdgcn_s_setprio(0); } while (0)
; #define PG8_WAIT_V(n) asm volatile("s_waitcnt vmcnt(" #n ")" ::: "memory")
; #define PG8_WAIT_L(n) asm volatile("s_waitcnt lgkmcnt(" #n ")" ::: "memory")
; #define PG8_BAR __builtin_amdgcn_s_barrier()
; template <class Epi, class Sched, bool ALIGN_EPI = false, bool SP2 = false>
; __device__ __forceinline__ void gemm_phase(PG8_LAS unsigned char* lds, const Gemm g, const Sched& S, const Epi& E, const int wv  ) {
;     ...
;         for (int t = 0; t < nt; t += 2) {
;             const bool last = (t == nt - 2);
;             const char* a1 = cA + (size_t)(t + 1) * kstep;
;             const char* a2 = last ? nA : cA + (size_t)(t + 2) * kstep; const char* b2 = last ? nB : cB + (size_t)(t + 2) * kstep;
;             const char* a3 = a2 + kstep; const char* b3 = b2 + kstep;
;             if (last && has_next) S.a_ready(nxt);
;             if constexpr (SP2) {
;             PG8_LDB(B0, 0, 0); PG8_LDB(B1, 0, 1); PG8_SCHED; PG8_LDA(At, 0, 0); PG8_STAGE(PG8_SA(1, 1), a1 + hstepA, voffA);
;             PG8_WAIT_V(8); PG8_WAIT_L(0); PG8_BAR; PG8_MMA(0, 0, At, B0); PG8_MMA(0, 1, At, B1); PG8_BAR; PG8_SCHED;
;             PG8_LDA(At, 0, 1); PG8_STAGE(PG8_SB(0, 0), b2, voffB); PG8_STAGE(PG8_SB(0, 1), b2 + hstepB, voffB); PG8_STAGE(PG8_SA(0, 0), a2, voffA);
.LBB0_2399:
	ds_read_b128 v[44:47], v196
	ds_read_b128 v[48:51], v196 offset:1024
	ds_read_b128 v[52:55], v196 offset:2048
	ds_read_b128 v[56:59], v196 offset:3072
	ds_read_b128 v[60:63], v197
	ds_read_b128 v[68:71], v197 offset:1024
	ds_read_b128 v[72:75], v197 offset:2048
	ds_read_b128 v[76:79], v197 offset:3072
	s_add_u32 s68, s66, 0xfff00080
	s_addc_u32 s69, s67, -1
	s_cmp_eq_u32 s94, 60
	s_cselect_b32 s71, s57, s69
	s_cselect_b32 s70, s63, s68
	s_cselect_b32 s69, s55, s93
	s_cselect_b32 s68, s65, s92
	v_lshl_add_u64 v[224:225], s[66:67], 0, v[172:173]
	s_add_i32 m0, s75, 0xc000
	ds_read_b128 v[180:183], v198
	ds_read_b128 v[184:187], v198 offset:1024
	ds_read_b128 v[200:203], v198 offset:2048
	ds_read_b128 v[204:207], v198 offset:3072
	ds_read_b128 v[208:211], v198 offset:4096
	ds_read_b128 v[212:215], v198 offset:5120
	ds_read_b128 v[216:219], v198 offset:6144
	ds_read_b128 v[220:223], v198 offset:7168
	global_load_lds_dwordx4 v[224:225], off
	v_lshl_add_u64 v[224:225], s[66:67], 0, v[174:175]
	s_add_i32 m0, s75, 0xe000
	s_nop 0
	global_load_lds_dwordx4 v[224:225], off
	s_waitcnt vmcnt(8)
	s_waitcnt lgkmcnt(0)
	s_barrier
	s_setprio 2
	s_waitcnt lgkmcnt(0)
	v_mfma_f32_16x16x32_bf16 v[104:107], v[44:47], v[180:183], v[104:107]
	v_mfma_f32_16x16x32_bf16 v[100:103], v[52:55], v[180:183], v[100:103]
	v_mfma_f32_16x16x32_bf16 v[156:159], v[44:47], v[200:203], v[156:159]
	v_mfma_f32_16x16x32_bf16 v[148:151], v[52:55], v[200:203], v[148:151]
	v_mfma_f32_16x16x32_bf16 v[140:143], v[44:47], v[208:211], v[140:143]
	v_mfma_f32_16x16x32_bf16 v[132:135], v[52:55], v[208:211], v[132:135]
	v_mfma_f32_16x16x32_bf16 v[124:127], v[44:47], v[216:219], v[124:127]
	v_mfma_f32_16x16x32_bf16 v[120:123], v[52:55], v[216:219], v[120:123]
	s_setprio 0
	s_setprio 2
	v_mfma_f32_16x16x32_bf16 v[104:107], v[48:51], v[184:187], v[104:107]
	v_mfma_f32_16x16x32_bf16 v[100:103], v[56:59], v[184:187], v[100:103]
	v_mfma_f32_16x16x32_bf16 v[156:159], v[48:51], v[204:207], v[156:159]
	v_mfma_f32_16x16x32_bf16 v[148:151], v[56:59], v[204:207], v[148:151]
	v_mfma_f32_16x16x32_bf16 v[140:143], v[48:51], v[212:215], v[140:143]
	v_mfma_f32_16x16x32_bf16 v[132:135], v[56:59], v[212:215], v[132:135]
	v_mfma_f32_16x16x32_bf16 v[124:127], v[48:51], v[220:223], v[124:127]
	v_mfma_f32_16x16x32_bf16 v[120:123], v[56:59], v[220:223], v[120:123]
	s_setprio 0
	s_setprio 2
	v_mfma_f32_16x16x32_bf16 v[92:95], v[60:63], v[180:183], v[92:95]
	v_mfma_f32_16x16x32_bf16 v[88:91], v[72:75], v[180:183], v[88:91]
	v_mfma_f32_16x16x32_bf16 v[152:155], v[60:63], v[200:203], v[152:155]
	v_mfma_f32_16x16x32_bf16 v[144:147], v[72:75], v[200:203], v[144:147]
	v_mfma_f32_16x16x32_bf16 v[136:139], v[60:63], v[208:211], v[136:139]
	v_mfma_f32_16x16x32_bf16 v[128:131], v[72:75], v[208:211], v[128:131]
	v_mfma_f32_16x16x32_bf16 v[116:119], v[60:63], v[216:219], v[116:119]
	v_mfma_f32_16x16x32_bf16 v[112:115], v[72:75], v[216:219], v[112:115]
	s_setprio 0
	s_setprio 2
	v_mfma_f32_16x16x32_bf16 v[92:95], v[68:71], v[184:187], v[92:95]
	v_mfma_f32_16x16x32_bf16 v[88:91], v[76:79], v[184:187], v[88:91]
	v_mfma_f32_16x16x32_bf16 v[152:155], v[68:71], v[204:207], v[152:155]
	v_mfma_f32_16x16x32_bf16 v[144:147], v[76:79], v[204:207], v[144:147]
	v_mfma_f32_16x16x32_bf16 v[136:139], v[68:71], v[212:215], v[136:139]
	v_mfma_f32_16x16x32_bf16 v[128:131], v[76:79], v[212:215], v[128:131]
	v_mfma_f32_16x16x32_bf16 v[116:119], v[68:71], v[220:223], v[116:119]
	s_setprio 3
	s_barrier
	v_mfma_f32_16x16x32_bf16 v[112:115], v[76:79], v[220:223], v[112:115]
	s_setprio 0
	s_add_i32 s95, s87, s74
	v_lshl_add_u64 v[228:229], s[68:69], 0, v[162:163]
	s_mov_b32 m0, s95
	ds_read_b128 v[180:183], v198 offset:16384
	ds_read_b128 v[184:187], v198 offset:17408
	ds_read_b128 v[200:203], v198 offset:18432
	ds_read_b128 v[204:207], v198 offset:19456
	ds_read_b128 v[208:211], v198 offset:20480
	ds_read_b128 v[212:215], v198 offset:21504
	ds_read_b128 v[216:219], v198 offset:22528
	ds_read_b128 v[220:223], v198 offset:23552
	global_load_lds_dwordx4 v[228:229], off
	s_add_i32 m0, s95, 0x2000
	s_add_u32 s96, s68, 0x100000
	v_lshl_add_u64 v[230:231], s[68:69], 0, v[166:167]
	s_addc_u32 s97, s69, 0
	s_add_i32 s95, s90, s74
	global_load_lds_dwordx4 v[230:231], off
	v_lshl_add_u64 v[224:225], s[96:97], 0, v[162:163]
	s_mov_b32 m0, s95
	v_lshl_add_u64 v[232:233], s[70:71], 0, v[160:161]
	global_load_lds_dwordx4 v[224:225], off
	v_lshl_add_u64 v[224:225], s[96:97], 0, v[166:167]
	s_add_i32 m0, s95, 0x2000
	v_lshl_add_u64 v[234:235], s[70:71], 0, v[164:165]
	global_load_lds_dwordx4 v[224:225], off
	s_mov_b32 m0, s75
	s_nop 0
	global_load_lds_dwordx4 v[232:233], off
	s_mov_b32 m0, s76
	s_nop 0
	global_load_lds_dwordx4 v[234:235], off
	s_waitcnt vmcnt(8)
	s_waitcnt lgkmcnt(0)
	s_barrier
; #define PG8_STAGE(bufoff, gbase, voff) do { _Pragma("unroll") for (int _i = 0; _i < 2; ++_i) \
;         __builtin_amdgcn_global_load_lds((const unsigned*)((const char*)(gbase) + (voff)[_i]), (PG8_LAS unsigned*)(lds + (bufoff) + ldsw + _i * 8192), 16, 0, 0); } while (0)
; #define PG8_LDA(dst, b, h) do { _Pragma("unroll") for (int m = 0; m < 4; ++m) _Pragma("unroll") for (int k = 0; k < 2; ++k) dst[m][k] = *(const PG8_LAS bf16x8*)(lds + PG8_SA(b, h) + aoff + m * 2048 + k * 1024); } while (0)
; #define PG8_LDB(dst, b, h) do { _Pragma("unroll") for (int n = 0; n < 2; ++n) _Pragma("unroll") for (int k = 0; k < 2; ++k) dst[n][k] = *(const PG8_LAS bf16x8*)(lds + PG8_SB(b, h) + boff + n * 2048 + k * 1024); } while (0)
; #define PG8_MMA(ai, bj, At, Bt) do { __builtin_amdgcn_s_setprio(1); _Pragma("unroll") for (int m = 0; m < 4; ++m) _Pragma("unroll") for (int n = 0; n < 2; ++n) _Pragma("unroll") for (int k = 0; k < 2; ++k) \
;         acc[ai][bj][m][n] = __builtin_amdgcn_mfma_f32_16x16x32_bf16(Bt[n][k], At[m][k], acc[ai][bj][m][n], 0, 0, 0); __builtin_amdgcn_s_setprio(0); } while (0)
; #define PG8_WAIT_V(n) asm volatile("s_waitcnt vmcnt(" #n ")" ::: "memory")
; #define PG8_WAIT_L(n) asm volatile("s_waitcnt lgkmcnt(" #n ")" ::: "memory")
; #define PG8_BAR __builtin_amdgcn_s_barrier()
; #define PG8_SCHED __builtin_amdgcn_sched_barrier(0)
; template <class Epi, class Sched, bool ALIGN_EPI = false, bool SP2 = false>
; __device__ __forceinline__ void gemm_phase(PG8_LAS unsigned char* lds, const Gemm g, const Sched& S, const Epi& E, const int wv  ) {
;     ...
;             PG8_WAIT_V(8); PG8_WAIT_L(0); PG8_BAR; PG8_MMA(1, 0, At, B0); PG8_MMA(1, 1, At, B1); PG8_BAR; PG8_SCHED;
;             PG8_LDB(B0, 1, 0); PG8_LDB(B1, 1, 1); PG8_SCHED; PG8_LDA(At, 1, 0); PG8_STAGE(PG8_SA(0, 1), a2 + hstepA, voffA);
;             PG8_WAIT_V(8); PG8_WAIT_L(0); PG8_BAR; PG8_MMA(0, 0, At, B0); PG8_MMA(0, 1, At, B1); PG8_BAR; PG8_SCHED;
	s_setprio 2
	s_waitcnt lgkmcnt(0)
	v_mfma_f32_16x16x32_bf16 v[108:111], v[44:47], v[180:183], v[108:111]
	v_mfma_f32_16x16x32_bf16 v[96:99], v[52:55], v[180:183], v[96:99]
	v_mfma_f32_16x16x32_bf16 v[64:67], v[44:47], v[200:203], v[64:67]
	v_mfma_f32_16x16x32_bf16 v[36:39], v[52:55], v[200:203], v[36:39]
	v_mfma_f32_16x16x32_bf16 v[28:31], v[44:47], v[208:211], v[28:31]
	v_mfma_f32_16x16x32_bf16 v[20:23], v[52:55], v[208:211], v[20:23]
	v_mfma_f32_16x16x32_bf16 v[12:15], v[44:47], v[216:219], v[12:15]
	v_mfma_f32_16x16x32_bf16 v[4:7], v[52:55], v[216:219], v[4:7]
	s_setprio 0
	s_setprio 2
	v_mfma_f32_16x16x32_bf16 v[108:111], v[48:51], v[184:187], v[108:111]
	v_mfma_f32_16x16x32_bf16 v[96:99], v[56:59], v[184:187], v[96:99]
	v_mfma_f32_16x16x32_bf16 v[64:67], v[48:51], v[204:207], v[64:67]
	v_mfma_f32_16x16x32_bf16 v[36:39], v[56:59], v[204:207], v[36:39]
	v_mfma_f32_16x16x32_bf16 v[28:31], v[48:51], v[212:215], v[28:31]
	v_mfma_f32_16x16x32_bf16 v[20:23], v[56:59], v[212:215], v[20:23]
	v_mfma_f32_16x16x32_bf16 v[12:15], v[48:51], v[220:223], v[12:15]
	v_mfma_f32_16x16x32_bf16 v[4:7], v[56:59], v[220:223], v[4:7]
	s_setprio 0
	s_setprio 2
	v_mfma_f32_16x16x32_bf16 v[40:43], v[60:63], v[200:203], v[40:43]
	v_mfma_f32_16x16x32_bf16 v[32:35], v[72:75], v[200:203], v[32:35]
	v_mfma_f32_16x16x32_bf16 v[24:27], v[60:63], v[208:211], v[24:27]
	v_mfma_f32_16x16x32_bf16 v[16:19], v[72:75], v[208:211], v[16:19]
	v_mfma_f32_16x16x32_bf16 v[8:11], v[60:63], v[216:219], v[8:11]
	v_mfma_f32_16x16x32_bf16 v[0:3], v[72:75], v[216:219], v[0:3]
	v_mfma_f32_16x16x32_bf16 v[44:47], v[60:63], v[180:183], v[84:87]
	v_mfma_f32_16x16x32_bf16 v[48:51], v[72:75], v[180:183], v[80:83]
	s_setprio 0
	s_setprio 2
	v_mfma_f32_16x16x32_bf16 v[40:43], v[68:71], v[204:207], v[40:43]
	v_mfma_f32_16x16x32_bf16 v[32:35], v[76:79], v[204:207], v[32:35]
	v_mfma_f32_16x16x32_bf16 v[24:27], v[68:71], v[212:215], v[24:27]
	v_mfma_f32_16x16x32_bf16 v[16:19], v[76:79], v[212:215], v[16:19]
	v_mfma_f32_16x16x32_bf16 v[8:11], v[68:71], v[220:223], v[8:11]
	v_mfma_f32_16x16x32_bf16 v[0:3], v[76:79], v[220:223], v[0:3]
	v_mfma_f32_16x16x32_bf16 v[44:47], v[68:71], v[184:187], v[44:47]
	s_setprio 3
	s_barrier
	v_mfma_f32_16x16x32_bf16 v[48:51], v[76:79], v[184:187], v[48:51]
	s_setprio 0
	s_add_i32 s95, 0, 0x18000
	s_add_i32 s96, 0, 0x1c000
	v_add_u32_e32 v68, s95, v190
	v_add_u32_e32 v80, s96, v190
	ds_read_b128 v[52:55], v68
	ds_read_b128 v[56:59], v68 offset:1024
	ds_read_b128 v[60:63], v68 offset:2048
	ds_read_b128 v[68:71], v68 offset:3072
	ds_read_b128 v[72:75], v80
	ds_read_b128 v[76:79], v80 offset:1024
	ds_read_b128 v[180:183], v80 offset:2048
	ds_read_b128 v[184:187], v80 offset:3072
	s_add_u32 s70, s70, 0x100000
	s_addc_u32 s71, s71, 0
	s_mov_b32 m0, s77
	v_lshl_add_u64 v[224:225], s[70:71], 0, v[160:161]
	ds_read_b128 v[80:83], v198 offset:32768
	ds_read_b128 v[84:87], v198 offset:33792
	ds_read_b128 v[200:203], v198 offset:34816
	ds_read_b128 v[204:207], v198 offset:35840
	ds_read_b128 v[208:211], v198 offset:36864
	ds_read_b128 v[212:215], v198 offset:37888
	ds_read_b128 v[216:219], v198 offset:38912
	ds_read_b128 v[220:223], v198 offset:39936
	global_load_lds_dwordx4 v[224:225], off
	v_lshl_add_u64 v[224:225], s[70:71], 0, v[164:165]
	s_mov_b32 m0, s78
	s_nop 0
	global_load_lds_dwordx4 v[224:225], off
	s_waitcnt vmcnt(8)
	s_waitcnt lgkmcnt(0)
	s_barrier
	s_setprio 2
	s_waitcnt lgkmcnt(0)
	v_mfma_f32_16x16x32_bf16 v[104:107], v[52:55], v[80:83], v[104:107]
	v_mfma_f32_16x16x32_bf16 v[100:103], v[60:63], v[80:83], v[100:103]
	v_mfma_f32_16x16x32_bf16 v[156:159], v[52:55], v[200:203], v[156:159]
	v_mfma_f32_16x16x32_bf16 v[148:151], v[60:63], v[200:203], v[148:151]
	v_mfma_f32_16x16x32_bf16 v[140:143], v[52:55], v[208:211], v[140:143]
	v_mfma_f32_16x16x32_bf16 v[132:135], v[60:63], v[208:211], v[132:135]
	v_mfma_f32_16x16x32_bf16 v[124:127], v[52:55], v[216:219], v[124:127]
	v_mfma_f32_16x16x32_bf16 v[120:123], v[60:63], v[216:219], v[120:123]
	s_setprio 0
	s_setprio 2
	v_mfma_f32_16x16x32_bf16 v[104:107], v[56:59], v[84:87], v[104:107]
	v_mfma_f32_16x16x32_bf16 v[100:103], v[68:71], v[84:87], v[100:103]
	v_mfma_f32_16x16x32_bf16 v[156:159], v[56:59], v[204:207], v[156:159]
	v_mfma_f32_16x16x32_bf16 v[148:151], v[68:71], v[204:207], v[148:151]
	v_mfma_f32_16x16x32_bf16 v[140:143], v[56:59], v[212:215], v[140:143]
	v_mfma_f32_16x16x32_bf16 v[132:135], v[68:71], v[212:215], v[132:135]
	v_mfma_f32_16x16x32_bf16 v[124:127], v[56:59], v[220:223], v[124:127]
	v_mfma_f32_16x16x32_bf16 v[120:123], v[68:71], v[220:223], v[120:123]
	s_setprio 0
	s_setprio 2
	v_mfma_f32_16x16x32_bf16 v[92:95], v[72:75], v[80:83], v[92:95]
	v_mfma_f32_16x16x32_bf16 v[80:83], v[180:183], v[80:83], v[88:91]
	v_mfma_f32_16x16x32_bf16 v[88:91], v[184:187], v[84:87], v[80:83]
	v_mfma_f32_16x16x32_bf16 v[80:83], v[72:75], v[200:203], v[152:155]
	v_mfma_f32_16x16x32_bf16 v[152:155], v[76:79], v[204:207], v[80:83]
	v_mfma_f32_16x16x32_bf16 v[80:83], v[180:183], v[200:203], v[144:147]
	v_mfma_f32_16x16x32_bf16 v[144:147], v[184:187], v[204:207], v[80:83]
	v_mfma_f32_16x16x32_bf16 v[80:83], v[72:75], v[208:211], v[136:139]
	s_setprio 0
	s_setprio 2
	v_mfma_f32_16x16x32_bf16 v[136:139], v[76:79], v[212:215], v[80:83]
	v_mfma_f32_16x16x32_bf16 v[80:83], v[180:183], v[208:211], v[128:131]
	v_mfma_f32_16x16x32_bf16 v[128:131], v[184:187], v[212:215], v[80:83]
	v_mfma_f32_16x16x32_bf16 v[80:83], v[72:75], v[216:219], v[116:119]
	v_mfma_f32_16x16x32_bf16 v[116:119], v[76:79], v[220:223], v[80:83]
	v_mfma_f32_16x16x32_bf16 v[80:83], v[180:183], v[216:219], v[112:115]
	v_mfma_f32_16x16x32_bf16 v[92:95], v[76:79], v[84:87], v[92:95]
	s_setprio 3
	s_barrier
; #define PG8_STAGE(bufoff, gbase, voff) do { _Pragma("unroll") for (int _i = 0; _i < 2; ++_i) \
;         __builtin_amdgcn_global_load_lds((const unsigned*)((const char*)(gbase) + (voff)[_i]), (PG8_LAS unsigned*)(lds + (bufoff) + ldsw + _i * 8192), 16, 0, 0); } while (0)
; #define PG8_LDA(dst, b, h) do { _Pragma("unroll") for (int m = 0; m < 4; ++m) _Pragma("unroll") for (int k = 0; k < 2; ++k) dst[m][k] = *(const PG8_LAS bf16x8*)(lds + PG8_SA(b, h) + aoff + m * 2048 + k * 1024); } while (0)
; #define PG8_MMA(ai, bj, At, Bt) do { __builtin_amdgcn_s_setprio(1); _Pragma("unroll") for (int m = 0; m < 4; ++m) _Pragma("unroll") for (int n = 0; n < 2; ++n) _Pragma("unroll") for (int k = 0; k < 2; ++k) \
;         acc[ai][bj][m][n] = __builtin_amdgcn_mfma_f32_16x16x32_bf16(Bt[n][k], At[m][k], acc[ai][bj][m][n], 0, 0, 0); __builtin_amdgcn_s_setprio(0); } while (0)
; #define PG8_WAIT_V(n) asm volatile("s_waitcnt vmcnt(" #n ")" ::: "memory")
; #define PG8_WAIT_L(n) asm volatile("s_waitcnt lgkmcnt(" #n ")" ::: "memory")
; #define PG8_BAR __builtin_amdgcn_s_barrier()
; #define PG8_SCHED __builtin_amdgcn_sched_barrier(0)
; template <class Epi, class Sched, bool ALIGN_EPI = false, bool SP2 = false>
; __device__ __forceinline__ void gemm_phase(PG8_LAS unsigned char* lds, const Gemm g, const Sched& S, const Epi& E, const int wv  ) {
;     ...
;             PG8_LDA(At, 1, 1); PG8_STAGE(PG8_SB(1, 0), b3, voffB); PG8_STAGE(PG8_SB(1, 1), b3 + hstepB, voffB); PG8_STAGE(PG8_SA(1, 0), a3, voffA);
;             PG8_WAIT_V(8); PG8_WAIT_L(0); PG8_BAR; PG8_MMA(1, 0, At, B0); PG8_MMA(1, 1, At, B1); PG8_BAR; PG8_SCHED;
;     ...
;         if constexpr (ALIGN_EPI) { if (wr == 0) PG8_BAR; }
;         if constexpr (!Epi::AFTER_DRAIN) { E(acc, cur, wr, wc, fr, fq); S.done(cur); }
;         if (!has_next) break;
	v_mfma_f32_16x16x32_bf16 v[112:115], v[184:187], v[220:223], v[80:83]
	s_setprio 0
	s_add_i32 s70, s95, s74
	v_lshl_add_u64 v[84:85], v[228:229], 0, s[20:21]
	s_mov_b32 m0, s70
	s_nop 0
	ds_read_b128 v[80:83], v198 offset:49152
	ds_read_b128 v[200:203], v198 offset:50176
	ds_read_b128 v[204:207], v198 offset:51200
	ds_read_b128 v[208:211], v198 offset:52224
	ds_read_b128 v[212:215], v198 offset:53248
	ds_read_b128 v[216:219], v198 offset:54272
	ds_read_b128 v[220:223], v198 offset:55296
	ds_read_b128 v[224:227], v198 offset:56320
	global_load_lds_dwordx4 v[84:85], off
	s_add_i32 m0, s70, 0x2000
	s_add_u32 s68, s68, 0x100080
	v_lshl_add_u64 v[84:85], v[230:231], 0, s[20:21]
	s_addc_u32 s69, s69, 0
	s_add_i32 s70, s96, s74
	global_load_lds_dwordx4 v[84:85], off
	v_lshl_add_u64 v[84:85], s[68:69], 0, v[162:163]
	s_mov_b32 m0, s70
	s_nop 0
	global_load_lds_dwordx4 v[84:85], off
	v_lshl_add_u64 v[84:85], s[68:69], 0, v[166:167]
	s_add_i32 m0, s70, 0x2000
	s_nop 0
	global_load_lds_dwordx4 v[84:85], off
	v_lshl_add_u64 v[84:85], v[232:233], 0, s[20:21]
	s_mov_b32 m0, s82
	s_nop 0
	global_load_lds_dwordx4 v[84:85], off
	v_lshl_add_u64 v[84:85], v[234:235], 0, s[20:21]
	s_mov_b32 m0, s83
	s_nop 0
	global_load_lds_dwordx4 v[84:85], off
	s_waitcnt vmcnt(8)
	s_waitcnt lgkmcnt(0)
	s_barrier
	s_setprio 2
	s_waitcnt lgkmcnt(0)
	v_mfma_f32_16x16x32_bf16 v[84:87], v[52:55], v[80:83], v[108:111]
	v_mfma_f32_16x16x32_bf16 v[108:111], v[56:59], v[200:203], v[84:87]
	v_mfma_f32_16x16x32_bf16 v[84:87], v[60:63], v[80:83], v[96:99]
	v_mfma_f32_16x16x32_bf16 v[64:67], v[52:55], v[204:207], v[64:67]
	v_mfma_f32_16x16x32_bf16 v[36:39], v[60:63], v[204:207], v[36:39]
	v_mfma_f32_16x16x32_bf16 v[28:31], v[52:55], v[212:215], v[28:31]
	v_mfma_f32_16x16x32_bf16 v[20:23], v[60:63], v[212:215], v[20:23]
	v_mfma_f32_16x16x32_bf16 v[12:15], v[52:55], v[220:223], v[12:15]
	s_setprio 0
	s_setprio 2
	v_mfma_f32_16x16x32_bf16 v[4:7], v[60:63], v[220:223], v[4:7]
	v_mfma_f32_16x16x32_bf16 v[96:99], v[68:71], v[200:203], v[84:87]
	v_mfma_f32_16x16x32_bf16 v[64:67], v[56:59], v[208:211], v[64:67]
	v_mfma_f32_16x16x32_bf16 v[36:39], v[68:71], v[208:211], v[36:39]
	v_mfma_f32_16x16x32_bf16 v[28:31], v[56:59], v[216:219], v[28:31]
	v_mfma_f32_16x16x32_bf16 v[20:23], v[68:71], v[216:219], v[20:23]
	v_mfma_f32_16x16x32_bf16 v[12:15], v[56:59], v[224:227], v[12:15]
	v_mfma_f32_16x16x32_bf16 v[4:7], v[68:71], v[224:227], v[4:7]
	s_setprio 0
	s_setprio 2
	v_mfma_f32_16x16x32_bf16 v[44:47], v[72:75], v[80:83], v[44:47]
	v_mfma_f32_16x16x32_bf16 v[84:87], v[76:79], v[200:203], v[44:47]
	v_mfma_f32_16x16x32_bf16 v[44:47], v[180:183], v[80:83], v[48:51]
	v_mfma_f32_16x16x32_bf16 v[40:43], v[72:75], v[204:207], v[40:43]
	v_mfma_f32_16x16x32_bf16 v[32:35], v[180:183], v[204:207], v[32:35]
	v_mfma_f32_16x16x32_bf16 v[24:27], v[72:75], v[212:215], v[24:27]
	v_mfma_f32_16x16x32_bf16 v[16:19], v[180:183], v[212:215], v[16:19]
	v_mfma_f32_16x16x32_bf16 v[8:11], v[72:75], v[220:223], v[8:11]
	s_setprio 0
	s_setprio 2
	v_mfma_f32_16x16x32_bf16 v[0:3], v[180:183], v[220:223], v[0:3]
	v_mfma_f32_16x16x32_bf16 v[80:83], v[184:187], v[200:203], v[44:47]
	v_mfma_f32_16x16x32_bf16 v[40:43], v[76:79], v[208:211], v[40:43]
	v_mfma_f32_16x16x32_bf16 v[32:35], v[184:187], v[208:211], v[32:35]
	v_mfma_f32_16x16x32_bf16 v[24:27], v[76:79], v[216:219], v[24:27]
	v_mfma_f32_16x16x32_bf16 v[16:19], v[184:187], v[216:219], v[16:19]
	v_mfma_f32_16x16x32_bf16 v[8:11], v[76:79], v[224:227], v[8:11]
	s_setprio 3
	s_barrier
	v_mfma_f32_16x16x32_bf16 v[0:3], v[184:187], v[224:227], v[0:3]
	s_setprio 0
	s_add_i32 s94, s94, 2
	s_add_u32 s66, s66, 0x100
	s_addc_u32 s67, s67, 0
	s_add_u32 s92, s92, 0x100
	s_addc_u32 s93, s93, 0
	s_cmp_gt_u32 s94, 61
	s_cbranch_scc0 .LBB0_2399
	s_and_b64 vcc, exec, s[22:23]
	s_cbranch_vccz .LBB0_2402
	s_barrier

; #define PG8_STAGE(bufoff, gbase, voff) do { _Pragma("unroll") for (int _i = 0; _i < 2; ++_i) \
;         __builtin_amdgcn_global_load_lds((const unsigned*)((const char*)(gbase) + (voff)[_i]), (PG8_LAS unsigned*)(lds + (bufoff) + ldsw + _i * 8192), 16, 0, 0); } while (0)
; #define PG8_LDA(dst, b, h) do { _Pragma("unroll") for (int m = 0; m < 4; ++m) _Pragma("unroll") for (int k = 0; k < 2; ++k) dst[m][k] = *(const PG8_LAS bf16x8*)(lds + PG8_SA(b, h) + aoff + m * 2048 + k * 1024); } while (0)
; #define PG8_LDB(dst, b, h) do { _Pragma("unroll") for (int n = 0; n < 2; ++n) _Pragma("unroll") for (int k = 0; k < 2; ++k) dst[n][k] = *(const PG8_LAS bf16x8*)(lds + PG8_SB(b, h) + boff + n * 2048 + k * 1024); } while (0)
; #define PG8_MMA(ai, bj, At, Bt) do { __builtin_amdgcn_s_setprio(1); _Pragma("unroll") for (int m = 0; m < 4; ++m) _Pragma("unroll") for (int n = 0; n < 2; ++n) _Pragma("unroll") for (int k = 0; k < 2; ++k) \
;         acc[ai][bj][m][n] = __builtin_amdgcn_mfma_f32_16x16x32_bf16(Bt[n][k], At[m][k], acc[ai][bj][m][n], 0, 0, 0); __builtin_amdgcn_s_setprio(0); } while (0)
; #define PG8_WAIT_V(n) asm volatile("s_waitcnt vmcnt(" #n ")" ::: "memory")
; #define PG8_WAIT_L(n) asm volatile("s_waitcnt lgkmcnt(" #n ")" ::: "memory")
; #define PG8_BAR __builtin_amdgcn_s_barrier()
; template <class Epi, class Sched, bool ALIGN_EPI = false, bool SP2 = false>
; __device__ __forceinline__ void gemm_phase(PG8_LAS unsigned char* lds, const Gemm g, const Sched& S, const Epi& E, const int wv  ) {
;     ...
;         for (int t = 0; t < nt; t += 2) {
;             const bool last = (t == nt - 2);
;             const char* a1 = cA + (size_t)(t + 1) * kstep;
;             const char* a2 = last ? nA : cA + (size_t)(t + 2) * kstep; const char* b2 = last ? nB : cB + (size_t)(t + 2) * kstep;
;             const char* a3 = a2 + kstep; const char* b3 = b2 + kstep;
;             if (last && has_next) S.a_ready(nxt);
;             if constexpr (SP2) {
;             PG8_LDB(B0, 0, 0); PG8_LDB(B1, 0, 1); PG8_SCHED; PG8_LDA(At, 0, 0); PG8_STAGE(PG8_SA(1, 1), a1 + hstepA, voffA);
;             PG8_WAIT_V(8); PG8_WAIT_L(0); PG8_BAR; PG8_MMA(0, 0, At, B0); PG8_MMA(0, 1, At, B1); PG8_BAR; PG8_SCHED;
;             PG8_LDA(At, 0, 1); PG8_STAGE(PG8_SB(0, 0), b2, voffB); PG8_STAGE(PG8_SB(0, 1), b2 + hstepB, voffB); PG8_STAGE(PG8_SA(0, 0), a2, voffA);
.LBB0_2756:
	ds_read_b128 v[146:149], v152
	ds_read_b128 v[156:159], v152 offset:1024
	ds_read_b128 v[160:163], v152 offset:2048
	ds_read_b128 v[164:167], v152 offset:3072
	ds_read_b128 v[168:171], v153
	ds_read_b128 v[172:175], v153 offset:1024
	ds_read_b128 v[176:179], v153 offset:2048
	ds_read_b128 v[180:183], v153 offset:3072
	s_add_u32 s54, s52, 0x100
	s_addc_u32 s55, s53, 0
	s_cmpk_eq_i32 s84, 0xa8
	s_cselect_b32 s59, s7, s55
	s_cselect_b32 s58, s6, s54
	s_cselect_b32 s57, s51, s83
	s_cselect_b32 s56, s50, s82
	v_lshl_add_u64 v[216:217], s[52:53], 0, v[138:139]
	s_add_i32 m0, s63, 0xc000
	ds_read_b128 v[184:187], v154
	ds_read_b128 v[188:191], v154 offset:1024
	ds_read_b128 v[192:195], v154 offset:2048
	ds_read_b128 v[196:199], v154 offset:3072
	ds_read_b128 v[200:203], v154 offset:4096
	ds_read_b128 v[204:207], v154 offset:5120
	ds_read_b128 v[208:211], v154 offset:6144
	ds_read_b128 v[212:215], v154 offset:7168
	global_load_lds_dwordx4 v[216:217], off
	v_lshl_add_u64 v[216:217], s[52:53], 0, v[140:141]
	s_add_i32 m0, s63, 0xe000
	s_nop 0
	global_load_lds_dwordx4 v[216:217], off
	s_waitcnt vmcnt(8)
	s_waitcnt lgkmcnt(0)
	s_barrier
	s_setprio 2
	s_waitcnt lgkmcnt(0)
	v_mfma_f32_16x16x32_bf16 v[76:79], v[146:149], v[184:187], v[76:79]
	v_mfma_f32_16x16x32_bf16 v[72:75], v[160:163], v[184:187], v[72:75]
	v_mfma_f32_16x16x32_bf16 v[68:71], v[146:149], v[192:195], v[68:71]
	v_mfma_f32_16x16x32_bf16 v[64:67], v[160:163], v[192:195], v[64:67]
	v_mfma_f32_16x16x32_bf16 v[56:59], v[146:149], v[200:203], v[56:59]
	v_mfma_f32_16x16x32_bf16 v[52:55], v[160:163], v[200:203], v[52:55]
	v_mfma_f32_16x16x32_bf16 v[44:47], v[146:149], v[208:211], v[44:47]
	v_mfma_f32_16x16x32_bf16 v[40:43], v[160:163], v[208:211], v[40:43]
	s_setprio 0
	s_setprio 2
	v_mfma_f32_16x16x32_bf16 v[76:79], v[156:159], v[188:191], v[76:79]
	v_mfma_f32_16x16x32_bf16 v[72:75], v[164:167], v[188:191], v[72:75]
	v_mfma_f32_16x16x32_bf16 v[68:71], v[156:159], v[196:199], v[68:71]
	v_mfma_f32_16x16x32_bf16 v[64:67], v[164:167], v[196:199], v[64:67]
	v_mfma_f32_16x16x32_bf16 v[56:59], v[156:159], v[204:207], v[56:59]
	v_mfma_f32_16x16x32_bf16 v[52:55], v[164:167], v[204:207], v[52:55]
	v_mfma_f32_16x16x32_bf16 v[44:47], v[156:159], v[212:215], v[44:47]
	v_mfma_f32_16x16x32_bf16 v[40:43], v[164:167], v[212:215], v[40:43]
	s_setprio 0
	s_setprio 2
	v_mfma_f32_16x16x32_bf16 v[124:127], v[168:171], v[184:187], v[124:127]
	v_mfma_f32_16x16x32_bf16 v[120:123], v[176:179], v[184:187], v[120:123]
	v_mfma_f32_16x16x32_bf16 v[116:119], v[168:171], v[192:195], v[116:119]
	v_mfma_f32_16x16x32_bf16 v[112:115], v[176:179], v[192:195], v[112:115]
	v_mfma_f32_16x16x32_bf16 v[108:111], v[168:171], v[200:203], v[108:111]
	v_mfma_f32_16x16x32_bf16 v[104:107], v[176:179], v[200:203], v[104:107]
	v_mfma_f32_16x16x32_bf16 v[100:103], v[168:171], v[208:211], v[100:103]
	v_mfma_f32_16x16x32_bf16 v[96:99], v[176:179], v[208:211], v[96:99]
	s_setprio 0
	s_setprio 2
	v_mfma_f32_16x16x32_bf16 v[124:127], v[172:175], v[188:191], v[124:127]
	v_mfma_f32_16x16x32_bf16 v[120:123], v[180:183], v[188:191], v[120:123]
	v_mfma_f32_16x16x32_bf16 v[116:119], v[172:175], v[196:199], v[116:119]
	v_mfma_f32_16x16x32_bf16 v[112:115], v[180:183], v[196:199], v[112:115]
	v_mfma_f32_16x16x32_bf16 v[108:111], v[172:175], v[204:207], v[108:111]
	v_mfma_f32_16x16x32_bf16 v[104:107], v[180:183], v[204:207], v[104:107]
	v_mfma_f32_16x16x32_bf16 v[100:103], v[172:175], v[212:215], v[100:103]
	s_setprio 3
	s_barrier
	v_mfma_f32_16x16x32_bf16 v[96:99], v[180:183], v[212:215], v[96:99]
	s_setprio 0
	s_add_i32 s52, s72, s62
	v_lshl_add_u64 v[216:217], s[56:57], 0, v[130:131]
	s_mov_b32 m0, s52
	ds_read_b128 v[184:187], v154 offset:16384
	ds_read_b128 v[188:191], v154 offset:17408
	ds_read_b128 v[192:195], v154 offset:18432
	ds_read_b128 v[196:199], v154 offset:19456
	ds_read_b128 v[200:203], v154 offset:20480
	ds_read_b128 v[204:207], v154 offset:21504
	ds_read_b128 v[208:211], v154 offset:22528
	ds_read_b128 v[212:215], v154 offset:23552
	global_load_lds_dwordx4 v[216:217], off
	s_add_i32 m0, s52, 0x2000
	s_add_u32 s52, s56, 0x2b0000
	v_lshl_add_u64 v[218:219], s[56:57], 0, v[134:135]
	s_addc_u32 s53, s57, 0
	s_add_i32 s85, s73, s62
	global_load_lds_dwordx4 v[218:219], off
	v_lshl_add_u64 v[220:221], s[52:53], 0, v[130:131]
	s_mov_b32 m0, s85
	v_lshl_add_u64 v[222:223], s[58:59], 0, v[132:133]
	global_load_lds_dwordx4 v[220:221], off
	v_lshl_add_u64 v[220:221], s[52:53], 0, v[134:135]
	s_add_i32 m0, s85, 0x2000
	s_nop 0
	global_load_lds_dwordx4 v[220:221], off
	v_lshl_add_u64 v[220:221], s[58:59], 0, v[128:129]
	s_mov_b32 m0, s63
	s_nop 0
	global_load_lds_dwordx4 v[220:221], off
	s_mov_b32 m0, s64
	s_nop 0
	global_load_lds_dwordx4 v[222:223], off
	s_waitcnt vmcnt(8)
	s_waitcnt lgkmcnt(0)
	s_barrier
; #define PG8_STAGE(bufoff, gbase, voff) do { _Pragma("unroll") for (int _i = 0; _i < 2; ++_i) \
;         __builtin_amdgcn_global_load_lds((const unsigned*)((const char*)(gbase) + (voff)[_i]), (PG8_LAS unsigned*)(lds + (bufoff) + ldsw + _i * 8192), 16, 0, 0); } while (0)
; #define PG8_LDA(dst, b, h) do { _Pragma("unroll") for (int m = 0; m < 4; ++m) _Pragma("unroll") for (int k = 0; k < 2; ++k) dst[m][k] = *(const PG8_LAS bf16x8*)(lds + PG8_SA(b, h) + aoff + m * 2048 + k * 1024); } while (0)
; #define PG8_LDB(dst, b, h) do { _Pragma("unroll") for (int n = 0; n < 2; ++n) _Pragma("unroll") for (int k = 0; k < 2; ++k) dst[n][k] = *(const PG8_LAS bf16x8*)(lds + PG8_SB(b, h) + boff + n * 2048 + k * 1024); } while (0)
; #define PG8_MMA(ai, bj, At, Bt) do { __builtin_amdgcn_s_setprio(1); _Pragma("unroll") for (int m = 0; m < 4; ++m) _Pragma("unroll") for (int n = 0; n < 2; ++n) _Pragma("unroll") for (int k = 0; k < 2; ++k) \
;         acc[ai][bj][m][n] = __builtin_amdgcn_mfma_f32_16x16x32_bf16(Bt[n][k], At[m][k], acc[ai][bj][m][n], 0, 0, 0); __builtin_amdgcn_s_setprio(0); } while (0)
; #define PG8_WAIT_V(n) asm volatile("s_waitcnt vmcnt(" #n ")" ::: "memory")
; #define PG8_WAIT_L(n) asm volatile("s_waitcnt lgkmcnt(" #n ")" ::: "memory")
; #define PG8_BAR __builtin_amdgcn_s_barrier()
; #define PG8_SCHED __builtin_amdgcn_sched_barrier(0)
; template <class Epi, class Sched, bool ALIGN_EPI = false, bool SP2 = false>
; __device__ __forceinline__ void gemm_phase(PG8_LAS unsigned char* lds, const Gemm g, const Sched& S, const Epi& E, const int wv  ) {
;     ...
;             PG8_WAIT_V(8); PG8_WAIT_L(0); PG8_BAR; PG8_MMA(1, 0, At, B0); PG8_MMA(1, 1, At, B1); PG8_BAR; PG8_SCHED;
;             PG8_LDB(B0, 1, 0); PG8_LDB(B1, 1, 1); PG8_SCHED; PG8_LDA(At, 1, 0); PG8_STAGE(PG8_SA(0, 1), a2 + hstepA, voffA);
;             PG8_WAIT_V(8); PG8_WAIT_L(0); PG8_BAR; PG8_MMA(0, 0, At, B0); PG8_MMA(0, 1, At, B1); PG8_BAR; PG8_SCHED;
	s_setprio 2
	s_waitcnt lgkmcnt(0)
	v_mfma_f32_16x16x32_bf16 v[28:31], v[146:149], v[184:187], v[28:31]
	v_mfma_f32_16x16x32_bf16 v[24:27], v[160:163], v[184:187], v[24:27]
	v_mfma_f32_16x16x32_bf16 v[20:23], v[146:149], v[192:195], v[20:23]
	v_mfma_f32_16x16x32_bf16 v[16:19], v[160:163], v[192:195], v[16:19]
	v_mfma_f32_16x16x32_bf16 v[12:15], v[146:149], v[200:203], v[12:15]
	v_mfma_f32_16x16x32_bf16 v[8:11], v[160:163], v[200:203], v[8:11]
	v_mfma_f32_16x16x32_bf16 v[4:7], v[146:149], v[208:211], v[4:7]
	v_mfma_f32_16x16x32_bf16 v[0:3], v[160:163], v[208:211], v[0:3]
	s_setprio 0
	s_setprio 2
	v_mfma_f32_16x16x32_bf16 v[28:31], v[156:159], v[188:191], v[28:31]
	v_mfma_f32_16x16x32_bf16 v[24:27], v[164:167], v[188:191], v[24:27]
	v_mfma_f32_16x16x32_bf16 v[20:23], v[156:159], v[196:199], v[20:23]
	v_mfma_f32_16x16x32_bf16 v[16:19], v[164:167], v[196:199], v[16:19]
	v_mfma_f32_16x16x32_bf16 v[12:15], v[156:159], v[204:207], v[12:15]
	v_mfma_f32_16x16x32_bf16 v[8:11], v[164:167], v[204:207], v[8:11]
	v_mfma_f32_16x16x32_bf16 v[4:7], v[156:159], v[212:215], v[4:7]
	v_mfma_f32_16x16x32_bf16 v[0:3], v[164:167], v[212:215], v[0:3]
	s_setprio 0
	s_setprio 2
	v_mfma_f32_16x16x32_bf16 v[92:95], v[168:171], v[184:187], v[92:95]
	v_mfma_f32_16x16x32_bf16 v[88:91], v[176:179], v[184:187], v[88:91]
	v_mfma_f32_16x16x32_bf16 v[84:87], v[168:171], v[192:195], v[84:87]
	v_mfma_f32_16x16x32_bf16 v[80:83], v[176:179], v[192:195], v[80:83]
	v_mfma_f32_16x16x32_bf16 v[60:63], v[168:171], v[200:203], v[60:63]
	v_mfma_f32_16x16x32_bf16 v[48:51], v[176:179], v[200:203], v[48:51]
	v_mfma_f32_16x16x32_bf16 v[36:39], v[168:171], v[208:211], v[36:39]
	v_mfma_f32_16x16x32_bf16 v[32:35], v[176:179], v[208:211], v[32:35]
	s_setprio 0
	s_setprio 2
	v_mfma_f32_16x16x32_bf16 v[92:95], v[172:175], v[188:191], v[92:95]
	v_mfma_f32_16x16x32_bf16 v[88:91], v[180:183], v[188:191], v[88:91]
	v_mfma_f32_16x16x32_bf16 v[84:87], v[172:175], v[196:199], v[84:87]
	v_mfma_f32_16x16x32_bf16 v[80:83], v[180:183], v[196:199], v[80:83]
	v_mfma_f32_16x16x32_bf16 v[60:63], v[172:175], v[204:207], v[60:63]
	v_mfma_f32_16x16x32_bf16 v[48:51], v[180:183], v[204:207], v[48:51]
	v_mfma_f32_16x16x32_bf16 v[36:39], v[172:175], v[212:215], v[36:39]
	s_setprio 3
	s_barrier
	v_mfma_f32_16x16x32_bf16 v[32:35], v[180:183], v[212:215], v[32:35]
	s_setprio 0
	s_add_i32 s85, 0, 0x18000
	v_add_u32_e32 v155, s85, v150
	s_add_i32 s86, 0, 0x1c000
	ds_read_b128 v[146:149], v155
	ds_read_b128 v[156:159], v155 offset:1024
	ds_read_b128 v[160:163], v155 offset:2048
	ds_read_b128 v[164:167], v155 offset:3072
	v_add_u32_e32 v155, s86, v150
	ds_read_b128 v[168:171], v155
	ds_read_b128 v[172:175], v155 offset:1024
	ds_read_b128 v[176:179], v155 offset:2048
	ds_read_b128 v[180:183], v155 offset:3072
	s_add_u32 s52, s58, 0x2b0000
	s_addc_u32 s53, s59, 0
	s_mov_b32 m0, s65
	v_lshl_add_u64 v[224:225], s[52:53], 0, v[128:129]
	ds_read_b128 v[184:187], v154 offset:32768
	ds_read_b128 v[188:191], v154 offset:33792
	ds_read_b128 v[192:195], v154 offset:34816
	ds_read_b128 v[196:199], v154 offset:35840
	ds_read_b128 v[200:203], v154 offset:36864
	ds_read_b128 v[204:207], v154 offset:37888
	ds_read_b128 v[208:211], v154 offset:38912
	ds_read_b128 v[212:215], v154 offset:39936
	global_load_lds_dwordx4 v[224:225], off
	v_lshl_add_u64 v[224:225], s[52:53], 0, v[132:133]
	s_mov_b32 m0, s66
	s_nop 0
	global_load_lds_dwordx4 v[224:225], off
	s_waitcnt vmcnt(8)
	s_waitcnt lgkmcnt(0)
	s_barrier
	s_setprio 2
	s_waitcnt lgkmcnt(0)
	v_mfma_f32_16x16x32_bf16 v[76:79], v[146:149], v[184:187], v[76:79]
	v_mfma_f32_16x16x32_bf16 v[72:75], v[160:163], v[184:187], v[72:75]
	v_mfma_f32_16x16x32_bf16 v[68:71], v[146:149], v[192:195], v[68:71]
	v_mfma_f32_16x16x32_bf16 v[64:67], v[160:163], v[192:195], v[64:67]
	v_mfma_f32_16x16x32_bf16 v[56:59], v[146:149], v[200:203], v[56:59]
	v_mfma_f32_16x16x32_bf16 v[52:55], v[160:163], v[200:203], v[52:55]
	v_mfma_f32_16x16x32_bf16 v[44:47], v[146:149], v[208:211], v[44:47]
	v_mfma_f32_16x16x32_bf16 v[40:43], v[160:163], v[208:211], v[40:43]
	s_setprio 0
	s_setprio 2
	v_mfma_f32_16x16x32_bf16 v[76:79], v[156:159], v[188:191], v[76:79]
	v_mfma_f32_16x16x32_bf16 v[72:75], v[164:167], v[188:191], v[72:75]
	v_mfma_f32_16x16x32_bf16 v[68:71], v[156:159], v[196:199], v[68:71]
	v_mfma_f32_16x16x32_bf16 v[64:67], v[164:167], v[196:199], v[64:67]
	v_mfma_f32_16x16x32_bf16 v[56:59], v[156:159], v[204:207], v[56:59]
	v_mfma_f32_16x16x32_bf16 v[52:55], v[164:167], v[204:207], v[52:55]
	v_mfma_f32_16x16x32_bf16 v[44:47], v[156:159], v[212:215], v[44:47]
	v_mfma_f32_16x16x32_bf16 v[40:43], v[164:167], v[212:215], v[40:43]
	s_setprio 0
	s_setprio 2
	v_mfma_f32_16x16x32_bf16 v[124:127], v[168:171], v[184:187], v[124:127]
	v_mfma_f32_16x16x32_bf16 v[120:123], v[176:179], v[184:187], v[120:123]
	v_mfma_f32_16x16x32_bf16 v[116:119], v[168:171], v[192:195], v[116:119]
	v_mfma_f32_16x16x32_bf16 v[112:115], v[176:179], v[192:195], v[112:115]
	v_mfma_f32_16x16x32_bf16 v[108:111], v[168:171], v[200:203], v[108:111]
	v_mfma_f32_16x16x32_bf16 v[104:107], v[176:179], v[200:203], v[104:107]
	v_mfma_f32_16x16x32_bf16 v[100:103], v[168:171], v[208:211], v[100:103]
	v_mfma_f32_16x16x32_bf16 v[96:99], v[176:179], v[208:211], v[96:99]
	s_setprio 0
	s_setprio 2
	v_mfma_f32_16x16x32_bf16 v[124:127], v[172:175], v[188:191], v[124:127]
	v_mfma_f32_16x16x32_bf16 v[120:123], v[180:183], v[188:191], v[120:123]
	v_mfma_f32_16x16x32_bf16 v[116:119], v[172:175], v[196:199], v[116:119]
	v_mfma_f32_16x16x32_bf16 v[112:115], v[180:183], v[196:199], v[112:115]
	v_mfma_f32_16x16x32_bf16 v[108:111], v[172:175], v[204:207], v[108:111]
	v_mfma_f32_16x16x32_bf16 v[104:107], v[180:183], v[204:207], v[104:107]
	v_mfma_f32_16x16x32_bf16 v[100:103], v[172:175], v[212:215], v[100:103]
	s_setprio 3
	s_barrier
; #define PG8_STAGE(bufoff, gbase, voff) do { _Pragma("unroll") for (int _i = 0; _i < 2; ++_i) \
;         __builtin_amdgcn_global_load_lds((const unsigned*)((const char*)(gbase) + (voff)[_i]), (PG8_LAS unsigned*)(lds + (bufoff) + ldsw + _i * 8192), 16, 0, 0); } while (0)
; #define PG8_LDA(dst, b, h) do { _Pragma("unroll") for (int m = 0; m < 4; ++m) _Pragma("unroll") for (int k = 0; k < 2; ++k) dst[m][k] = *(const PG8_LAS bf16x8*)(lds + PG8_SA(b, h) + aoff + m * 2048 + k * 1024); } while (0)
; #define PG8_MMA(ai, bj, At, Bt) do { __builtin_amdgcn_s_setprio(1); _Pragma("unroll") for (int m = 0; m < 4; ++m) _Pragma("unroll") for (int n = 0; n < 2; ++n) _Pragma("unroll") for (int k = 0; k < 2; ++k) \
;         acc[ai][bj][m][n] = __builtin_amdgcn_mfma_f32_16x16x32_bf16(Bt[n][k], At[m][k], acc[ai][bj][m][n], 0, 0, 0); __builtin_amdgcn_s_setprio(0); } while (0)
; #define PG8_WAIT_V(n) asm volatile("s_waitcnt vmcnt(" #n ")" ::: "memory")
; #define PG8_WAIT_L(n) asm volatile("s_waitcnt lgkmcnt(" #n ")" ::: "memory")
; #define PG8_BAR __builtin_amdgcn_s_barrier()
; #define PG8_SCHED __builtin_amdgcn_sched_barrier(0)
; template <class Epi, class Sched, bool ALIGN_EPI = false, bool SP2 = false>
; __device__ __forceinline__ void gemm_phase(PG8_LAS unsigned char* lds, const Gemm g, const Sched& S, const Epi& E, const int wv  ) {
;     ...
;             PG8_LDA(At, 1, 1); PG8_STAGE(PG8_SB(1, 0), b3, voffB); PG8_STAGE(PG8_SB(1, 1), b3 + hstepB, voffB); PG8_STAGE(PG8_SA(1, 0), a3, voffA);
;             PG8_WAIT_V(8); PG8_WAIT_L(0); PG8_BAR; PG8_MMA(1, 0, At, B0); PG8_MMA(1, 1, At, B1); PG8_BAR; PG8_SCHED;
;     ...
;         if constexpr (ALIGN_EPI) { if (wr == 0) PG8_BAR; }
;         if constexpr (!Epi::AFTER_DRAIN) { E(acc, cur, wr, wc, fr, fq); S.done(cur); }
;         if (!has_next) break;
	v_mfma_f32_16x16x32_bf16 v[96:99], v[180:183], v[212:215], v[96:99]
	s_setprio 0
	s_add_i32 s52, s85, s62
	v_lshl_add_u64 v[216:217], v[216:217], 0, s[12:13]
	s_mov_b32 m0, s52
	ds_read_b128 v[184:187], v154 offset:49152
	ds_read_b128 v[188:191], v154 offset:50176
	ds_read_b128 v[192:195], v154 offset:51200
	ds_read_b128 v[196:199], v154 offset:52224
	ds_read_b128 v[200:203], v154 offset:53248
	ds_read_b128 v[204:207], v154 offset:54272
	ds_read_b128 v[208:211], v154 offset:55296
	ds_read_b128 v[212:215], v154 offset:56320
	global_load_lds_dwordx4 v[216:217], off
	s_add_i32 m0, s52, 0x2000
	s_add_u32 s52, s56, 0x2b0080
	v_lshl_add_u64 v[216:217], v[218:219], 0, s[12:13]
	s_addc_u32 s53, s57, 0
	s_add_i32 s56, s86, s62
	global_load_lds_dwordx4 v[216:217], off
	v_lshl_add_u64 v[216:217], s[52:53], 0, v[130:131]
	s_mov_b32 m0, s56
	s_nop 0
	global_load_lds_dwordx4 v[216:217], off
	v_lshl_add_u64 v[216:217], s[52:53], 0, v[134:135]
	s_add_i32 m0, s56, 0x2000
	s_nop 0
	global_load_lds_dwordx4 v[216:217], off
	v_lshl_add_u64 v[216:217], v[220:221], 0, s[12:13]
	s_mov_b32 m0, s69
	s_nop 0
	global_load_lds_dwordx4 v[216:217], off
	v_lshl_add_u64 v[216:217], v[222:223], 0, s[12:13]
	s_mov_b32 m0, s70
	s_nop 0
	global_load_lds_dwordx4 v[216:217], off
	s_waitcnt vmcnt(8)
	s_waitcnt lgkmcnt(0)
	s_barrier
	s_setprio 2
	s_waitcnt lgkmcnt(0)
	v_mfma_f32_16x16x32_bf16 v[28:31], v[146:149], v[184:187], v[28:31]
	v_mfma_f32_16x16x32_bf16 v[24:27], v[160:163], v[184:187], v[24:27]
	v_mfma_f32_16x16x32_bf16 v[20:23], v[146:149], v[192:195], v[20:23]
	v_mfma_f32_16x16x32_bf16 v[16:19], v[160:163], v[192:195], v[16:19]
	v_mfma_f32_16x16x32_bf16 v[12:15], v[146:149], v[200:203], v[12:15]
	v_mfma_f32_16x16x32_bf16 v[8:11], v[160:163], v[200:203], v[8:11]
	v_mfma_f32_16x16x32_bf16 v[4:7], v[146:149], v[208:211], v[4:7]
	v_mfma_f32_16x16x32_bf16 v[0:3], v[160:163], v[208:211], v[0:3]
	s_setprio 0
	s_setprio 2
	v_mfma_f32_16x16x32_bf16 v[28:31], v[156:159], v[188:191], v[28:31]
	v_mfma_f32_16x16x32_bf16 v[24:27], v[164:167], v[188:191], v[24:27]
	v_mfma_f32_16x16x32_bf16 v[20:23], v[156:159], v[196:199], v[20:23]
	v_mfma_f32_16x16x32_bf16 v[16:19], v[164:167], v[196:199], v[16:19]
	v_mfma_f32_16x16x32_bf16 v[12:15], v[156:159], v[204:207], v[12:15]
	v_mfma_f32_16x16x32_bf16 v[8:11], v[164:167], v[204:207], v[8:11]
	v_mfma_f32_16x16x32_bf16 v[4:7], v[156:159], v[212:215], v[4:7]
	v_mfma_f32_16x16x32_bf16 v[0:3], v[164:167], v[212:215], v[0:3]
	s_setprio 0
	s_setprio 2
	v_mfma_f32_16x16x32_bf16 v[92:95], v[168:171], v[184:187], v[92:95]
	v_mfma_f32_16x16x32_bf16 v[88:91], v[176:179], v[184:187], v[88:91]
	v_mfma_f32_16x16x32_bf16 v[84:87], v[168:171], v[192:195], v[84:87]
	v_mfma_f32_16x16x32_bf16 v[80:83], v[176:179], v[192:195], v[80:83]
	v_mfma_f32_16x16x32_bf16 v[60:63], v[168:171], v[200:203], v[60:63]
	v_mfma_f32_16x16x32_bf16 v[48:51], v[176:179], v[200:203], v[48:51]
	v_mfma_f32_16x16x32_bf16 v[36:39], v[168:171], v[208:211], v[36:39]
	v_mfma_f32_16x16x32_bf16 v[32:35], v[176:179], v[208:211], v[32:35]
	s_setprio 0
	s_setprio 2
	v_mfma_f32_16x16x32_bf16 v[92:95], v[172:175], v[188:191], v[92:95]
	v_mfma_f32_16x16x32_bf16 v[88:91], v[180:183], v[188:191], v[88:91]
	v_mfma_f32_16x16x32_bf16 v[84:87], v[172:175], v[196:199], v[84:87]
	v_mfma_f32_16x16x32_bf16 v[80:83], v[180:183], v[196:199], v[80:83]
	v_mfma_f32_16x16x32_bf16 v[60:63], v[172:175], v[204:207], v[60:63]
	v_mfma_f32_16x16x32_bf16 v[48:51], v[180:183], v[204:207], v[48:51]
	v_mfma_f32_16x16x32_bf16 v[36:39], v[172:175], v[212:215], v[36:39]
	s_setprio 3
	s_barrier
	v_mfma_f32_16x16x32_bf16 v[32:35], v[180:183], v[212:215], v[32:35]
	s_setprio 0
	s_add_i32 s84, s84, 2
	s_add_u32 s82, s82, 0x100
	s_addc_u32 s83, s83, 0
	s_cmpk_gt_u32 s84, 0xa9
	s_mov_b64 s[52:53], s[54:55]
	s_cbranch_scc0 .LBB0_2756
	s_and_b64 vcc, exec, s[14:15]
	s_cbranch_vccz .LBB0_2759
	s_barrier
